# v085 + P3a per-column parameters loaded once (no loads/vmcnt waits in the epilogues), P4 loop kept 8-byte aligned
# speedup vs baseline: 1.0105x; 1.0105x over previous
; __device__ __forceinline__ float bf_lo(unsigned u) { return __uint_as_float(u << 16); }
; __global__ void __launch_bounds__(NT, 2) mk_fwd(Args args) {
;     ...
;                 const int t0 = item * 64;
;                 bf16* Al = (bf16*)lds;
;                 bf16* Ks = (bf16*)(lds + 40960);
;                 const float* mu = args.in[11];
;                 {
;                     const int tl = tid >> 3, cb = (tid & 7) * 36; const int t = t0 + tl; const bool first = (t & (SEQ - 1)) == 0;
;                     const bf16* cur = P + (size_t)t * NINP + 2048 + 3072 + cb; const bf16* prv = cur - NINP;
; #pragma unroll 6
;                     for (int q = 0; q < 18; ++q) { const unsigned c2 = *(const unsigned*)(cur + 2 * q); const unsigned p2 = first ? 0u : *(const unsigned*)(prv + 2 * q);
;                         const int c = cb + 2 * q; const float m0 = mu[3072 + c], m1 = mu[3072 + c + 1];
;                         float v0 = bf_lo(c2), v1 = bf_hi(c2); v0 += (bf_lo(p2) - v0) * m0; v1 += (bf_hi(p2) - v1) * m1;
;                         if (c < 64) { v0 = tanh_fast(v0); v1 = tanh_fast(v1); } else if (c >= 128) { v0 = sigmoid1(v0); v1 = sigmoid1(v1); }
;                         *(unsigned*)(Al + tl * 296 + c) = pk2(v0, v1); }
;                 }
;                 const int c0 = wave * 128;
;                 const float* w0p = args.in[12]; const float* a0p = args.in[14]; const float* kkw = args.in[17]; const float* kaw = args.in[18];
;     ...
;                     for (int nt = 0; nt < 4; ++nt) { const int col = c0 + nt * 32 + (lane & 31); const float w0v = w0p[col];
; #pragma unroll
;                         for (int r = 0; r < 16; ++r) { const int t = t0 + mt * 32 + (r & 3) + 8 * (r >> 2) + 4 * (lane >> 5);
;                             const float sg = sigmoid1(w0v + acc[nt][r]);
;                             DEC[(size_t)t * 1024 + col] = __expf(-0.60653065971f * sg); }
;                         asm volatile("" ::: "memory"); }
;                     RW_ZERO(); RW_MM(A2T, 64, 64, 4);
; #pragma unroll
;                     for (int hh = 0; hh < 2; ++hh) {
;                         const int colA = c0 + hh * 64 + (lane & 31), colB = colA + 32;
;                         const float a0A = a0p[colA], a0B = a0p[colB], kkA = kkw[colA], kkB = kkw[colB], kaA = kaw[colA], kaB = kaw[colB];
.LBB0_300:
	s_cmp_lt_i32 s94, 4
	s_cselect_b64 s[6:7], -1, 0
	s_add_u32 s96, s92, 0x19a00000
	s_addc_u32 s97, s93, 0
	s_add_u32 s30, s92, 0x1ba00000
	s_addc_u32 s31, s93, 0
	s_add_u32 s34, s92, 0x1da00000
	s_addc_u32 s35, s93, 0
	s_add_u32 s24, s92, 0x1fa00000
	s_addc_u32 s25, s93, 0
	s_add_u32 s26, s90, 0x4000000
	s_addc_u32 s27, s91, 0
	s_add_u32 s28, s90, 0x6000000
	s_addc_u32 s29, s91, 0
	s_and_b64 s[40:41], s[6:7], s[0:1]
	s_cmpk_lt_i32 s2, 0x100
	s_cselect_b64 s[38:39], -1, 0
	s_and_b64 s[0:1], s[40:41], s[38:39]
	s_andn2_b64 vcc, exec, s[0:1]
	s_cbranch_vccnz .LBB0_389
	v_writelane_b32 v249, s68, 31
	s_lshl_b32 s3, s85, 7
	v_and_b32_e32 v129, 31, v168
	v_writelane_b32 v249, s69, 32
	v_or_b32_e32 v64, s3, v129
	v_lshrrev_b32_e32 v133, 3, v168
	v_lshrrev_b32_e32 v0, 1, v168
	v_ashrrev_i32_e32 v65, 31, v64
	v_readlane_b32 s4, v249, 8
	v_and_b32_e32 v5, 16, v0
	v_and_b32_e32 v131, 4, v133
	v_lshlrev_b64 v[0:1], 2, v[64:65]
	v_readlane_b32 s6, v249, 10
	v_readlane_b32 s7, v249, 11
	v_readlane_b32 s8, v249, 12
	v_readlane_b32 s9, v249, 13
	v_or_b32_e32 v72, 0x60, v64
	v_lshl_add_u64 v[74:75], s[60:61], 0, v[0:1]
	v_lshl_add_u64 v[76:77], s[90:91], 0, v[0:1]
	v_lshl_add_u64 v[78:79], s[64:65], 0, v[0:1]
	v_lshl_add_u64 v[80:81], s[6:7], 0, v[0:1]
	v_lshl_add_u64 v[82:83], s[8:9], 0, v[0:1]
	v_mul_u32_u24_e32 v1, 0x408, v131
	v_ashrrev_i32_e32 v73, 31, v72
	v_lshlrev_b32_e32 v0, 1, v64
	v_lshlrev_b32_e32 v1, 1, v1
	v_or_b32_e32 v70, 64, v64
	v_add3_u32 v171, 0, v0, v1
	v_lshlrev_b64 v[0:1], 7, v[72:73]
	v_ashrrev_i32_e32 v71, 31, v70
	v_or_b32_e32 v0, v0, v5
	v_or_b32_e32 v68, 32, v64
	v_lshl_add_u64 v[100:101], s[92:93], 0, v[0:1]
	v_lshlrev_b64 v[0:1], 7, v[70:71]
	v_ashrrev_i32_e32 v69, 31, v68
	v_or_b32_e32 v0, v0, v5
	v_lshl_add_u64 v[102:103], s[92:93], 0, v[0:1]
	v_lshlrev_b64 v[0:1], 7, v[68:69]
	s_mov_b64 s[0:1], 0x80
	v_or_b32_e32 v0, v0, v5
	v_lshl_add_u64 v[84:85], v[76:77], 0, s[0:1]
	s_mov_b64 s[0:1], 0x100
	v_lshl_add_u64 v[104:105], s[92:93], 0, v[0:1]
	v_lshlrev_b64 v[0:1], 7, v[64:65]
	v_lshl_add_u64 v[86:87], v[76:77], 0, s[0:1]
	s_mov_b64 s[0:1], 0x180
	v_or_b32_e32 v0, v0, v5
	s_movk_i32 s6, 0x140
	v_lshl_add_u64 v[88:89], v[76:77], 0, s[0:1]
	v_lshl_add_u64 v[106:107], s[92:93], 0, v[0:1]
	v_mad_i64_i32 v[0:1], s[0:1], v72, s6, 0
	v_or_b32_e32 v0, v0, v5
	v_lshl_add_u64 v[108:109], s[92:93], 0, v[0:1]
	v_mad_i64_i32 v[0:1], s[0:1], v70, s6, 0
	v_or_b32_e32 v0, v0, v5
	v_lshl_add_u64 v[110:111], s[92:93], 0, v[0:1]
	v_mad_i64_i32 v[0:1], s[0:1], v68, s6, 0
	v_and_b32_e32 v2, 7, v168
	v_or_b32_e32 v0, v0, v5
	v_mul_u32_u24_e32 v3, 36, v2
	v_lshl_add_u64 v[112:113], s[92:93], 0, v[0:1]
	v_mad_i64_i32 v[0:1], s[0:1], v64, s6, 0
	v_mul_u32_u24_e32 v4, 0x250, v133
	v_add_u32_e32 v170, 0, v5
	v_lshlrev_b32_e32 v96, 1, v3
	v_mov_b32_e32 v97, 0
	v_or_b32_e32 v0, v0, v5
	s_movk_i32 s46, 0x250
	v_lshrrev_b32_e32 v135, 2, v168
	v_lshl_add_u64 v[66:67], v[64:65], 1, s[26:27]
	v_or_b32_e32 v172, 1, v131
	v_add_u32_e32 v173, 0x810, v171
	v_or_b32_e32 v174, 2, v131
	v_add_u32_e32 v175, 0x1020, v171
	v_or_b32_e32 v176, 3, v131
	v_add_u32_e32 v177, 0x1830, v171
	v_or_b32_e32 v178, 8, v131
	v_add_u32_e32 v179, 0x4080, v171
	v_or_b32_e32 v180, 9, v131
	v_add_u32_e32 v181, 0x4890, v171
	v_or_b32_e32 v182, 10, v131
	v_add_u32_e32 v183, 0x50a0, v171
	v_or_b32_e32 v184, 11, v131
	v_add_u32_e32 v185, 0x58b0, v171
	v_or_b32_e32 v186, 16, v131
	v_add_u32_e32 v187, 0x8100, v171
	v_or_b32_e32 v188, 17, v131
	v_add_u32_e32 v189, 0x8910, v171
	v_or_b32_e32 v190, 18, v131
	v_add_u32_e32 v191, 0x9120, v171
	v_or_b32_e32 v192, 19, v131
	v_add_u32_e32 v193, 0x9930, v171
	v_or_b32_e32 v194, 24, v131
	v_add_u32_e32 v195, 0xc180, v171
	v_or_b32_e32 v196, 25, v131
	v_add_u32_e32 v197, 0xc990, v171
	v_or_b32_e32 v198, 26, v131
	v_add_u32_e32 v199, 0xd1a0, v171
	v_or_b32_e32 v200, 27, v131
	v_add_u32_e32 v201, 0xd9b0, v171
	v_lshl_add_u64 v[90:91], v[68:69], 1, s[26:27]
	v_lshl_add_u64 v[92:93], v[70:71], 1, s[26:27]
	v_lshl_add_u64 v[94:95], v[72:73], 1, s[26:27]
	v_lshl_add_u64 v[98:99], s[92:93], 0, v[96:97]
	v_mad_u32_u24 v202, v2, 36, 10
	v_add3_u32 v203, v4, v96, 0
	v_lshrrev_b32_e32 v204, 7, v168
	v_lshlrev_b32_e32 v205, 3, v168
	v_add_u32_e32 v206, 0x80, v170
	v_add_u32_e32 v207, 0x100, v170
	v_lshl_add_u64 v[114:115], s[92:93], 0, v[0:1]
	s_movk_i32 s47, 0x7ff
	s_movk_i32 s60, 0x7f
	s_movk_i32 s61, 0x2c00
	s_mov_b64 s[6:7], 0x1000
	s_movk_i32 s62, 0xfff
	s_movk_i32 s63, 0x2dff
	s_mov_b32 s64, 0x280000
	s_mov_b32 s65, 0x2a0000
	s_mov_b32 s66, 0x2c0000
	v_mbcnt_hi_u32_b32 v208, -1, v169
	s_mov_b32 s67, s2
	v_readlane_b32 s5, v249, 9
	v_readlane_b32 s10, v249, 14
	v_readlane_b32 s11, v249, 15
	v_readlane_b32 s12, v249, 16
	v_readlane_b32 s13, v249, 17
	v_readlane_b32 s14, v249, 18
	v_readlane_b32 s15, v249, 19
	v_readlane_b32 s16, v249, 20
	v_readlane_b32 s17, v249, 21
	v_readlane_b32 s18, v249, 22
	v_readlane_b32 s19, v249, 23
	global_load_dword v230, v[74:75], off
	global_load_dword v231, v[74:75], off offset:128
	global_load_dword v232, v[74:75], off offset:256
	global_load_dword v233, v[74:75], off offset:384
	global_load_dword v234, v[78:79], off
	global_load_dword v235, v[78:79], off offset:128
	global_load_dword v236, v[78:79], off offset:256
	global_load_dword v237, v[78:79], off offset:384
	global_load_dword v238, v[80:81], off
	global_load_dword v239, v[80:81], off offset:128
	global_load_dword v240, v[80:81], off offset:256
	global_load_dword v241, v[80:81], off offset:384
	global_load_dword v242, v[82:83], off
	global_load_dword v243, v[82:83], off offset:128
	global_load_dword v244, v[82:83], off offset:256
	global_load_dword v245, v[82:83], off offset:384
	s_waitcnt vmcnt(0)

; __device__ __forceinline__ float sigmoid1(float x) { return __builtin_amdgcn_rcpf(1.0f + __expf(-x)); }
; __global__ void __launch_bounds__(NT, 2) mk_fwd(Args args) {
;     ...
;                     for (int nt = 0; nt < 4; ++nt) { const int col = c0 + nt * 32 + (lane & 31); const float w0v = w0p[col];
; #pragma unroll
;                         for (int r = 0; r < 16; ++r) { const int t = t0 + mt * 32 + (r & 3) + 8 * (r >> 2) + 4 * (lane >> 5);
;                             const float sg = sigmoid1(w0v + acc[nt][r]);
;                             DEC[(size_t)t * 1024 + col] = __expf(-0.60653065971f * sg); }
.LBB0_366:
	v_lshl_add_u64 v[124:125], v[106:107], 0, s[8:9]
	v_add_co_u32_e32 v148, vcc, s64, v124
	v_lshl_add_u64 v[126:127], v[104:105], 0, s[8:9]
	s_nop 0
	v_addc_co_u32_e32 v149, vcc, 0, v125, vcc
	v_add_co_u32_e32 v152, vcc, s64, v126
	v_lshl_add_u64 v[136:137], v[102:103], 0, s[8:9]
	s_nop 0
	v_addc_co_u32_e32 v153, vcc, 0, v127, vcc
	v_add_co_u32_e32 v154, vcc, s64, v136
	v_lshl_add_u64 v[138:139], v[100:101], 0, s[8:9]
	s_nop 0
	v_addc_co_u32_e32 v155, vcc, 0, v137, vcc
	v_add_co_u32_e32 v156, vcc, s64, v138
	ds_read_b128 v[116:119], v96
	ds_read_b128 v[120:123], v96 offset:32
	v_addc_co_u32_e32 v157, vcc, 0, v139, vcc
	global_load_dwordx4 v[124:127], v[148:149], off
	global_load_dwordx4 v[136:139], v[152:153], off
	global_load_dwordx4 v[140:143], v[154:155], off
	global_load_dwordx4 v[144:147], v[156:157], off
	s_nop 0
	global_load_dwordx4 v[148:151], v[148:149], off offset:32
	s_add_u32 s8, s8, 64
	s_addc_u32 s9, s9, 0
	s_cmpk_eq_i32 s8, 0x80
	v_add_u32_e32 v96, 64, v96
	s_waitcnt vmcnt(4) lgkmcnt(1)
	v_mfma_f32_32x32x16_bf16 v[48:63], v[116:119], v[124:127], v[48:63]
	global_load_dwordx4 v[124:127], v[152:153], off offset:32
	s_waitcnt vmcnt(4)
	v_mfma_f32_32x32x16_bf16 v[32:47], v[116:119], v[136:139], v[32:47]
	global_load_dwordx4 v[136:139], v[154:155], off offset:32
	s_waitcnt vmcnt(4)
	v_mfma_f32_32x32x16_bf16 v[16:31], v[116:119], v[140:143], v[16:31]
	global_load_dwordx4 v[140:143], v[156:157], off offset:32
	s_waitcnt vmcnt(4)
	v_mfma_f32_32x32x16_bf16 v[0:15], v[116:119], v[144:147], v[0:15]
	s_waitcnt vmcnt(3) lgkmcnt(0)
	v_mfma_f32_32x32x16_bf16 v[48:63], v[120:123], v[148:151], v[48:63]
	s_waitcnt vmcnt(2)
	v_mfma_f32_32x32x16_bf16 v[32:47], v[120:123], v[124:127], v[32:47]
	s_waitcnt vmcnt(1)
	v_mfma_f32_32x32x16_bf16 v[16:31], v[120:123], v[136:139], v[16:31]
	s_waitcnt vmcnt(0)
	v_mfma_f32_32x32x16_bf16 v[0:15], v[120:123], v[140:143], v[0:15]
	s_cbranch_scc0 .LBB0_366
	v_mov_b32_e32 v148, v230
	v_or_b32_e32 v96, s69, v209
	v_lshlrev_b32_e32 v96, 10, v96
	v_mov_b32_e32 v127, v97
	v_mov_b32_e32 v117, v97
	v_mov_b32_e32 v119, v97
	v_mov_b32_e32 v121, v97
	v_mov_b32_e32 v123, v97
	v_mov_b32_e32 v125, v97
	v_or_b32_e32 v126, 0x400, v96
	v_or_b32_e32 v116, 0x800, v96
	v_or_b32_e32 v118, 0xc00, v96
	v_or_b32_e32 v120, 0x2000, v96
	v_or_b32_e32 v122, 0x2400, v96
	v_or_b32_e32 v124, 0x2800, v96
	v_lshl_add_u64 v[164:165], v[96:97], 2, v[76:77]
	v_lshlrev_b64 v[162:163], 2, v[126:127]
	v_lshlrev_b64 v[160:161], 2, v[116:117]
	v_lshlrev_b64 v[158:159], 2, v[118:119]
	v_lshlrev_b64 v[156:157], 2, v[120:121]
	v_lshlrev_b64 v[154:155], 2, v[122:123]
	v_lshlrev_b64 v[152:153], 2, v[124:125]
	v_lshl_add_u64 v[126:127], v[76:77], 0, v[162:163]
	v_lshl_add_u64 v[136:137], v[76:77], 0, v[160:161]
	v_lshl_add_u64 v[138:139], v[76:77], 0, v[158:159]
	v_lshl_add_u64 v[140:141], v[76:77], 0, v[156:157]
	v_lshl_add_u64 v[142:143], v[76:77], 0, v[154:155]
	v_lshl_add_u64 v[144:145], v[76:77], 0, v[152:153]
	v_or_b32_e32 v146, 0x6400, v96
	v_mov_b32_e32 v147, v97
	v_lshlrev_b64 v[166:167], 2, v[146:147]
	v_mov_b32_e32 v149, v97
	v_or_b32_e32 v150, 0x6c00, v96
	v_mov_b32_e32 v151, v97
	s_mov_b64 s[8:9], 0
	v_add_f32_e32 v48, v148, v48
	v_add_f32_e32 v49, v148, v49
	v_mul_f32_e32 v48, 0xbfb8aa3b, v48
	v_add_f32_e32 v50, v148, v50
	v_mul_f32_e32 v49, 0xbfb8aa3b, v49
	v_exp_f32_e32 v48, v48
	v_add_f32_e32 v51, v148, v51
	v_mul_f32_e32 v50, 0xbfb8aa3b, v50
	v_exp_f32_e32 v49, v49
	v_add_f32_e32 v52, v148, v52
	v_add_f32_e32 v53, v148, v53
	v_add_f32_e32 v54, v148, v54
	v_mul_f32_e32 v51, 0xbfb8aa3b, v51
	v_exp_f32_e32 v50, v50
	v_mul_f32_e32 v52, 0xbfb8aa3b, v52
	v_mul_f32_e32 v53, 0xbfb8aa3b, v53
	v_mul_f32_e32 v54, 0xbfb8aa3b, v54
	v_exp_f32_e32 v51, v51
	v_exp_f32_e32 v52, v52
	v_exp_f32_e32 v53, v53
	v_exp_f32_e32 v54, v54
	v_add_f32_e32 v48, 1.0, v48
	v_add_f32_e32 v49, 1.0, v49
	v_rcp_f32_e32 v48, v48
	v_add_f32_e32 v50, 1.0, v50
	v_rcp_f32_e32 v49, v49
	v_add_f32_e32 v55, v148, v55
	v_add_f32_e32 v51, 1.0, v51
	v_rcp_f32_e32 v50, v50
	v_mul_f32_e32 v55, 0xbfb8aa3b, v55
	v_add_f32_e32 v52, 1.0, v52
	v_add_f32_e32 v53, 1.0, v53
	v_add_f32_e32 v54, 1.0, v54
	v_rcp_f32_e32 v51, v51
	v_exp_f32_e32 v55, v55
	v_rcp_f32_e32 v52, v52
	v_rcp_f32_e32 v53, v53
	v_rcp_f32_e32 v54, v54
	v_mul_f32_e32 v48, 0xbf1b4598, v48
	v_mul_f32_e32 v49, 0xbf1b4598, v49
	v_mul_f32_e32 v48, 0x3fb8aa3b, v48
	v_mul_f32_e32 v50, 0xbf1b4598, v50
	v_mul_f32_e32 v49, 0x3fb8aa3b, v49
	v_exp_f32_e32 v48, v48
	v_mul_f32_e32 v51, 0xbf1b4598, v51
	v_mul_f32_e32 v50, 0x3fb8aa3b, v50
	v_exp_f32_e32 v49, v49
	v_add_f32_e32 v55, 1.0, v55
	v_mul_f32_e32 v52, 0xbf1b4598, v52
	v_mul_f32_e32 v53, 0xbf1b4598, v53
	v_mul_f32_e32 v54, 0xbf1b4598, v54
	v_mul_f32_e32 v51, 0x3fb8aa3b, v51
	v_exp_f32_e32 v50, v50
	v_rcp_f32_e32 v55, v55
	v_mul_f32_e32 v52, 0x3fb8aa3b, v52
	v_mul_f32_e32 v53, 0x3fb8aa3b, v53
	v_mul_f32_e32 v54, 0x3fb8aa3b, v54
	v_exp_f32_e32 v51, v51
	v_exp_f32_e32 v52, v52
	v_exp_f32_e32 v53, v53
	v_exp_f32_e32 v54, v54
	global_store_dword v[164:165], v48, off
	global_store_dword v[126:127], v49, off
	global_store_dword v[136:137], v50, off
	global_store_dword v[138:139], v51, off
	global_store_dword v[140:141], v52, off
	global_store_dword v[142:143], v53, off
	global_store_dword v[144:145], v54, off
	v_add_f32_e32 v48, v148, v56
	v_mul_f32_e32 v48, 0xbfb8aa3b, v48
	v_exp_f32_e32 v48, v48
	v_mul_f32_e32 v55, 0xbf1b4598, v55
	v_mul_f32_e32 v55, 0x3fb8aa3b, v55
	v_exp_f32_e32 v52, v55
	v_or_b32_e32 v126, 0x2c00, v96
	v_mov_b32_e32 v127, v97
	v_add_f32_e32 v48, 1.0, v48
	v_rcp_f32_e32 v53, v48
	v_lshlrev_b64 v[48:49], 2, v[126:127]
	v_lshl_add_u64 v[50:51], v[76:77], 0, v[48:49]
; __device__ __forceinline__ float sigmoid1(float x) { return __builtin_amdgcn_rcpf(1.0f + __expf(-x)); }
; __global__ void __launch_bounds__(NT, 2) mk_fwd(Args args) {
;     ...
;                     for (int nt = 0; nt < 4; ++nt) { const int col = c0 + nt * 32 + (lane & 31); const float w0v = w0p[col];
; #pragma unroll
;                         for (int r = 0; r < 16; ++r) { const int t = t0 + mt * 32 + (r & 3) + 8 * (r >> 2) + 4 * (lane >> 5);
;                             const float sg = sigmoid1(w0v + acc[nt][r]);
;                             DEC[(size_t)t * 1024 + col] = __expf(-0.60653065971f * sg); }
;                         asm volatile("" ::: "memory"); }
	global_store_dword v[50:51], v52, off
	v_add_f32_e32 v51, v148, v57
	v_mul_f32_e32 v51, 0xbfb8aa3b, v51
	v_exp_f32_e32 v51, v51
	v_mul_f32_e32 v50, 0xbf1b4598, v53
	v_mul_f32_e32 v50, 0x3fb8aa3b, v50
	v_exp_f32_e32 v54, v50
	v_or_b32_e32 v136, 0x4000, v96
	v_mov_b32_e32 v137, v97
	v_add_f32_e32 v50, 1.0, v51
	v_rcp_f32_e32 v55, v50
	v_lshlrev_b64 v[50:51], 2, v[136:137]
	v_lshl_add_u64 v[52:53], v[76:77], 0, v[50:51]
	global_store_dword v[52:53], v54, off
	v_add_f32_e32 v53, v148, v58
	v_mul_f32_e32 v53, 0xbfb8aa3b, v53
	v_exp_f32_e32 v53, v53
	v_mul_f32_e32 v52, 0xbf1b4598, v55
	v_mul_f32_e32 v52, 0x3fb8aa3b, v52
	v_exp_f32_e32 v56, v52
	v_or_b32_e32 v138, 0x4400, v96
	v_mov_b32_e32 v139, v97
	v_add_f32_e32 v52, 1.0, v53
	v_rcp_f32_e32 v57, v52
	v_lshlrev_b64 v[52:53], 2, v[138:139]
	v_lshl_add_u64 v[54:55], v[76:77], 0, v[52:53]
	global_store_dword v[54:55], v56, off
	v_add_f32_e32 v55, v148, v59
	v_mul_f32_e32 v55, 0xbfb8aa3b, v55
	v_exp_f32_e32 v55, v55
	v_mul_f32_e32 v54, 0xbf1b4598, v57
	v_mul_f32_e32 v54, 0x3fb8aa3b, v54
	v_exp_f32_e32 v58, v54
	v_or_b32_e32 v140, 0x4800, v96
	v_mov_b32_e32 v141, v97
	v_add_f32_e32 v54, 1.0, v55
	v_rcp_f32_e32 v59, v54
	v_lshlrev_b64 v[54:55], 2, v[140:141]
	v_lshl_add_u64 v[56:57], v[76:77], 0, v[54:55]
	global_store_dword v[56:57], v58, off
	v_add_f32_e32 v57, v148, v60
	v_mul_f32_e32 v57, 0xbfb8aa3b, v57
	v_exp_f32_e32 v57, v57
	v_mul_f32_e32 v56, 0xbf1b4598, v59
	v_mul_f32_e32 v56, 0x3fb8aa3b, v56
	v_exp_f32_e32 v60, v56
	v_or_b32_e32 v142, 0x4c00, v96
	v_mov_b32_e32 v143, v97
	v_add_f32_e32 v56, 1.0, v57
	v_rcp_f32_e32 v117, v56
	v_lshlrev_b64 v[56:57], 2, v[142:143]
	v_lshl_add_u64 v[58:59], v[76:77], 0, v[56:57]
	global_store_dword v[58:59], v60, off
	v_add_f32_e32 v59, v148, v61
	v_mul_f32_e32 v59, 0xbfb8aa3b, v59
	v_exp_f32_e32 v59, v59
	v_mul_f32_e32 v58, 0xbf1b4598, v117
	v_mul_f32_e32 v58, 0x3fb8aa3b, v58
	v_exp_f32_e32 v117, v58
	v_or_b32_e32 v144, 0x6000, v96
	v_mov_b32_e32 v145, v97
	v_add_f32_e32 v58, 1.0, v59
	v_rcp_f32_e32 v119, v58
	v_lshlrev_b64 v[58:59], 2, v[144:145]
	v_lshl_add_u64 v[60:61], v[76:77], 0, v[58:59]
	global_store_dword v[60:61], v117, off
	v_add_f32_e32 v61, v148, v62
	v_mul_f32_e32 v61, 0xbfb8aa3b, v61
	v_mul_f32_e32 v60, 0xbf1b4598, v119
	v_exp_f32_e32 v61, v61
	v_mul_f32_e32 v60, 0x3fb8aa3b, v60
	v_exp_f32_e32 v62, v60
	v_add_f32_e32 v60, 1.0, v61
	v_rcp_f32_e32 v117, v60
	v_lshl_add_u64 v[60:61], v[76:77], 0, v[166:167]
	global_store_dword v[60:61], v62, off
	v_add_f32_e32 v61, v148, v63
	v_mul_f32_e32 v61, 0xbfb8aa3b, v61
	v_exp_f32_e32 v61, v61
	v_mul_f32_e32 v60, 0xbf1b4598, v117
	v_mul_f32_e32 v60, 0x3fb8aa3b, v60
	v_exp_f32_e32 v117, v60
	v_add_f32_e32 v60, 1.0, v61
	v_rcp_f32_e32 v119, v60
	v_or_b32_e32 v148, 0x6800, v96
	v_lshlrev_b64 v[60:61], 2, v[148:149]
	v_lshl_add_u64 v[62:63], v[76:77], 0, v[60:61]
	global_store_dword v[62:63], v117, off
	v_mul_f32_e32 v62, 0xbf1b4598, v119
	v_mul_f32_e32 v62, 0x3fb8aa3b, v62
	v_exp_f32_e32 v117, v62
	v_lshlrev_b64 v[62:63], 2, v[150:151]
	v_lshl_add_u64 v[212:213], v[76:77], 0, v[62:63]
	global_store_dword v[212:213], v117, off
	v_mov_b32_e32 v117, v231
	v_add_f32_e32 v32, v117, v32
	v_mul_f32_e32 v32, 0xbfb8aa3b, v32
	v_exp_f32_e32 v32, v32
	v_add_f32_e32 v33, v117, v33
	v_mul_f32_e32 v33, 0xbfb8aa3b, v33
	v_exp_f32_e32 v33, v33
	v_add_f32_e32 v32, 1.0, v32
	v_rcp_f32_e32 v32, v32
	v_add_f32_e32 v35, v117, v35
	v_add_f32_e32 v33, 1.0, v33
	v_rcp_f32_e32 v33, v33
	v_mul_f32_e32 v32, 0xbf1b4598, v32
	v_mul_f32_e32 v32, 0x3fb8aa3b, v32
	v_exp_f32_e32 v32, v32
	v_mul_f32_e32 v35, 0xbfb8aa3b, v35
	v_exp_f32_e32 v35, v35
	global_store_dword v[164:165], v32, off offset:128
	v_mul_f32_e32 v32, 0xbf1b4598, v33
	v_add_f32_e32 v33, v117, v34
	v_mul_f32_e32 v33, 0xbfb8aa3b, v33
	v_exp_f32_e32 v34, v33
	v_mul_f32_e32 v32, 0x3fb8aa3b, v32
	v_exp_f32_e32 v119, v32
	v_lshl_add_u64 v[32:33], v[84:85], 0, v[162:163]
	v_add_f32_e32 v34, 1.0, v34
	v_rcp_f32_e32 v34, v34
	global_store_dword v[32:33], v119, off
	v_lshl_add_u64 v[32:33], v[84:85], 0, v[160:161]
	v_add_f32_e32 v35, 1.0, v35
	v_mul_f32_e32 v34, 0xbf1b4598, v34
	v_mul_f32_e32 v34, 0x3fb8aa3b, v34
	v_exp_f32_e32 v34, v34
	v_rcp_f32_e32 v35, v35
	global_store_dword v[32:33], v34, off
	v_add_f32_e32 v33, v117, v36
	v_mul_f32_e32 v33, 0xbfb8aa3b, v33
	v_exp_f32_e32 v34, v33
	v_mul_f32_e32 v32, 0xbf1b4598, v35
	v_mul_f32_e32 v32, 0x3fb8aa3b, v32
	v_exp_f32_e32 v35, v32
	v_add_f32_e32 v34, 1.0, v34
	v_rcp_f32_e32 v34, v34
	v_lshl_add_u64 v[32:33], v[84:85], 0, v[158:159]
	v_add_f32_e32 v36, v117, v37
	global_store_dword v[32:33], v35, off
	v_mul_f32_e32 v34, 0xbf1b4598, v34
	v_mul_f32_e32 v34, 0x3fb8aa3b, v34
	v_exp_f32_e32 v34, v34
	v_lshl_add_u64 v[32:33], v[84:85], 0, v[156:157]
	v_mul_f32_e32 v36, 0xbfb8aa3b, v36
	v_exp_f32_e32 v36, v36
	global_store_dword v[32:33], v34, off
	v_add_f32_e32 v33, v117, v38
	v_mul_f32_e32 v33, 0xbfb8aa3b, v33
	v_exp_f32_e32 v34, v33
	v_add_f32_e32 v36, 1.0, v36
	v_rcp_f32_e32 v36, v36
	v_add_f32_e32 v34, 1.0, v34
	v_rcp_f32_e32 v34, v34
	v_mul_f32_e32 v32, 0xbf1b4598, v36
	v_mul_f32_e32 v32, 0x3fb8aa3b, v32
	v_exp_f32_e32 v35, v32
	v_mul_f32_e32 v34, 0xbf1b4598, v34
	v_mul_f32_e32 v34, 0x3fb8aa3b, v34
	v_exp_f32_e32 v34, v34
	v_lshl_add_u64 v[32:33], v[84:85], 0, v[154:155]
	v_add_f32_e32 v36, v117, v39
	global_store_dword v[32:33], v35, off
	v_lshl_add_u64 v[32:33], v[84:85], 0, v[152:153]
	v_mul_f32_e32 v36, 0xbfb8aa3b, v36
	global_store_dword v[32:33], v34, off
	v_add_f32_e32 v33, v117, v40
	v_exp_f32_e32 v36, v36
	v_mul_f32_e32 v33, 0xbfb8aa3b, v33
	v_exp_f32_e32 v34, v33
	v_add_f32_e32 v36, 1.0, v36
	v_rcp_f32_e32 v36, v36
; __device__ __forceinline__ float sigmoid1(float x) { return __builtin_amdgcn_rcpf(1.0f + __expf(-x)); }
; __global__ void __launch_bounds__(NT, 2) mk_fwd(Args args) {
;     ...
;                     for (int nt = 0; nt < 4; ++nt) { const int col = c0 + nt * 32 + (lane & 31); const float w0v = w0p[col];
; #pragma unroll
;                         for (int r = 0; r < 16; ++r) { const int t = t0 + mt * 32 + (r & 3) + 8 * (r >> 2) + 4 * (lane >> 5);
;                             const float sg = sigmoid1(w0v + acc[nt][r]);
;                             DEC[(size_t)t * 1024 + col] = __expf(-0.60653065971f * sg); }
;                         asm volatile("" ::: "memory"); }
	v_add_f32_e32 v34, 1.0, v34
	v_rcp_f32_e32 v34, v34
	v_mul_f32_e32 v32, 0xbf1b4598, v36
	v_mul_f32_e32 v32, 0x3fb8aa3b, v32
	v_mul_f32_e32 v34, 0xbf1b4598, v34
	v_exp_f32_e32 v35, v32
	v_mul_f32_e32 v34, 0x3fb8aa3b, v34
	v_exp_f32_e32 v34, v34
	v_lshl_add_u64 v[32:33], v[84:85], 0, v[48:49]
	v_add_f32_e32 v36, v117, v41
	global_store_dword v[32:33], v35, off
	v_lshl_add_u64 v[32:33], v[84:85], 0, v[50:51]
	v_mul_f32_e32 v36, 0xbfb8aa3b, v36
	global_store_dword v[32:33], v34, off
	v_add_f32_e32 v33, v117, v42
	v_exp_f32_e32 v36, v36
	v_mul_f32_e32 v33, 0xbfb8aa3b, v33
	v_exp_f32_e32 v34, v33
	v_add_f32_e32 v36, 1.0, v36
	v_rcp_f32_e32 v36, v36
	v_add_f32_e32 v34, 1.0, v34
	v_rcp_f32_e32 v34, v34
	v_mul_f32_e32 v32, 0xbf1b4598, v36
	v_mul_f32_e32 v32, 0x3fb8aa3b, v32
	v_mul_f32_e32 v34, 0xbf1b4598, v34
	v_exp_f32_e32 v35, v32
	v_add_f32_e32 v36, v117, v43
	v_mul_f32_e32 v34, 0x3fb8aa3b, v34
	v_mul_f32_e32 v36, 0xbfb8aa3b, v36
	v_exp_f32_e32 v34, v34
	v_exp_f32_e32 v36, v36
	v_lshl_add_u64 v[32:33], v[84:85], 0, v[52:53]
	global_store_dword v[32:33], v35, off
	v_lshl_add_u64 v[32:33], v[84:85], 0, v[54:55]
	global_store_dword v[32:33], v34, off
	v_add_f32_e32 v33, v117, v44
	v_add_f32_e32 v36, 1.0, v36
	v_mul_f32_e32 v33, 0xbfb8aa3b, v33
	v_rcp_f32_e32 v36, v36
	v_exp_f32_e32 v34, v33
	v_mul_f32_e32 v32, 0xbf1b4598, v36
	v_add_f32_e32 v34, 1.0, v34
	v_add_f32_e32 v36, v117, v45
	v_rcp_f32_e32 v34, v34
	v_mul_f32_e32 v36, 0xbfb8aa3b, v36
	v_exp_f32_e32 v36, v36
	v_mul_f32_e32 v32, 0x3fb8aa3b, v32
	v_mul_f32_e32 v34, 0xbf1b4598, v34
	v_exp_f32_e32 v35, v32
	v_mul_f32_e32 v34, 0x3fb8aa3b, v34
	v_add_f32_e32 v36, 1.0, v36
	v_exp_f32_e32 v34, v34
	v_rcp_f32_e32 v36, v36
	v_lshl_add_u64 v[32:33], v[84:85], 0, v[56:57]
	global_store_dword v[32:33], v35, off
	v_lshl_add_u64 v[32:33], v[84:85], 0, v[58:59]
	v_add_f32_e32 v35, v117, v46
	global_store_dword v[32:33], v34, off
	v_mul_f32_e32 v32, 0xbf1b4598, v36
	v_mul_f32_e32 v35, 0xbfb8aa3b, v35
	v_add_f32_e32 v36, v117, v47
	v_mul_f32_e32 v32, 0x3fb8aa3b, v32
	v_exp_f32_e32 v35, v35
	v_mul_f32_e32 v36, 0xbfb8aa3b, v36
	v_exp_f32_e32 v34, v32
	v_exp_f32_e32 v36, v36
	v_lshl_add_u64 v[32:33], v[84:85], 0, v[166:167]
	v_add_f32_e32 v35, 1.0, v35
	v_rcp_f32_e32 v35, v35
	global_store_dword v[32:33], v34, off
	v_add_f32_e32 v32, 1.0, v36
	v_rcp_f32_e32 v32, v32
	v_mul_f32_e32 v33, 0xbf1b4598, v35
	v_mul_f32_e32 v33, 0x3fb8aa3b, v33
	v_exp_f32_e32 v34, v33
	v_mul_f32_e32 v32, 0xbf1b4598, v32
	v_mul_f32_e32 v32, 0x3fb8aa3b, v32
	v_exp_f32_e32 v35, v32
	v_lshl_add_u64 v[32:33], v[84:85], 0, v[60:61]
	global_store_dword v[32:33], v34, off
	v_lshl_add_u64 v[32:33], v[84:85], 0, v[62:63]
	global_store_dword v[32:33], v35, off
	v_mov_b32_e32 v32, v232
	v_add_u32_e32 v117, v206, v210
	v_add_f32_e32 v16, v32, v16
	v_mul_f32_e32 v16, 0xbfb8aa3b, v16
	v_exp_f32_e32 v16, v16
	v_add_f32_e32 v17, v32, v17
	v_mul_f32_e32 v17, 0xbfb8aa3b, v17
	v_exp_f32_e32 v17, v17
	v_add_f32_e32 v16, 1.0, v16
	v_rcp_f32_e32 v16, v16
	v_add_f32_e32 v19, v32, v19
	v_add_f32_e32 v17, 1.0, v17
	v_rcp_f32_e32 v17, v17
	v_mul_f32_e32 v16, 0xbf1b4598, v16
	v_mul_f32_e32 v16, 0x3fb8aa3b, v16
	v_exp_f32_e32 v16, v16
	v_mul_f32_e32 v19, 0xbfb8aa3b, v19
	v_exp_f32_e32 v19, v19
	global_store_dword v[164:165], v16, off offset:256
	v_mul_f32_e32 v16, 0xbf1b4598, v17
	v_add_f32_e32 v17, v32, v18
	v_mul_f32_e32 v17, 0xbfb8aa3b, v17
	v_exp_f32_e32 v18, v17
	v_mul_f32_e32 v16, 0x3fb8aa3b, v16
	v_exp_f32_e32 v33, v16
	v_lshl_add_u64 v[16:17], v[86:87], 0, v[162:163]
	v_add_f32_e32 v18, 1.0, v18
	v_rcp_f32_e32 v18, v18
	global_store_dword v[16:17], v33, off
	v_lshl_add_u64 v[16:17], v[86:87], 0, v[160:161]
	v_add_f32_e32 v19, 1.0, v19
	v_mul_f32_e32 v18, 0xbf1b4598, v18
	v_mul_f32_e32 v18, 0x3fb8aa3b, v18
	v_exp_f32_e32 v18, v18
	v_rcp_f32_e32 v19, v19
	global_store_dword v[16:17], v18, off
	v_add_f32_e32 v17, v32, v20
	v_mul_f32_e32 v17, 0xbfb8aa3b, v17
	v_exp_f32_e32 v18, v17
	v_mul_f32_e32 v16, 0xbf1b4598, v19
	v_mul_f32_e32 v16, 0x3fb8aa3b, v16
	v_exp_f32_e32 v19, v16
	v_add_f32_e32 v18, 1.0, v18
	v_rcp_f32_e32 v18, v18
	v_lshl_add_u64 v[16:17], v[86:87], 0, v[158:159]
	v_add_f32_e32 v20, v32, v21
	global_store_dword v[16:17], v19, off
	v_mul_f32_e32 v18, 0xbf1b4598, v18
	v_mul_f32_e32 v18, 0x3fb8aa3b, v18
	v_exp_f32_e32 v18, v18
	v_lshl_add_u64 v[16:17], v[86:87], 0, v[156:157]
	v_mul_f32_e32 v20, 0xbfb8aa3b, v20
	v_exp_f32_e32 v20, v20
	global_store_dword v[16:17], v18, off
	v_add_f32_e32 v17, v32, v22
	v_mul_f32_e32 v17, 0xbfb8aa3b, v17
	v_exp_f32_e32 v18, v17
	v_add_f32_e32 v20, 1.0, v20
	v_rcp_f32_e32 v20, v20
	v_add_f32_e32 v18, 1.0, v18
	v_rcp_f32_e32 v18, v18
	v_mul_f32_e32 v16, 0xbf1b4598, v20
	v_mul_f32_e32 v16, 0x3fb8aa3b, v16
	v_exp_f32_e32 v19, v16
	v_mul_f32_e32 v18, 0xbf1b4598, v18
	v_mul_f32_e32 v18, 0x3fb8aa3b, v18
	v_exp_f32_e32 v18, v18
	v_lshl_add_u64 v[16:17], v[86:87], 0, v[154:155]
	v_add_f32_e32 v20, v32, v23
	global_store_dword v[16:17], v19, off
	v_lshl_add_u64 v[16:17], v[86:87], 0, v[152:153]
	v_mul_f32_e32 v20, 0xbfb8aa3b, v20
	global_store_dword v[16:17], v18, off
	v_add_f32_e32 v17, v32, v24
	v_exp_f32_e32 v20, v20
	v_mul_f32_e32 v17, 0xbfb8aa3b, v17
	v_exp_f32_e32 v18, v17
	v_add_f32_e32 v20, 1.0, v20
	v_rcp_f32_e32 v20, v20
	v_add_f32_e32 v18, 1.0, v18
	v_rcp_f32_e32 v18, v18
	v_mul_f32_e32 v16, 0xbf1b4598, v20
	v_mul_f32_e32 v16, 0x3fb8aa3b, v16
	v_mul_f32_e32 v18, 0xbf1b4598, v18
	v_exp_f32_e32 v19, v16
	v_mul_f32_e32 v18, 0x3fb8aa3b, v18
	v_exp_f32_e32 v18, v18
	v_lshl_add_u64 v[16:17], v[86:87], 0, v[48:49]
	v_add_f32_e32 v20, v32, v25
	global_store_dword v[16:17], v19, off
	v_lshl_add_u64 v[16:17], v[86:87], 0, v[50:51]
; __device__ __forceinline__ float sigmoid1(float x) { return __builtin_amdgcn_rcpf(1.0f + __expf(-x)); }
; #define RW_ZERO() do { _Pragma("unroll") for (int b_ = 0; b_ < 4; ++b_) _Pragma("unroll") for (int r_ = 0; r_ < 16; ++r_) acc[b_][r_] = 0.f; } while (0)
; __global__ void __launch_bounds__(NT, 2) mk_fwd(Args args) {
;     ...
;                     for (int nt = 0; nt < 4; ++nt) { const int col = c0 + nt * 32 + (lane & 31); const float w0v = w0p[col];
; #pragma unroll
;                         for (int r = 0; r < 16; ++r) { const int t = t0 + mt * 32 + (r & 3) + 8 * (r >> 2) + 4 * (lane >> 5);
;                             const float sg = sigmoid1(w0v + acc[nt][r]);
;                             DEC[(size_t)t * 1024 + col] = __expf(-0.60653065971f * sg); }
;                         asm volatile("" ::: "memory"); }
;                     RW_ZERO(); RW_MM(A2T, 64, 64, 4);
	v_mul_f32_e32 v20, 0xbfb8aa3b, v20
	global_store_dword v[16:17], v18, off
	v_add_f32_e32 v17, v32, v26
	v_exp_f32_e32 v20, v20
	v_mul_f32_e32 v17, 0xbfb8aa3b, v17
	v_exp_f32_e32 v18, v17
	v_add_f32_e32 v20, 1.0, v20
	v_rcp_f32_e32 v20, v20
	v_add_f32_e32 v18, 1.0, v18
	v_rcp_f32_e32 v18, v18
	v_mul_f32_e32 v16, 0xbf1b4598, v20
	v_mul_f32_e32 v16, 0x3fb8aa3b, v16
	v_mul_f32_e32 v18, 0xbf1b4598, v18
	v_exp_f32_e32 v19, v16
	v_add_f32_e32 v20, v32, v27
	v_mul_f32_e32 v18, 0x3fb8aa3b, v18
	v_mul_f32_e32 v20, 0xbfb8aa3b, v20
	v_exp_f32_e32 v18, v18
	v_exp_f32_e32 v20, v20
	v_lshl_add_u64 v[16:17], v[86:87], 0, v[52:53]
	global_store_dword v[16:17], v19, off
	v_lshl_add_u64 v[16:17], v[86:87], 0, v[54:55]
	global_store_dword v[16:17], v18, off
	v_add_f32_e32 v17, v32, v28
	v_add_f32_e32 v20, 1.0, v20
	v_mul_f32_e32 v17, 0xbfb8aa3b, v17
	v_rcp_f32_e32 v20, v20
	v_exp_f32_e32 v18, v17
	v_mul_f32_e32 v16, 0xbf1b4598, v20
	v_add_f32_e32 v18, 1.0, v18
	v_add_f32_e32 v20, v32, v29
	v_rcp_f32_e32 v18, v18
	v_mul_f32_e32 v20, 0xbfb8aa3b, v20
	v_exp_f32_e32 v20, v20
	v_mul_f32_e32 v16, 0x3fb8aa3b, v16
	v_mul_f32_e32 v18, 0xbf1b4598, v18
	v_exp_f32_e32 v19, v16
	v_mul_f32_e32 v18, 0x3fb8aa3b, v18
	v_add_f32_e32 v20, 1.0, v20
	v_exp_f32_e32 v18, v18
	v_rcp_f32_e32 v20, v20
	v_lshl_add_u64 v[16:17], v[86:87], 0, v[56:57]
	global_store_dword v[16:17], v19, off
	v_lshl_add_u64 v[16:17], v[86:87], 0, v[58:59]
	v_add_f32_e32 v19, v32, v30
	global_store_dword v[16:17], v18, off
	v_mul_f32_e32 v16, 0xbf1b4598, v20
	v_mul_f32_e32 v19, 0xbfb8aa3b, v19
	v_add_f32_e32 v20, v32, v31
	v_mul_f32_e32 v16, 0x3fb8aa3b, v16
	v_exp_f32_e32 v19, v19
	v_mul_f32_e32 v20, 0xbfb8aa3b, v20
	v_exp_f32_e32 v18, v16
	v_exp_f32_e32 v20, v20
	v_lshl_add_u64 v[16:17], v[86:87], 0, v[166:167]
	v_add_f32_e32 v19, 1.0, v19
	v_rcp_f32_e32 v19, v19
	global_store_dword v[16:17], v18, off
	v_add_f32_e32 v16, 1.0, v20
	v_rcp_f32_e32 v16, v16
	v_mul_f32_e32 v17, 0xbf1b4598, v19
	v_mul_f32_e32 v17, 0x3fb8aa3b, v17
	v_exp_f32_e32 v18, v17
	v_mul_f32_e32 v16, 0xbf1b4598, v16
	v_mul_f32_e32 v16, 0x3fb8aa3b, v16
	v_exp_f32_e32 v19, v16
	v_lshl_add_u64 v[16:17], v[86:87], 0, v[60:61]
	global_store_dword v[16:17], v18, off
	v_lshl_add_u64 v[16:17], v[86:87], 0, v[62:63]
	global_store_dword v[16:17], v19, off
	v_mov_b32_e32 v16, v233
	v_add_f32_e32 v0, v16, v0
	v_mul_f32_e32 v0, 0xbfb8aa3b, v0
	v_exp_f32_e32 v0, v0
	v_add_f32_e32 v1, v16, v1
	v_mul_f32_e32 v1, 0xbfb8aa3b, v1
	v_exp_f32_e32 v1, v1
	v_add_f32_e32 v0, 1.0, v0
	v_rcp_f32_e32 v0, v0
	v_add_f32_e32 v3, v16, v3
	v_add_f32_e32 v1, 1.0, v1
	v_rcp_f32_e32 v1, v1
	v_mul_f32_e32 v0, 0xbf1b4598, v0
	v_mul_f32_e32 v0, 0x3fb8aa3b, v0
	v_exp_f32_e32 v0, v0
	v_mul_f32_e32 v3, 0xbfb8aa3b, v3
	v_exp_f32_e32 v3, v3
	global_store_dword v[164:165], v0, off offset:384
	v_mul_f32_e32 v0, 0xbf1b4598, v1
	v_add_f32_e32 v1, v16, v2
	v_mul_f32_e32 v1, 0xbfb8aa3b, v1
	v_exp_f32_e32 v2, v1
	v_mul_f32_e32 v0, 0x3fb8aa3b, v0
	v_exp_f32_e32 v17, v0
	v_lshl_add_u64 v[0:1], v[88:89], 0, v[162:163]
	v_add_f32_e32 v2, 1.0, v2
	v_rcp_f32_e32 v2, v2
	global_store_dword v[0:1], v17, off
	v_lshl_add_u64 v[0:1], v[88:89], 0, v[160:161]
	v_add_f32_e32 v3, 1.0, v3
	v_mul_f32_e32 v2, 0xbf1b4598, v2
	v_mul_f32_e32 v2, 0x3fb8aa3b, v2
	v_exp_f32_e32 v2, v2
	v_rcp_f32_e32 v3, v3
	global_store_dword v[0:1], v2, off
	v_add_f32_e32 v1, v16, v4
	v_mul_f32_e32 v1, 0xbfb8aa3b, v1
	v_exp_f32_e32 v2, v1
	v_mul_f32_e32 v0, 0xbf1b4598, v3
	v_mul_f32_e32 v0, 0x3fb8aa3b, v0
	v_exp_f32_e32 v3, v0
	v_add_f32_e32 v2, 1.0, v2
	v_rcp_f32_e32 v2, v2
	v_lshl_add_u64 v[0:1], v[88:89], 0, v[158:159]
	v_add_f32_e32 v4, v16, v5
	global_store_dword v[0:1], v3, off
	v_mul_f32_e32 v2, 0xbf1b4598, v2
	v_mul_f32_e32 v2, 0x3fb8aa3b, v2
	v_exp_f32_e32 v2, v2
	v_lshl_add_u64 v[0:1], v[88:89], 0, v[156:157]
	v_mul_f32_e32 v4, 0xbfb8aa3b, v4
	v_exp_f32_e32 v4, v4
	global_store_dword v[0:1], v2, off
	v_add_f32_e32 v1, v16, v6
	v_mul_f32_e32 v1, 0xbfb8aa3b, v1
	v_exp_f32_e32 v2, v1
	v_add_f32_e32 v4, 1.0, v4
	v_rcp_f32_e32 v4, v4
	v_add_f32_e32 v2, 1.0, v2
	v_rcp_f32_e32 v2, v2
	v_mul_f32_e32 v0, 0xbf1b4598, v4
	v_mul_f32_e32 v0, 0x3fb8aa3b, v0
	v_exp_f32_e32 v3, v0
	v_mul_f32_e32 v2, 0xbf1b4598, v2
	v_mul_f32_e32 v2, 0x3fb8aa3b, v2
	v_exp_f32_e32 v2, v2
	v_lshl_add_u64 v[0:1], v[88:89], 0, v[154:155]
	v_add_f32_e32 v4, v16, v7
	global_store_dword v[0:1], v3, off
	v_lshl_add_u64 v[0:1], v[88:89], 0, v[152:153]
	v_mul_f32_e32 v4, 0xbfb8aa3b, v4
	global_store_dword v[0:1], v2, off
	v_add_f32_e32 v1, v16, v8
	v_exp_f32_e32 v4, v4
	v_mul_f32_e32 v1, 0xbfb8aa3b, v1
	v_exp_f32_e32 v2, v1
	v_add_f32_e32 v4, 1.0, v4
	v_rcp_f32_e32 v4, v4
	v_add_f32_e32 v2, 1.0, v2
	v_rcp_f32_e32 v2, v2
	v_mul_f32_e32 v0, 0xbf1b4598, v4
	v_mul_f32_e32 v0, 0x3fb8aa3b, v0
	v_mul_f32_e32 v2, 0xbf1b4598, v2
	v_exp_f32_e32 v3, v0
	v_mul_f32_e32 v2, 0x3fb8aa3b, v2
	v_exp_f32_e32 v2, v2
	v_lshl_add_u64 v[0:1], v[88:89], 0, v[48:49]
	v_add_f32_e32 v4, v16, v9
	global_store_dword v[0:1], v3, off
	v_lshl_add_u64 v[0:1], v[88:89], 0, v[50:51]
	v_mul_f32_e32 v4, 0xbfb8aa3b, v4
	global_store_dword v[0:1], v2, off
	v_add_f32_e32 v1, v16, v10
	v_exp_f32_e32 v4, v4
	v_mul_f32_e32 v1, 0xbfb8aa3b, v1
	v_exp_f32_e32 v2, v1
	v_mov_b32_e32 v48, 0
	v_add_f32_e32 v4, 1.0, v4
	v_rcp_f32_e32 v4, v4
	v_add_f32_e32 v2, 1.0, v2
	v_rcp_f32_e32 v2, v2
	v_mov_b32_e32 v49, v48
	v_mul_f32_e32 v0, 0xbf1b4598, v4
	v_mul_f32_e32 v0, 0x3fb8aa3b, v0
	v_mul_f32_e32 v2, 0xbf1b4598, v2
	v_exp_f32_e32 v3, v0
	v_add_f32_e32 v4, v16, v11
	v_mul_f32_e32 v2, 0x3fb8aa3b, v2
	v_mul_f32_e32 v4, 0xbfb8aa3b, v4
	v_exp_f32_e32 v2, v2
	v_exp_f32_e32 v4, v4
	v_lshl_add_u64 v[0:1], v[88:89], 0, v[52:53]
; __device__ __forceinline__ float sigmoid1(float x) { return __builtin_amdgcn_rcpf(1.0f + __expf(-x)); }
; #define RW_ZERO() do { _Pragma("unroll") for (int b_ = 0; b_ < 4; ++b_) _Pragma("unroll") for (int r_ = 0; r_ < 16; ++r_) acc[b_][r_] = 0.f; } while (0)
; __global__ void __launch_bounds__(NT, 2) mk_fwd(Args args) {
;     ...
;                     for (int nt = 0; nt < 4; ++nt) { const int col = c0 + nt * 32 + (lane & 31); const float w0v = w0p[col];
; #pragma unroll
;                         for (int r = 0; r < 16; ++r) { const int t = t0 + mt * 32 + (r & 3) + 8 * (r >> 2) + 4 * (lane >> 5);
;                             const float sg = sigmoid1(w0v + acc[nt][r]);
;                             DEC[(size_t)t * 1024 + col] = __expf(-0.60653065971f * sg); }
;                         asm volatile("" ::: "memory"); }
;                     RW_ZERO(); RW_MM(A2T, 64, 64, 4);
	global_store_dword v[0:1], v3, off
	v_lshl_add_u64 v[0:1], v[88:89], 0, v[54:55]
	global_store_dword v[0:1], v2, off
	v_add_f32_e32 v1, v16, v12
	v_add_f32_e32 v4, 1.0, v4
	v_mul_f32_e32 v1, 0xbfb8aa3b, v1
	v_rcp_f32_e32 v4, v4
	v_exp_f32_e32 v2, v1
	v_mov_b32_e32 v50, v48
	v_mov_b32_e32 v51, v48
	v_mul_f32_e32 v0, 0xbf1b4598, v4
	v_add_f32_e32 v2, 1.0, v2
	v_add_f32_e32 v4, v16, v13
	v_rcp_f32_e32 v2, v2
	v_mul_f32_e32 v4, 0xbfb8aa3b, v4
	v_exp_f32_e32 v4, v4
	v_mul_f32_e32 v0, 0x3fb8aa3b, v0
	v_mul_f32_e32 v2, 0xbf1b4598, v2
	v_exp_f32_e32 v3, v0
	v_mul_f32_e32 v2, 0x3fb8aa3b, v2
	v_add_f32_e32 v4, 1.0, v4
	v_exp_f32_e32 v2, v2
	v_rcp_f32_e32 v4, v4
	v_lshl_add_u64 v[0:1], v[88:89], 0, v[56:57]
	global_store_dword v[0:1], v3, off
	v_lshl_add_u64 v[0:1], v[88:89], 0, v[58:59]
	v_add_f32_e32 v3, v16, v14
	global_store_dword v[0:1], v2, off
	v_mul_f32_e32 v0, 0xbf1b4598, v4
	v_mul_f32_e32 v3, 0xbfb8aa3b, v3
	v_add_f32_e32 v4, v16, v15
	v_mul_f32_e32 v0, 0x3fb8aa3b, v0
	v_exp_f32_e32 v3, v3
	v_mul_f32_e32 v4, 0xbfb8aa3b, v4
	v_exp_f32_e32 v2, v0
	v_exp_f32_e32 v4, v4
	v_lshl_add_u64 v[0:1], v[88:89], 0, v[166:167]
	v_add_f32_e32 v3, 1.0, v3
	v_rcp_f32_e32 v3, v3
	global_store_dword v[0:1], v2, off
	v_add_f32_e32 v0, 1.0, v4
	v_rcp_f32_e32 v0, v0
	v_mul_f32_e32 v1, 0xbf1b4598, v3
	v_mul_f32_e32 v1, 0x3fb8aa3b, v1
	v_exp_f32_e32 v2, v1
	v_mul_f32_e32 v0, 0xbf1b4598, v0
	v_mul_f32_e32 v0, 0x3fb8aa3b, v0
	v_exp_f32_e32 v3, v0
	v_lshl_add_u64 v[0:1], v[88:89], 0, v[60:61]
	global_store_dword v[0:1], v2, off
	v_lshl_add_u64 v[0:1], v[88:89], 0, v[62:63]
	global_store_dword v[0:1], v3, off
	v_mov_b32_e32 v52, v48
	v_mov_b32_e32 v53, v48
	v_mov_b32_e32 v54, v48
	v_mov_b32_e32 v55, v48
	v_mov_b32_e32 v56, v48
	v_mov_b32_e32 v57, v48
	v_mov_b32_e32 v58, v48
	v_mov_b32_e32 v59, v48
	v_mov_b32_e32 v60, v48
	v_mov_b32_e32 v61, v48
	v_mov_b32_e32 v62, v48
	v_mov_b32_e32 v63, v48
	v_mov_b32_e32 v32, v48
	v_mov_b32_e32 v33, v48
	v_mov_b32_e32 v34, v48
	v_mov_b32_e32 v35, v48
	v_mov_b32_e32 v36, v48
	v_mov_b32_e32 v37, v48
	v_mov_b32_e32 v38, v48
	v_mov_b32_e32 v39, v48
	v_mov_b32_e32 v40, v48
	v_mov_b32_e32 v41, v48
	v_mov_b32_e32 v42, v48
	v_mov_b32_e32 v43, v48
	v_mov_b32_e32 v44, v48
	v_mov_b32_e32 v45, v48
	v_mov_b32_e32 v46, v48
	v_mov_b32_e32 v47, v48
	v_mov_b32_e32 v16, v48
	v_mov_b32_e32 v17, v48
	v_mov_b32_e32 v18, v48
	v_mov_b32_e32 v19, v48
	v_mov_b32_e32 v20, v48
	v_mov_b32_e32 v21, v48
	v_mov_b32_e32 v22, v48
	v_mov_b32_e32 v23, v48
	v_mov_b32_e32 v24, v48
	v_mov_b32_e32 v25, v48
	v_mov_b32_e32 v26, v48
	v_mov_b32_e32 v27, v48
	v_mov_b32_e32 v28, v48
	v_mov_b32_e32 v29, v48
	v_mov_b32_e32 v30, v48
	v_mov_b32_e32 v31, v48
	v_mov_b32_e32 v0, v48
	v_mov_b32_e32 v1, v48
	v_mov_b32_e32 v2, v48
	v_mov_b32_e32 v3, v48
	v_mov_b32_e32 v4, v48
	v_mov_b32_e32 v5, v48
	v_mov_b32_e32 v6, v48
	v_mov_b32_e32 v7, v48
	v_mov_b32_e32 v8, v48
	v_mov_b32_e32 v9, v48
	v_mov_b32_e32 v10, v48
	v_mov_b32_e32 v11, v48
	v_mov_b32_e32 v12, v48
	v_mov_b32_e32 v13, v48
	v_mov_b32_e32 v14, v48
	v_mov_b32_e32 v15, v48
.LBB0_368:
	v_lshl_add_u64 v[160:161], v[106:107], 0, s[8:9]
	v_add_co_u32_e32 v220, vcc, s65, v160
	v_lshl_add_u64 v[162:163], v[104:105], 0, s[8:9]
	s_nop 0
	v_addc_co_u32_e32 v221, vcc, 0, v161, vcc
	v_add_co_u32_e32 v224, vcc, s65, v162
	v_lshl_add_u64 v[164:165], v[102:103], 0, s[8:9]
	s_nop 0
	v_addc_co_u32_e32 v225, vcc, 0, v163, vcc
	v_add_co_u32_e32 v226, vcc, s65, v164
	v_lshl_add_u64 v[166:167], v[100:101], 0, s[8:9]
	s_nop 0
	v_addc_co_u32_e32 v227, vcc, 0, v165, vcc
	v_add_co_u32_e32 v228, vcc, s65, v166
	ds_read_b128 v[152:155], v117
	ds_read_b128 v[156:159], v117 offset:32
	v_addc_co_u32_e32 v229, vcc, 0, v167, vcc
	global_load_dwordx4 v[160:163], v[220:221], off
	global_load_dwordx4 v[164:167], v[224:225], off
	global_load_dwordx4 v[212:215], v[226:227], off
	global_load_dwordx4 v[216:219], v[228:229], off
	s_nop 0
	global_load_dwordx4 v[220:223], v[220:221], off offset:32
	s_add_u32 s8, s8, 64
	s_addc_u32 s9, s9, 0
	s_cmpk_eq_i32 s8, 0x80
	v_add_u32_e32 v117, 64, v117
	s_waitcnt vmcnt(4) lgkmcnt(1)
	v_mfma_f32_32x32x16_bf16 v[48:63], v[152:155], v[160:163], v[48:63]
	global_load_dwordx4 v[160:163], v[224:225], off offset:32
	s_waitcnt vmcnt(4)
	v_mfma_f32_32x32x16_bf16 v[32:47], v[152:155], v[164:167], v[32:47]
	global_load_dwordx4 v[164:167], v[226:227], off offset:32
	s_waitcnt vmcnt(4)
	v_mfma_f32_32x32x16_bf16 v[16:31], v[152:155], v[212:215], v[16:31]
	global_load_dwordx4 v[212:215], v[228:229], off offset:32
	s_waitcnt vmcnt(4)
	v_mfma_f32_32x32x16_bf16 v[0:15], v[152:155], v[216:219], v[0:15]
	s_waitcnt vmcnt(3) lgkmcnt(0)
	v_mfma_f32_32x32x16_bf16 v[48:63], v[156:159], v[220:223], v[48:63]
	s_waitcnt vmcnt(2)
	v_mfma_f32_32x32x16_bf16 v[32:47], v[156:159], v[160:163], v[32:47]
	s_waitcnt vmcnt(1)
	v_mfma_f32_32x32x16_bf16 v[16:31], v[156:159], v[164:167], v[16:31]
	s_waitcnt vmcnt(0)
	v_mfma_f32_32x32x16_bf16 v[0:15], v[156:159], v[212:215], v[0:15]
	s_cbranch_scc0 .LBB0_368
; __device__ __forceinline__ float bf1(bf16 h) { return __uint_as_float((unsigned)h << 16); }
; __device__ __forceinline__ bf16 f2bf(float f) { return (bf16)(pg8::cvt_pk_bf16(f, 0.f) & 0xffffu); }
; __device__ __forceinline__ float half32_sum(float v) { v = row16_sum(v); v += __shfl_xor(v, 16); return v; }
; __device__ __forceinline__ float sigmoid1(float x) { return __builtin_amdgcn_rcpf(1.0f + __expf(-x)); }
; __global__ void __launch_bounds__(NT, 2) mk_fwd(Args args) {
;     ...
; #pragma unroll
;                     for (int hh = 0; hh < 2; ++hh) {
;                         const int colA = c0 + hh * 64 + (lane & 31), colB = colA + 32;
;                         const float a0A = a0p[colA], a0B = a0p[colB], kkA = kkw[colA], kkB = kkw[colB], kaA = kaw[colA], kaB = kaw[colB];
; #pragma unroll
;                         for (int r = 0; r < 16; ++r) { const int tl = (r & 3) + 8 * (r >> 2) + 4 * (lane >> 5); const int t = t0 + mt * 32 + tl;
;                             const float kA = bf1(Ks[tl * 1032 + colA]), kB = bf1(Ks[tl * 1032 + colB]);
;                             const float aA = sigmoid1(a0A + acc[hh * 2][r]), aB = sigmoid1(a0B + acc[hh * 2 + 1][r]);
;                             const float qA = kA * kkA, qB = kB * kkB;
;                             const float ss = half32_sum(qA * qA + qB * qB);
;                             const float inv = __builtin_amdgcn_rsqf(fmaxf(ss, 1e-24f));
;                             const float nA = qA * inv, nB = qB * inv;
;                             const size_t oA = (size_t)t * 1024 + colA, oB = oA + 32;
;                             KP[oA] = f2bf(kA * (1.0f + (aA - 1.0f) * kaA)); KP[oB] = f2bf(kB * (1.0f + (aB - 1.0f) * kaB));
;                             KKn[oA] = f2bf(nA); KKn[oB] = f2bf(nB); BB[oA] = f2bf(nA * aA); BB[oB] = f2bf(nB * aB);
;                             if ((r & 3) == 3) asm volatile("" ::: "memory"); }
	v_mov_b32_e32 v139, v234
	v_mov_b32_e32 v123, v235
	v_mov_b32_e32 v125, v238
	v_mov_b32_e32 v127, v239
	v_mov_b32_e32 v121, v242
	v_mov_b32_e32 v119, v243
	v_or_b32_e32 v141, s33, v131
	ds_read_u16 v145, v171 offset:40960
	ds_read_u16 v147, v171 offset:41024
	ds_read_u16 v149, v173 offset:40960
	ds_read_u16 v151, v173 offset:41024
	ds_read_u16 v166, v175 offset:40960
	ds_read_u16 v167, v175 offset:41024
	ds_read_u16 v211, v177 offset:40960
	ds_read_u16 v212, v177 offset:41024
	v_lshlrev_b32_e32 v152, 10, v141
	s_waitcnt lgkmcnt(7)
	v_lshlrev_b32_e32 v141, 16, v145
	s_waitcnt lgkmcnt(6)
	v_lshlrev_b32_e32 v145, 16, v147
	s_waitcnt lgkmcnt(5)
	v_lshlrev_b32_e32 v147, 16, v149
	s_waitcnt lgkmcnt(4)
	v_lshlrev_b32_e32 v149, 16, v151
	v_and_b32_e32 v117, 64, v208
	v_xor_b32_e32 v137, 16, v208
	v_add_u32_e32 v117, 64, v117
	v_cmp_lt_i32_e32 vcc, v137, v117
	v_mov_b32_e32 v153, v97
	v_lshl_add_u64 v[154:155], v[152:153], 0, v[64:65]
	v_cndmask_b32_e32 v137, v208, v137, vcc
	v_lshlrev_b32_e32 v137, 2, v137
	v_lshlrev_b64 v[154:155], 1, v[154:155]
	v_lshl_add_u64 v[156:157], s[96:97], 0, v[154:155]
	v_or_b32_e32 v158, 64, v154
	v_mov_b32_e32 v159, v155
	v_lshl_add_u64 v[162:163], s[96:97], 0, v[158:159]
	v_lshl_add_u64 v[160:161], s[30:31], 0, v[154:155]
	v_lshl_add_u64 v[154:155], s[34:35], 0, v[154:155]
	v_or_b32_e32 v143, s33, v172
	v_lshl_add_u64 v[164:165], s[30:31], 0, v[158:159]
	v_lshl_add_u64 v[158:159], s[34:35], 0, v[158:159]
	v_lshl_add_u64 v[152:153], v[152:153], 0, v[70:71]
	v_lshlrev_b64 v[152:153], 1, v[152:153]
	s_mov_b64 s[8:9], 0
	v_add_f32_e32 v48, v139, v48
	v_add_f32_e32 v32, v123, v32
	v_mul_f32_e32 v151, v125, v141
	v_mul_f32_e32 v213, v127, v145
	v_mul_f32_e32 v216, v213, v213
	v_fmac_f32_e32 v216, v151, v151
	v_mul_f32_e32 v48, 0xbfb8aa3b, v48
	v_mul_f32_e32 v32, 0xbfb8aa3b, v32
	v_add_f32_dpp v216, v216, v216 quad_perm:[1,0,3,2] row_mask:0xf bank_mask:0xf bound_ctrl:1
	v_add_f32_e32 v49, v139, v49
	v_mul_f32_e32 v215, v127, v149
	v_add_f32_dpp v216, v216, v216 quad_perm:[2,3,0,1] row_mask:0xf bank_mask:0xf bound_ctrl:1
	v_exp_f32_e32 v48, v48
	v_exp_f32_e32 v32, v32
	v_add_f32_dpp v216, v216, v216 row_half_mirror row_mask:0xf bank_mask:0xf bound_ctrl:1
	v_mul_f32_e32 v214, v125, v147
	v_mul_f32_e32 v49, 0xbfb8aa3b, v49
	v_mul_f32_e32 v217, v215, v215
	v_add_f32_dpp v216, v216, v216 row_mirror row_mask:0xf bank_mask:0xf bound_ctrl:1
	v_exp_f32_e32 v49, v49
	v_fmac_f32_e32 v217, v214, v214
	ds_bpermute_b32 v218, v137, v216
	v_add_f32_e32 v48, 1.0, v48
	v_add_f32_dpp v217, v217, v217 quad_perm:[1,0,3,2] row_mask:0xf bank_mask:0xf bound_ctrl:1
	v_add_f32_e32 v32, 1.0, v32
	v_rcp_f32_e32 v48, v48
	v_add_f32_dpp v217, v217, v217 quad_perm:[2,3,0,1] row_mask:0xf bank_mask:0xf bound_ctrl:1
	v_rcp_f32_e32 v32, v32
	v_add_f32_e32 v49, 1.0, v49
	v_add_f32_dpp v217, v217, v217 row_half_mirror row_mask:0xf bank_mask:0xf bound_ctrl:1
	v_rcp_f32_e32 v219, v49
	s_waitcnt lgkmcnt(0)
	v_add_f32_e32 v216, v216, v218
	v_add_f32_dpp v217, v217, v217 row_mirror row_mask:0xf bank_mask:0xf bound_ctrl:1
	ds_bpermute_b32 v49, v137, v217
	v_max_f32_e32 v216, 0x179abe15, v216
	v_add_f32_e32 v220, -1.0, v48
	v_add_f32_e32 v221, -1.0, v32
	v_rsq_f32_e32 v216, v216
	v_add_f32_e32 v33, v123, v33
	v_fma_f32 v218, v121, v220, 1.0
	v_fma_f32 v220, v119, v221, 1.0
	v_mul_f32_e32 v33, 0xbfb8aa3b, v33
	v_mul_f32_e32 v141, v218, v141
	v_mul_f32_e32 v145, v220, v145
	v_exp_f32_e32 v33, v33
	s_waitcnt lgkmcnt(0)
	v_add_f32_e32 v49, v217, v49
	v_cvt_pk_bf16_f32 v141, v141, v97
	v_cvt_pk_bf16_f32 v145, v145, v97
	v_max_f32_e32 v49, 0x179abe15, v49
	global_store_short v[156:157], v141, off
	global_store_short v[162:163], v145, off
	v_mul_f32_e32 v141, v151, v216
	v_mul_f32_e32 v145, v213, v216
	v_rsq_f32_e32 v49, v49
	v_mul_f32_e32 v48, v48, v141
	v_mul_f32_e32 v32, v32, v145
	v_cvt_pk_bf16_f32 v151, v141, v97
	v_cvt_pk_bf16_f32 v48, v48, v97
	v_cvt_pk_bf16_f32 v32, v32, v97
	v_cvt_pk_bf16_f32 v156, v145, v97
	global_store_short v[160:161], v151, off
	global_store_short v[164:165], v156, off
	global_store_short v[154:155], v48, off
	global_store_short v[158:159], v32, off
	v_add_f32_e32 v32, 1.0, v33
	v_rcp_f32_e32 v141, v32
	v_lshlrev_b32_e32 v32, 10, v143
	v_mov_b32_e32 v33, v97
	v_add_f32_e32 v143, -1.0, v219
	v_mul_f32_e32 v145, v214, v49
	v_mul_f32_e32 v151, v215, v49
	v_lshl_add_u64 v[48:49], v[32:33], 0, v[64:65]
	v_fma_f32 v143, v121, v143, 1.0
	v_mul_f32_e32 v143, v143, v147
	v_lshlrev_b64 v[48:49], 1, v[48:49]
	v_cvt_pk_bf16_f32 v143, v143, v97
	v_lshl_add_u64 v[154:155], s[96:97], 0, v[48:49]
	global_store_short v[154:155], v143, off
	v_add_f32_e32 v143, -1.0, v141
	v_fma_f32 v143, v119, v143, 1.0
	v_mul_f32_e32 v143, v143, v149
	v_or_b32_e32 v154, 64, v48
	v_mov_b32_e32 v155, v49
	v_cvt_pk_bf16_f32 v143, v143, v97
	v_lshl_add_u64 v[156:157], s[96:97], 0, v[154:155]
	global_store_short v[156:157], v143, off
	v_cvt_pk_bf16_f32 v143, v145, v97
	v_lshl_add_u64 v[156:157], s[30:31], 0, v[48:49]
	global_store_short v[156:157], v143, off
	v_cvt_pk_bf16_f32 v143, v151, v97
	v_lshl_add_u64 v[156:157], s[30:31], 0, v[154:155]
	global_store_short v[156:157], v143, off
	v_mul_f32_e32 v143, v219, v145
	v_lshl_add_u64 v[48:49], s[34:35], 0, v[48:49]
	v_cvt_pk_bf16_f32 v143, v143, v97
	global_store_short v[48:49], v143, off
	v_mul_f32_e32 v48, v141, v151
	v_cvt_pk_bf16_f32 v141, v48, v97
	v_lshl_add_u64 v[48:49], s[34:35], 0, v[154:155]
	v_lshlrev_b32_e32 v143, 16, v167
	global_store_short v[48:49], v141, off
	v_lshlrev_b32_e32 v141, 16, v166
	v_mul_f32_e32 v145, v127, v143
	v_add_f32_e32 v49, v139, v50
	v_mul_f32_e32 v50, v125, v141
	v_mul_f32_e32 v147, v145, v145
	v_fmac_f32_e32 v147, v50, v50
	v_mul_f32_e32 v49, 0xbfb8aa3b, v49
	v_exp_f32_e32 v49, v49
	v_add_f32_dpp v147, v147, v147 quad_perm:[1,0,3,2] row_mask:0xf bank_mask:0xf bound_ctrl:1
	v_add_f32_e32 v34, v123, v34
	v_mul_f32_e32 v34, 0xbfb8aa3b, v34
	v_add_f32_dpp v147, v147, v147 quad_perm:[2,3,0,1] row_mask:0xf bank_mask:0xf bound_ctrl:1
	v_add_f32_e32 v49, 1.0, v49
	v_exp_f32_e32 v34, v34
	v_add_f32_dpp v147, v147, v147 row_half_mirror row_mask:0xf bank_mask:0xf bound_ctrl:1
	v_or_b32_e32 v48, s33, v174
	v_lshlrev_b32_e32 v48, 10, v48
	v_add_f32_dpp v147, v147, v147 row_mirror row_mask:0xf bank_mask:0xf bound_ctrl:1
	ds_bpermute_b32 v149, v137, v147
	v_add_f32_e32 v34, 1.0, v34
	v_rcp_f32_e32 v34, v34
	v_add_f32_e32 v35, v123, v35
	v_mul_f32_e32 v35, 0xbfb8aa3b, v35
	s_waitcnt lgkmcnt(0)
; __device__ __forceinline__ float bf1(bf16 h) { return __uint_as_float((unsigned)h << 16); }
; __device__ __forceinline__ bf16 f2bf(float f) { return (bf16)(pg8::cvt_pk_bf16(f, 0.f) & 0xffffu); }
; __device__ __forceinline__ float half32_sum(float v) { v = row16_sum(v); v += __shfl_xor(v, 16); return v; }
; __device__ __forceinline__ float sigmoid1(float x) { return __builtin_amdgcn_rcpf(1.0f + __expf(-x)); }
; __global__ void __launch_bounds__(NT, 2) mk_fwd(Args args) {
;     ...
;                         for (int r = 0; r < 16; ++r) { const int tl = (r & 3) + 8 * (r >> 2) + 4 * (lane >> 5); const int t = t0 + mt * 32 + tl;
;                             const float kA = bf1(Ks[tl * 1032 + colA]), kB = bf1(Ks[tl * 1032 + colB]);
;                             const float aA = sigmoid1(a0A + acc[hh * 2][r]), aB = sigmoid1(a0B + acc[hh * 2 + 1][r]);
;                             const float qA = kA * kkA, qB = kB * kkB;
;                             const float ss = half32_sum(qA * qA + qB * qB);
;                             const float inv = __builtin_amdgcn_rsqf(fmaxf(ss, 1e-24f));
;                             const float nA = qA * inv, nB = qB * inv;
;                             const size_t oA = (size_t)t * 1024 + colA, oB = oA + 32;
;                             KP[oA] = f2bf(kA * (1.0f + (aA - 1.0f) * kaA)); KP[oB] = f2bf(kB * (1.0f + (aB - 1.0f) * kaB));
;                             KKn[oA] = f2bf(nA); KKn[oB] = f2bf(nB); BB[oA] = f2bf(nA * aA); BB[oB] = f2bf(nB * aB);
;                             if ((r & 3) == 3) asm volatile("" ::: "memory"); }
	v_add_f32_e32 v147, v147, v149
	v_max_f32_e32 v147, 0x179abe15, v147
	v_rsq_f32_e32 v147, v147
	v_rcp_f32_e32 v149, v49
	v_mov_b32_e32 v49, v97
	v_lshl_add_u64 v[154:155], v[48:49], 0, v[64:65]
	v_mul_f32_e32 v50, v50, v147
	v_mul_f32_e32 v145, v145, v147
	v_add_f32_e32 v147, -1.0, v149
	v_fma_f32 v147, v121, v147, 1.0
	v_mul_f32_e32 v141, v147, v141
	v_lshlrev_b64 v[154:155], 1, v[154:155]
	v_cvt_pk_bf16_f32 v141, v141, v97
	v_lshl_add_u64 v[156:157], s[96:97], 0, v[154:155]
	global_store_short v[156:157], v141, off
	v_add_f32_e32 v141, -1.0, v34
	v_fma_f32 v141, v119, v141, 1.0
	v_mul_f32_e32 v141, v141, v143
	v_or_b32_e32 v156, 64, v154
	v_mov_b32_e32 v157, v155
	v_cvt_pk_bf16_f32 v141, v141, v97
	v_lshl_add_u64 v[158:159], s[96:97], 0, v[156:157]
	global_store_short v[158:159], v141, off
	v_cvt_pk_bf16_f32 v141, v50, v97
	v_lshl_add_u64 v[158:159], s[30:31], 0, v[154:155]
	global_store_short v[158:159], v141, off
	v_cvt_pk_bf16_f32 v141, v145, v97
	v_lshl_add_u64 v[158:159], s[30:31], 0, v[156:157]
	v_mul_f32_e32 v50, v149, v50
	v_lshlrev_b32_e32 v143, 16, v212
	global_store_short v[158:159], v141, off
	v_cvt_pk_bf16_f32 v50, v50, v97
	v_lshl_add_u64 v[154:155], s[34:35], 0, v[154:155]
	v_mul_f32_e32 v34, v34, v145
	v_lshlrev_b32_e32 v141, 16, v211
	v_mul_f32_e32 v145, v127, v143
	global_store_short v[154:155], v50, off
	v_add_f32_e32 v50, v139, v51
	v_mul_f32_e32 v51, v125, v141
	v_mul_f32_e32 v147, v145, v145
	v_fmac_f32_e32 v147, v51, v51
	v_mul_f32_e32 v50, 0xbfb8aa3b, v50
	v_exp_f32_e32 v50, v50
	v_add_f32_dpp v147, v147, v147 quad_perm:[1,0,3,2] row_mask:0xf bank_mask:0xf bound_ctrl:1
	v_exp_f32_e32 v35, v35
	v_cvt_pk_bf16_f32 v34, v34, v97
	v_add_f32_e32 v50, 1.0, v50
	v_add_f32_dpp v147, v147, v147 quad_perm:[2,3,0,1] row_mask:0xf bank_mask:0xf bound_ctrl:1
	v_lshl_add_u64 v[154:155], s[34:35], 0, v[156:157]
	global_store_short v[154:155], v34, off
	v_add_f32_dpp v147, v147, v147 row_half_mirror row_mask:0xf bank_mask:0xf bound_ctrl:1
	v_or_b32_e32 v34, s33, v176
	v_add_f32_e32 v35, 1.0, v35
	v_add_f32_dpp v147, v147, v147 row_mirror row_mask:0xf bank_mask:0xf bound_ctrl:1
	ds_bpermute_b32 v149, v137, v147
	v_rcp_f32_e32 v151, v35
	v_lshlrev_b32_e32 v34, 10, v34
	v_mov_b32_e32 v35, v97
	v_add_f32_e32 v36, v123, v36
	s_waitcnt lgkmcnt(0)
	v_add_f32_e32 v147, v147, v149
	v_max_f32_e32 v147, 0x179abe15, v147
	v_rsq_f32_e32 v147, v147
	v_rcp_f32_e32 v149, v50
	v_mul_f32_e32 v36, 0xbfb8aa3b, v36
	v_exp_f32_e32 v36, v36
	v_mul_f32_e32 v158, v51, v147
	v_mul_f32_e32 v145, v145, v147
	v_add_f32_e32 v147, -1.0, v149
	v_lshl_add_u64 v[50:51], v[34:35], 0, v[64:65]
	v_fma_f32 v147, v121, v147, 1.0
	v_mul_f32_e32 v141, v147, v141
	v_lshlrev_b64 v[50:51], 1, v[50:51]
	v_cvt_pk_bf16_f32 v141, v141, v97
	v_lshl_add_u64 v[154:155], s[96:97], 0, v[50:51]
	global_store_short v[154:155], v141, off
	v_add_f32_e32 v141, -1.0, v151
	v_fma_f32 v141, v119, v141, 1.0
	v_mul_f32_e32 v141, v141, v143
	v_or_b32_e32 v154, 64, v50
	v_mov_b32_e32 v155, v51
	v_cvt_pk_bf16_f32 v141, v141, v97
	v_lshl_add_u64 v[156:157], s[96:97], 0, v[154:155]
	global_store_short v[156:157], v141, off
	v_cvt_pk_bf16_f32 v141, v158, v97
	v_lshl_add_u64 v[156:157], s[30:31], 0, v[50:51]
	global_store_short v[156:157], v141, off
	v_cvt_pk_bf16_f32 v141, v145, v97
	v_lshl_add_u64 v[156:157], s[30:31], 0, v[154:155]
	global_store_short v[156:157], v141, off
	v_mul_f32_e32 v141, v149, v158
	v_lshl_add_u64 v[50:51], s[34:35], 0, v[50:51]
	v_cvt_pk_bf16_f32 v141, v141, v97
	global_store_short v[50:51], v141, off
	v_mul_f32_e32 v50, v151, v145
	v_cvt_pk_bf16_f32 v141, v50, v97
	v_lshl_add_u64 v[50:51], s[34:35], 0, v[154:155]
	global_store_short v[50:51], v141, off
	ds_read_u16 v51, v179 offset:40960
	ds_read_u16 v141, v179 offset:41024
	ds_read_u16 v143, v181 offset:40960
	ds_read_u16 v145, v181 offset:41024
	ds_read_u16 v147, v183 offset:40960
	ds_read_u16 v149, v183 offset:41024
	ds_read_u16 v151, v185 offset:40960
	ds_read_u16 v160, v185 offset:41024
	s_waitcnt lgkmcnt(6)
	v_lshlrev_b32_e32 v141, 16, v141
	v_lshlrev_b32_e32 v156, 16, v51
	v_mul_f32_e32 v154, v127, v141
	v_add_f32_e32 v51, v139, v52
	v_mul_f32_e32 v52, v125, v156
	v_mul_f32_e32 v155, v154, v154
	v_fmac_f32_e32 v155, v52, v52
	v_mul_f32_e32 v51, 0xbfb8aa3b, v51
	v_exp_f32_e32 v51, v51
	v_add_f32_dpp v155, v155, v155 quad_perm:[1,0,3,2] row_mask:0xf bank_mask:0xf bound_ctrl:1
	v_or_b32_e32 v50, s33, v178
	v_add_f32_e32 v36, 1.0, v36
	v_add_f32_dpp v155, v155, v155 quad_perm:[2,3,0,1] row_mask:0xf bank_mask:0xf bound_ctrl:1
	v_add_f32_e32 v51, 1.0, v51
	v_rcp_f32_e32 v161, v51
	v_add_f32_dpp v155, v155, v155 row_half_mirror row_mask:0xf bank_mask:0xf bound_ctrl:1
	v_rcp_f32_e32 v36, v36
	v_lshlrev_b32_e32 v50, 10, v50
	v_add_f32_dpp v155, v155, v155 row_mirror row_mask:0xf bank_mask:0xf bound_ctrl:1
	ds_bpermute_b32 v157, v137, v155
	v_mov_b32_e32 v51, v97
	v_add_f32_e32 v37, v123, v37
	v_mul_f32_e32 v37, 0xbfb8aa3b, v37
	v_exp_f32_e32 v37, v37
	s_waitcnt lgkmcnt(0)
; __device__ __forceinline__ float bf1(bf16 h) { return __uint_as_float((unsigned)h << 16); }
; __device__ __forceinline__ bf16 f2bf(float f) { return (bf16)(pg8::cvt_pk_bf16(f, 0.f) & 0xffffu); }
; __device__ __forceinline__ float half32_sum(float v) { v = row16_sum(v); v += __shfl_xor(v, 16); return v; }
; __device__ __forceinline__ float sigmoid1(float x) { return __builtin_amdgcn_rcpf(1.0f + __expf(-x)); }
; __global__ void __launch_bounds__(NT, 2) mk_fwd(Args args) {
;     ...
;                         for (int r = 0; r < 16; ++r) { const int tl = (r & 3) + 8 * (r >> 2) + 4 * (lane >> 5); const int t = t0 + mt * 32 + tl;
;                             const float kA = bf1(Ks[tl * 1032 + colA]), kB = bf1(Ks[tl * 1032 + colB]);
;                             const float aA = sigmoid1(a0A + acc[hh * 2][r]), aB = sigmoid1(a0B + acc[hh * 2 + 1][r]);
;                             const float qA = kA * kkA, qB = kB * kkB;
;                             const float ss = half32_sum(qA * qA + qB * qB);
;                             const float inv = __builtin_amdgcn_rsqf(fmaxf(ss, 1e-24f));
;                             const float nA = qA * inv, nB = qB * inv;
;                             const size_t oA = (size_t)t * 1024 + colA, oB = oA + 32;
;                             KP[oA] = f2bf(kA * (1.0f + (aA - 1.0f) * kaA)); KP[oB] = f2bf(kB * (1.0f + (aB - 1.0f) * kaB));
;                             KKn[oA] = f2bf(nA); KKn[oB] = f2bf(nB); BB[oA] = f2bf(nA * aA); BB[oB] = f2bf(nB * aB);
;                             if ((r & 3) == 3) asm volatile("" ::: "memory"); }
	v_add_f32_e32 v155, v155, v157
	v_max_f32_e32 v155, 0x179abe15, v155
	v_rsq_f32_e32 v155, v155
	v_add_f32_e32 v157, -1.0, v161
	v_fma_f32 v157, v121, v157, 1.0
	v_mul_f32_e32 v156, v157, v156
	v_mul_f32_e32 v52, v52, v155
	v_mul_f32_e32 v162, v154, v155
	v_lshl_add_u64 v[154:155], v[50:51], 0, v[64:65]
	v_lshlrev_b64 v[154:155], 1, v[154:155]
	v_cvt_pk_bf16_f32 v158, v156, v97
	v_lshl_add_u64 v[156:157], s[96:97], 0, v[154:155]
	global_store_short v[156:157], v158, off
	v_add_f32_e32 v156, -1.0, v36
	v_fma_f32 v156, v119, v156, 1.0
	v_mul_f32_e32 v141, v156, v141
	v_or_b32_e32 v156, 64, v154
	v_mov_b32_e32 v157, v155
	v_cvt_pk_bf16_f32 v141, v141, v97
	v_lshl_add_u64 v[158:159], s[96:97], 0, v[156:157]
	global_store_short v[158:159], v141, off
	v_cvt_pk_bf16_f32 v141, v52, v97
	v_lshl_add_u64 v[158:159], s[30:31], 0, v[154:155]
	global_store_short v[158:159], v141, off
	v_cvt_pk_bf16_f32 v141, v162, v97
	v_lshl_add_u64 v[158:159], s[30:31], 0, v[156:157]
	global_store_short v[158:159], v141, off
	v_mul_f32_e32 v52, v161, v52
	v_lshl_add_u64 v[154:155], s[34:35], 0, v[154:155]
	v_lshlrev_b32_e32 v141, 16, v143
	v_lshlrev_b32_e32 v143, 16, v145
	v_cvt_pk_bf16_f32 v52, v52, v97
	global_store_short v[154:155], v52, off
	v_mul_f32_e32 v36, v36, v162
	v_lshl_add_u64 v[154:155], s[34:35], 0, v[156:157]
	v_mul_f32_e32 v145, v127, v143
	v_cvt_pk_bf16_f32 v36, v36, v97
	global_store_short v[154:155], v36, off
	v_add_f32_e32 v52, v139, v53
	v_mul_f32_e32 v53, v125, v141
	v_mul_f32_e32 v154, v145, v145
	v_fmac_f32_e32 v154, v53, v53
	v_mul_f32_e32 v52, 0xbfb8aa3b, v52
	v_exp_f32_e32 v52, v52
	v_add_f32_dpp v154, v154, v154 quad_perm:[1,0,3,2] row_mask:0xf bank_mask:0xf bound_ctrl:1
	v_or_b32_e32 v36, s33, v180
	v_add_f32_e32 v37, 1.0, v37
	v_add_f32_dpp v154, v154, v154 quad_perm:[2,3,0,1] row_mask:0xf bank_mask:0xf bound_ctrl:1
	v_add_f32_e32 v52, 1.0, v52
	v_rcp_f32_e32 v158, v52
	v_add_f32_dpp v154, v154, v154 row_half_mirror row_mask:0xf bank_mask:0xf bound_ctrl:1
	v_rcp_f32_e32 v159, v37
	v_lshlrev_b32_e32 v36, 10, v36
	v_add_f32_dpp v154, v154, v154 row_mirror row_mask:0xf bank_mask:0xf bound_ctrl:1
	ds_bpermute_b32 v155, v137, v154
	v_mov_b32_e32 v37, v97
	v_add_f32_e32 v38, v123, v38
	v_mul_f32_e32 v38, 0xbfb8aa3b, v38
	v_exp_f32_e32 v38, v38
	s_waitcnt lgkmcnt(0)
	v_add_f32_e32 v154, v154, v155
	v_max_f32_e32 v154, 0x179abe15, v154
	v_rsq_f32_e32 v154, v154
	v_add_f32_e32 v38, 1.0, v38
	v_rcp_f32_e32 v38, v38
	v_add_f32_e32 v39, v123, v39
	v_mul_f32_e32 v161, v53, v154
	v_mul_f32_e32 v145, v145, v154
	v_add_f32_e32 v154, -1.0, v158
	v_lshl_add_u64 v[52:53], v[36:37], 0, v[64:65]
	v_fma_f32 v154, v121, v154, 1.0
	v_mul_f32_e32 v141, v154, v141
	v_lshlrev_b64 v[52:53], 1, v[52:53]
	v_cvt_pk_bf16_f32 v141, v141, v97
	v_lshl_add_u64 v[154:155], s[96:97], 0, v[52:53]
	global_store_short v[154:155], v141, off
	v_add_f32_e32 v141, -1.0, v159
	v_fma_f32 v141, v119, v141, 1.0
	v_mul_f32_e32 v141, v141, v143
	v_or_b32_e32 v154, 64, v52
	v_mov_b32_e32 v155, v53
	v_cvt_pk_bf16_f32 v141, v141, v97
	v_lshl_add_u64 v[156:157], s[96:97], 0, v[154:155]
	global_store_short v[156:157], v141, off
	v_cvt_pk_bf16_f32 v141, v161, v97
	v_lshl_add_u64 v[156:157], s[30:31], 0, v[52:53]
	global_store_short v[156:157], v141, off
	v_cvt_pk_bf16_f32 v141, v145, v97
	v_lshl_add_u64 v[156:157], s[30:31], 0, v[154:155]
	global_store_short v[156:157], v141, off
	v_mul_f32_e32 v141, v158, v161
	v_lshl_add_u64 v[52:53], s[34:35], 0, v[52:53]
	v_cvt_pk_bf16_f32 v141, v141, v97
	global_store_short v[52:53], v141, off
	v_mul_f32_e32 v52, v159, v145
	v_cvt_pk_bf16_f32 v141, v52, v97
	v_lshl_add_u64 v[52:53], s[34:35], 0, v[154:155]
	v_lshlrev_b32_e32 v143, 16, v149
	global_store_short v[52:53], v141, off
	v_lshlrev_b32_e32 v141, 16, v147
	v_mul_f32_e32 v145, v127, v143
	v_add_f32_e32 v53, v139, v54
	v_mul_f32_e32 v54, v125, v141
	v_mul_f32_e32 v147, v145, v145
	v_fmac_f32_e32 v147, v54, v54
	v_mul_f32_e32 v53, 0xbfb8aa3b, v53
	v_exp_f32_e32 v53, v53
	v_add_f32_dpp v147, v147, v147 quad_perm:[1,0,3,2] row_mask:0xf bank_mask:0xf bound_ctrl:1
	v_or_b32_e32 v52, s33, v182
	v_lshlrev_b32_e32 v52, 10, v52
	v_add_f32_dpp v147, v147, v147 quad_perm:[2,3,0,1] row_mask:0xf bank_mask:0xf bound_ctrl:1
	v_add_f32_e32 v53, 1.0, v53
	v_mul_f32_e32 v39, 0xbfb8aa3b, v39
	v_add_f32_dpp v147, v147, v147 row_half_mirror row_mask:0xf bank_mask:0xf bound_ctrl:1
	v_exp_f32_e32 v39, v39
	v_add_f32_e32 v40, v123, v40
	v_add_f32_dpp v147, v147, v147 row_mirror row_mask:0xf bank_mask:0xf bound_ctrl:1
	ds_bpermute_b32 v149, v137, v147
	v_add_f32_e32 v39, 1.0, v39
	v_mul_f32_e32 v40, 0xbfb8aa3b, v40
	v_exp_f32_e32 v40, v40
	v_add_f32_e32 v41, v123, v41
	s_waitcnt lgkmcnt(0)
; __device__ __forceinline__ float bf1(bf16 h) { return __uint_as_float((unsigned)h << 16); }
; __device__ __forceinline__ bf16 f2bf(float f) { return (bf16)(pg8::cvt_pk_bf16(f, 0.f) & 0xffffu); }
; __device__ __forceinline__ float half32_sum(float v) { v = row16_sum(v); v += __shfl_xor(v, 16); return v; }
; __device__ __forceinline__ float sigmoid1(float x) { return __builtin_amdgcn_rcpf(1.0f + __expf(-x)); }
; __global__ void __launch_bounds__(NT, 2) mk_fwd(Args args) {
;     ...
;                         for (int r = 0; r < 16; ++r) { const int tl = (r & 3) + 8 * (r >> 2) + 4 * (lane >> 5); const int t = t0 + mt * 32 + tl;
;                             const float kA = bf1(Ks[tl * 1032 + colA]), kB = bf1(Ks[tl * 1032 + colB]);
;                             const float aA = sigmoid1(a0A + acc[hh * 2][r]), aB = sigmoid1(a0B + acc[hh * 2 + 1][r]);
;                             const float qA = kA * kkA, qB = kB * kkB;
;                             const float ss = half32_sum(qA * qA + qB * qB);
;                             const float inv = __builtin_amdgcn_rsqf(fmaxf(ss, 1e-24f));
;                             const float nA = qA * inv, nB = qB * inv;
;                             const size_t oA = (size_t)t * 1024 + colA, oB = oA + 32;
;                             KP[oA] = f2bf(kA * (1.0f + (aA - 1.0f) * kaA)); KP[oB] = f2bf(kB * (1.0f + (aB - 1.0f) * kaB));
;                             KKn[oA] = f2bf(nA); KKn[oB] = f2bf(nB); BB[oA] = f2bf(nA * aA); BB[oB] = f2bf(nB * aB);
;                             if ((r & 3) == 3) asm volatile("" ::: "memory"); }
	v_add_f32_e32 v147, v147, v149
	v_max_f32_e32 v147, 0x179abe15, v147
	v_rsq_f32_e32 v147, v147
	v_rcp_f32_e32 v149, v53
	v_mov_b32_e32 v53, v97
	v_lshl_add_u64 v[154:155], v[52:53], 0, v[64:65]
	v_mul_f32_e32 v54, v54, v147
	v_mul_f32_e32 v145, v145, v147
	v_add_f32_e32 v147, -1.0, v149
	v_fma_f32 v147, v121, v147, 1.0
	v_mul_f32_e32 v141, v147, v141
	v_lshlrev_b64 v[154:155], 1, v[154:155]
	v_cvt_pk_bf16_f32 v141, v141, v97
	v_lshl_add_u64 v[156:157], s[96:97], 0, v[154:155]
	global_store_short v[156:157], v141, off
	v_add_f32_e32 v141, -1.0, v38
	v_fma_f32 v141, v119, v141, 1.0
	v_mul_f32_e32 v141, v141, v143
	v_or_b32_e32 v156, 64, v154
	v_mov_b32_e32 v157, v155
	v_cvt_pk_bf16_f32 v141, v141, v97
	v_lshl_add_u64 v[158:159], s[96:97], 0, v[156:157]
	global_store_short v[158:159], v141, off
	v_cvt_pk_bf16_f32 v141, v54, v97
	v_lshl_add_u64 v[158:159], s[30:31], 0, v[154:155]
	global_store_short v[158:159], v141, off
	v_cvt_pk_bf16_f32 v141, v145, v97
	v_lshl_add_u64 v[158:159], s[30:31], 0, v[156:157]
	v_mul_f32_e32 v54, v149, v54
	v_lshlrev_b32_e32 v143, 16, v160
	global_store_short v[158:159], v141, off
	v_cvt_pk_bf16_f32 v54, v54, v97
	v_lshl_add_u64 v[154:155], s[34:35], 0, v[154:155]
	v_mul_f32_e32 v38, v38, v145
	v_lshlrev_b32_e32 v141, 16, v151
	v_mul_f32_e32 v145, v127, v143
	global_store_short v[154:155], v54, off
	v_add_f32_e32 v54, v139, v55
	v_mul_f32_e32 v55, v125, v141
	v_mul_f32_e32 v147, v145, v145
	v_fmac_f32_e32 v147, v55, v55
	v_mul_f32_e32 v54, 0xbfb8aa3b, v54
	v_exp_f32_e32 v54, v54
	v_add_f32_dpp v147, v147, v147 quad_perm:[1,0,3,2] row_mask:0xf bank_mask:0xf bound_ctrl:1
	v_cvt_pk_bf16_f32 v38, v38, v97
	v_lshl_add_u64 v[154:155], s[34:35], 0, v[156:157]
	v_add_f32_e32 v54, 1.0, v54
	v_add_f32_dpp v147, v147, v147 quad_perm:[2,3,0,1] row_mask:0xf bank_mask:0xf bound_ctrl:1
	global_store_short v[154:155], v38, off
	v_or_b32_e32 v38, s33, v184
	v_add_f32_dpp v147, v147, v147 row_half_mirror row_mask:0xf bank_mask:0xf bound_ctrl:1
	v_rcp_f32_e32 v151, v39
	v_lshlrev_b32_e32 v38, 10, v38
	v_add_f32_dpp v147, v147, v147 row_mirror row_mask:0xf bank_mask:0xf bound_ctrl:1
	ds_bpermute_b32 v149, v137, v147
	v_mov_b32_e32 v39, v97
	v_add_f32_e32 v40, 1.0, v40
	v_rcp_f32_e32 v40, v40
	v_mul_f32_e32 v41, 0xbfb8aa3b, v41
	s_waitcnt lgkmcnt(0)
	v_add_f32_e32 v147, v147, v149
	v_max_f32_e32 v147, 0x179abe15, v147
	v_rsq_f32_e32 v147, v147
	v_rcp_f32_e32 v149, v54
	v_exp_f32_e32 v41, v41
	v_add_f32_e32 v42, v123, v42
	v_mul_f32_e32 v158, v55, v147
	v_mul_f32_e32 v145, v145, v147
	v_add_f32_e32 v147, -1.0, v149
	v_lshl_add_u64 v[54:55], v[38:39], 0, v[64:65]
	v_fma_f32 v147, v121, v147, 1.0
	v_mul_f32_e32 v141, v147, v141
	v_lshlrev_b64 v[54:55], 1, v[54:55]
	v_cvt_pk_bf16_f32 v141, v141, v97
	v_lshl_add_u64 v[154:155], s[96:97], 0, v[54:55]
	global_store_short v[154:155], v141, off
	v_add_f32_e32 v141, -1.0, v151
	v_fma_f32 v141, v119, v141, 1.0
	v_mul_f32_e32 v141, v141, v143
	v_or_b32_e32 v154, 64, v54
	v_mov_b32_e32 v155, v55
	v_cvt_pk_bf16_f32 v141, v141, v97
	v_lshl_add_u64 v[156:157], s[96:97], 0, v[154:155]
	global_store_short v[156:157], v141, off
	v_cvt_pk_bf16_f32 v141, v158, v97
	v_lshl_add_u64 v[156:157], s[30:31], 0, v[54:55]
	global_store_short v[156:157], v141, off
	v_cvt_pk_bf16_f32 v141, v145, v97
	v_lshl_add_u64 v[156:157], s[30:31], 0, v[154:155]
	global_store_short v[156:157], v141, off
	v_mul_f32_e32 v141, v149, v158
	v_lshl_add_u64 v[54:55], s[34:35], 0, v[54:55]
	v_cvt_pk_bf16_f32 v141, v141, v97
	global_store_short v[54:55], v141, off
	v_mul_f32_e32 v54, v151, v145
	v_cvt_pk_bf16_f32 v141, v54, v97
	v_lshl_add_u64 v[54:55], s[34:35], 0, v[154:155]
	global_store_short v[54:55], v141, off
	ds_read_u16 v55, v187 offset:40960
	ds_read_u16 v141, v187 offset:41024
	ds_read_u16 v143, v189 offset:40960
	ds_read_u16 v145, v189 offset:41024
	ds_read_u16 v147, v191 offset:40960
	ds_read_u16 v149, v191 offset:41024
	ds_read_u16 v151, v193 offset:40960
	ds_read_u16 v160, v193 offset:41024
	s_waitcnt lgkmcnt(6)
	v_lshlrev_b32_e32 v141, 16, v141
	v_lshlrev_b32_e32 v156, 16, v55
	v_mul_f32_e32 v154, v127, v141
	v_add_f32_e32 v55, v139, v56
	v_mul_f32_e32 v56, v125, v156
	v_mul_f32_e32 v155, v154, v154
	v_fmac_f32_e32 v155, v56, v56
	v_mul_f32_e32 v55, 0xbfb8aa3b, v55
	v_exp_f32_e32 v55, v55
	v_add_f32_dpp v155, v155, v155 quad_perm:[1,0,3,2] row_mask:0xf bank_mask:0xf bound_ctrl:1
	v_or_b32_e32 v54, s33, v186
	v_lshlrev_b32_e32 v54, 10, v54
	v_add_f32_dpp v155, v155, v155 quad_perm:[2,3,0,1] row_mask:0xf bank_mask:0xf bound_ctrl:1
	v_add_f32_e32 v55, 1.0, v55
	v_rcp_f32_e32 v161, v55
	v_add_f32_dpp v155, v155, v155 row_half_mirror row_mask:0xf bank_mask:0xf bound_ctrl:1
	v_mov_b32_e32 v55, v97
	v_add_f32_e32 v41, 1.0, v41
	v_add_f32_dpp v155, v155, v155 row_mirror row_mask:0xf bank_mask:0xf bound_ctrl:1
	ds_bpermute_b32 v157, v137, v155
	v_mul_f32_e32 v42, 0xbfb8aa3b, v42
	v_exp_f32_e32 v42, v42
	v_add_f32_e32 v43, v123, v43
	v_mul_f32_e32 v43, 0xbfb8aa3b, v43
	s_waitcnt lgkmcnt(0)
; __device__ __forceinline__ float bf1(bf16 h) { return __uint_as_float((unsigned)h << 16); }
; __device__ __forceinline__ bf16 f2bf(float f) { return (bf16)(pg8::cvt_pk_bf16(f, 0.f) & 0xffffu); }
; __device__ __forceinline__ float half32_sum(float v) { v = row16_sum(v); v += __shfl_xor(v, 16); return v; }
; __device__ __forceinline__ float sigmoid1(float x) { return __builtin_amdgcn_rcpf(1.0f + __expf(-x)); }
; __global__ void __launch_bounds__(NT, 2) mk_fwd(Args args) {
;     ...
;                         for (int r = 0; r < 16; ++r) { const int tl = (r & 3) + 8 * (r >> 2) + 4 * (lane >> 5); const int t = t0 + mt * 32 + tl;
;                             const float kA = bf1(Ks[tl * 1032 + colA]), kB = bf1(Ks[tl * 1032 + colB]);
;                             const float aA = sigmoid1(a0A + acc[hh * 2][r]), aB = sigmoid1(a0B + acc[hh * 2 + 1][r]);
;                             const float qA = kA * kkA, qB = kB * kkB;
;                             const float ss = half32_sum(qA * qA + qB * qB);
;                             const float inv = __builtin_amdgcn_rsqf(fmaxf(ss, 1e-24f));
;                             const float nA = qA * inv, nB = qB * inv;
;                             const size_t oA = (size_t)t * 1024 + colA, oB = oA + 32;
;                             KP[oA] = f2bf(kA * (1.0f + (aA - 1.0f) * kaA)); KP[oB] = f2bf(kB * (1.0f + (aB - 1.0f) * kaB));
;                             KKn[oA] = f2bf(nA); KKn[oB] = f2bf(nB); BB[oA] = f2bf(nA * aA); BB[oB] = f2bf(nB * aB);
;                             if ((r & 3) == 3) asm volatile("" ::: "memory"); }
	v_add_f32_e32 v155, v155, v157
	v_max_f32_e32 v155, 0x179abe15, v155
	v_rsq_f32_e32 v155, v155
	v_add_f32_e32 v157, -1.0, v161
	v_fma_f32 v157, v121, v157, 1.0
	v_mul_f32_e32 v156, v157, v156
	v_mul_f32_e32 v56, v56, v155
	v_mul_f32_e32 v162, v154, v155
	v_lshl_add_u64 v[154:155], v[54:55], 0, v[64:65]
	v_lshlrev_b64 v[154:155], 1, v[154:155]
	v_cvt_pk_bf16_f32 v158, v156, v97
	v_lshl_add_u64 v[156:157], s[96:97], 0, v[154:155]
	global_store_short v[156:157], v158, off
	v_add_f32_e32 v156, -1.0, v40
	v_fma_f32 v156, v119, v156, 1.0
	v_mul_f32_e32 v141, v156, v141
	v_or_b32_e32 v156, 64, v154
	v_mov_b32_e32 v157, v155
	v_cvt_pk_bf16_f32 v141, v141, v97
	v_lshl_add_u64 v[158:159], s[96:97], 0, v[156:157]
	global_store_short v[158:159], v141, off
	v_cvt_pk_bf16_f32 v141, v56, v97
	v_lshl_add_u64 v[158:159], s[30:31], 0, v[154:155]
	global_store_short v[158:159], v141, off
	v_cvt_pk_bf16_f32 v141, v162, v97
	v_lshl_add_u64 v[158:159], s[30:31], 0, v[156:157]
	global_store_short v[158:159], v141, off
	v_mul_f32_e32 v56, v161, v56
	v_lshl_add_u64 v[154:155], s[34:35], 0, v[154:155]
	v_lshlrev_b32_e32 v141, 16, v143
	v_lshlrev_b32_e32 v143, 16, v145
	v_cvt_pk_bf16_f32 v56, v56, v97
	global_store_short v[154:155], v56, off
	v_mul_f32_e32 v40, v40, v162
	v_lshl_add_u64 v[154:155], s[34:35], 0, v[156:157]
	v_mul_f32_e32 v145, v127, v143
	v_cvt_pk_bf16_f32 v40, v40, v97
	global_store_short v[154:155], v40, off
	v_add_f32_e32 v56, v139, v57
	v_mul_f32_e32 v57, v125, v141
	v_mul_f32_e32 v154, v145, v145
	v_fmac_f32_e32 v154, v57, v57
	v_mul_f32_e32 v56, 0xbfb8aa3b, v56
	v_exp_f32_e32 v56, v56
	v_add_f32_dpp v154, v154, v154 quad_perm:[1,0,3,2] row_mask:0xf bank_mask:0xf bound_ctrl:1
	v_or_b32_e32 v40, s33, v188
	v_rcp_f32_e32 v159, v41
	v_add_f32_dpp v154, v154, v154 quad_perm:[2,3,0,1] row_mask:0xf bank_mask:0xf bound_ctrl:1
	v_add_f32_e32 v56, 1.0, v56
	v_rcp_f32_e32 v158, v56
	v_add_f32_dpp v154, v154, v154 row_half_mirror row_mask:0xf bank_mask:0xf bound_ctrl:1
	v_lshlrev_b32_e32 v40, 10, v40
	v_mov_b32_e32 v41, v97
	v_add_f32_dpp v154, v154, v154 row_mirror row_mask:0xf bank_mask:0xf bound_ctrl:1
	ds_bpermute_b32 v155, v137, v154
	v_add_f32_e32 v42, 1.0, v42
	v_rcp_f32_e32 v42, v42
	v_exp_f32_e32 v43, v43
	v_add_f32_e32 v44, v123, v44
	s_waitcnt lgkmcnt(0)
	v_add_f32_e32 v154, v154, v155
	v_max_f32_e32 v154, 0x179abe15, v154
	v_rsq_f32_e32 v154, v154
	v_add_f32_e32 v43, 1.0, v43
	v_mul_f32_e32 v44, 0xbfb8aa3b, v44
	v_exp_f32_e32 v44, v44
	v_mul_f32_e32 v161, v57, v154
	v_mul_f32_e32 v145, v145, v154
	v_add_f32_e32 v154, -1.0, v158
	v_lshl_add_u64 v[56:57], v[40:41], 0, v[64:65]
	v_fma_f32 v154, v121, v154, 1.0
	v_mul_f32_e32 v141, v154, v141
	v_lshlrev_b64 v[56:57], 1, v[56:57]
	v_cvt_pk_bf16_f32 v141, v141, v97
	v_lshl_add_u64 v[154:155], s[96:97], 0, v[56:57]
	global_store_short v[154:155], v141, off
	v_add_f32_e32 v141, -1.0, v159
	v_fma_f32 v141, v119, v141, 1.0
	v_mul_f32_e32 v141, v141, v143
	v_or_b32_e32 v154, 64, v56
	v_mov_b32_e32 v155, v57
	v_cvt_pk_bf16_f32 v141, v141, v97
	v_lshl_add_u64 v[156:157], s[96:97], 0, v[154:155]
	global_store_short v[156:157], v141, off
	v_cvt_pk_bf16_f32 v141, v161, v97
	v_lshl_add_u64 v[156:157], s[30:31], 0, v[56:57]
	global_store_short v[156:157], v141, off
	v_cvt_pk_bf16_f32 v141, v145, v97
	v_lshl_add_u64 v[156:157], s[30:31], 0, v[154:155]
	global_store_short v[156:157], v141, off
	v_mul_f32_e32 v141, v158, v161
	v_lshl_add_u64 v[56:57], s[34:35], 0, v[56:57]
	v_cvt_pk_bf16_f32 v141, v141, v97
	global_store_short v[56:57], v141, off
	v_mul_f32_e32 v56, v159, v145
	v_cvt_pk_bf16_f32 v141, v56, v97
	v_lshl_add_u64 v[56:57], s[34:35], 0, v[154:155]
	v_lshlrev_b32_e32 v143, 16, v149
	global_store_short v[56:57], v141, off
	v_lshlrev_b32_e32 v141, 16, v147
	v_mul_f32_e32 v145, v127, v143
	v_add_f32_e32 v57, v139, v58
	v_mul_f32_e32 v58, v125, v141
	v_mul_f32_e32 v147, v145, v145
	v_fmac_f32_e32 v147, v58, v58
	v_mul_f32_e32 v57, 0xbfb8aa3b, v57
	v_exp_f32_e32 v57, v57
	v_add_f32_dpp v147, v147, v147 quad_perm:[1,0,3,2] row_mask:0xf bank_mask:0xf bound_ctrl:1
	v_or_b32_e32 v56, s33, v190
	v_lshlrev_b32_e32 v56, 10, v56
	v_add_f32_dpp v147, v147, v147 quad_perm:[2,3,0,1] row_mask:0xf bank_mask:0xf bound_ctrl:1
	v_add_f32_e32 v57, 1.0, v57
	v_add_f32_e32 v44, 1.0, v44
	v_add_f32_dpp v147, v147, v147 row_half_mirror row_mask:0xf bank_mask:0xf bound_ctrl:1
	v_rcp_f32_e32 v44, v44
	v_add_f32_e32 v45, v123, v45
	v_add_f32_dpp v147, v147, v147 row_mirror row_mask:0xf bank_mask:0xf bound_ctrl:1
	ds_bpermute_b32 v149, v137, v147
	v_mul_f32_e32 v45, 0xbfb8aa3b, v45
	v_exp_f32_e32 v45, v45
	v_add_f32_e32 v46, v123, v46
	v_mul_f32_e32 v46, 0xbfb8aa3b, v46
	s_waitcnt lgkmcnt(0)
; __device__ __forceinline__ float bf1(bf16 h) { return __uint_as_float((unsigned)h << 16); }
; __device__ __forceinline__ bf16 f2bf(float f) { return (bf16)(pg8::cvt_pk_bf16(f, 0.f) & 0xffffu); }
; __device__ __forceinline__ float half32_sum(float v) { v = row16_sum(v); v += __shfl_xor(v, 16); return v; }
; __device__ __forceinline__ float sigmoid1(float x) { return __builtin_amdgcn_rcpf(1.0f + __expf(-x)); }
; __global__ void __launch_bounds__(NT, 2) mk_fwd(Args args) {
;     ...
;                     for (int hh = 0; hh < 2; ++hh) {
;                         const int colA = c0 + hh * 64 + (lane & 31), colB = colA + 32;
;                         const float a0A = a0p[colA], a0B = a0p[colB], kkA = kkw[colA], kkB = kkw[colB], kaA = kaw[colA], kaB = kaw[colB];
; #pragma unroll
;                         for (int r = 0; r < 16; ++r) { const int tl = (r & 3) + 8 * (r >> 2) + 4 * (lane >> 5); const int t = t0 + mt * 32 + tl;
;                             const float kA = bf1(Ks[tl * 1032 + colA]), kB = bf1(Ks[tl * 1032 + colB]);
;                             const float aA = sigmoid1(a0A + acc[hh * 2][r]), aB = sigmoid1(a0B + acc[hh * 2 + 1][r]);
;                             const float qA = kA * kkA, qB = kB * kkB;
;                             const float ss = half32_sum(qA * qA + qB * qB);
;                             const float inv = __builtin_amdgcn_rsqf(fmaxf(ss, 1e-24f));
;                             const float nA = qA * inv, nB = qB * inv;
;                             const size_t oA = (size_t)t * 1024 + colA, oB = oA + 32;
;                             KP[oA] = f2bf(kA * (1.0f + (aA - 1.0f) * kaA)); KP[oB] = f2bf(kB * (1.0f + (aB - 1.0f) * kaB));
;                             KKn[oA] = f2bf(nA); KKn[oB] = f2bf(nB); BB[oA] = f2bf(nA * aA); BB[oB] = f2bf(nB * aB);
;                             if ((r & 3) == 3) asm volatile("" ::: "memory"); }
;                     }
	v_add_f32_e32 v147, v147, v149
	v_max_f32_e32 v147, 0x179abe15, v147
	v_rsq_f32_e32 v147, v147
	v_rcp_f32_e32 v149, v57
	v_mov_b32_e32 v57, v97
	v_lshl_add_u64 v[154:155], v[56:57], 0, v[64:65]
	v_mul_f32_e32 v58, v58, v147
	v_mul_f32_e32 v145, v145, v147
	v_add_f32_e32 v147, -1.0, v149
	v_fma_f32 v147, v121, v147, 1.0
	v_mul_f32_e32 v141, v147, v141
	v_lshlrev_b64 v[154:155], 1, v[154:155]
	v_cvt_pk_bf16_f32 v141, v141, v97
	v_lshl_add_u64 v[156:157], s[96:97], 0, v[154:155]
	global_store_short v[156:157], v141, off
	v_add_f32_e32 v141, -1.0, v42
	v_fma_f32 v141, v119, v141, 1.0
	v_mul_f32_e32 v141, v141, v143
	v_or_b32_e32 v156, 64, v154
	v_mov_b32_e32 v157, v155
	v_cvt_pk_bf16_f32 v141, v141, v97
	v_lshl_add_u64 v[158:159], s[96:97], 0, v[156:157]
	global_store_short v[158:159], v141, off
	v_cvt_pk_bf16_f32 v141, v58, v97
	v_lshl_add_u64 v[158:159], s[30:31], 0, v[154:155]
	global_store_short v[158:159], v141, off
	v_cvt_pk_bf16_f32 v141, v145, v97
	v_lshl_add_u64 v[158:159], s[30:31], 0, v[156:157]
	v_mul_f32_e32 v58, v149, v58
	v_lshlrev_b32_e32 v143, 16, v160
	global_store_short v[158:159], v141, off
	v_cvt_pk_bf16_f32 v58, v58, v97
	v_lshl_add_u64 v[154:155], s[34:35], 0, v[154:155]
	v_mul_f32_e32 v42, v42, v145
	v_lshlrev_b32_e32 v141, 16, v151
	v_mul_f32_e32 v145, v127, v143
	global_store_short v[154:155], v58, off
	v_add_f32_e32 v58, v139, v59
	v_mul_f32_e32 v59, v125, v141
	v_mul_f32_e32 v147, v145, v145
	v_fmac_f32_e32 v147, v59, v59
	v_mul_f32_e32 v58, 0xbfb8aa3b, v58
	v_exp_f32_e32 v58, v58
	v_add_f32_dpp v147, v147, v147 quad_perm:[1,0,3,2] row_mask:0xf bank_mask:0xf bound_ctrl:1
	v_cvt_pk_bf16_f32 v42, v42, v97
	v_lshl_add_u64 v[154:155], s[34:35], 0, v[156:157]
	v_add_f32_e32 v58, 1.0, v58
	v_add_f32_dpp v147, v147, v147 quad_perm:[2,3,0,1] row_mask:0xf bank_mask:0xf bound_ctrl:1
	global_store_short v[154:155], v42, off
	v_or_b32_e32 v42, s33, v192
	v_add_f32_dpp v147, v147, v147 row_half_mirror row_mask:0xf bank_mask:0xf bound_ctrl:1
	v_rcp_f32_e32 v151, v43
	v_lshlrev_b32_e32 v42, 10, v42
	v_add_f32_dpp v147, v147, v147 row_mirror row_mask:0xf bank_mask:0xf bound_ctrl:1
	ds_bpermute_b32 v149, v137, v147
	v_mov_b32_e32 v43, v97
	v_add_f32_e32 v45, 1.0, v45
	v_exp_f32_e32 v46, v46
	v_add_f32_e32 v47, v123, v47
	s_waitcnt lgkmcnt(0)
	v_add_f32_e32 v147, v147, v149
	v_max_f32_e32 v147, 0x179abe15, v147
	v_rsq_f32_e32 v147, v147
	v_rcp_f32_e32 v149, v58
	v_add_f32_e32 v46, 1.0, v46
	v_rcp_f32_e32 v46, v46
	v_mul_f32_e32 v158, v59, v147
	v_mul_f32_e32 v145, v145, v147
	v_add_f32_e32 v147, -1.0, v149
	v_lshl_add_u64 v[58:59], v[42:43], 0, v[64:65]
	v_fma_f32 v147, v121, v147, 1.0
	v_mul_f32_e32 v141, v147, v141
	v_lshlrev_b64 v[58:59], 1, v[58:59]
	v_cvt_pk_bf16_f32 v141, v141, v97
	v_lshl_add_u64 v[154:155], s[96:97], 0, v[58:59]
	global_store_short v[154:155], v141, off
	v_add_f32_e32 v141, -1.0, v151
	v_fma_f32 v141, v119, v141, 1.0
	v_mul_f32_e32 v141, v141, v143
	v_or_b32_e32 v154, 64, v58
	v_mov_b32_e32 v155, v59
	v_cvt_pk_bf16_f32 v141, v141, v97
	v_lshl_add_u64 v[156:157], s[96:97], 0, v[154:155]
	global_store_short v[156:157], v141, off
	v_cvt_pk_bf16_f32 v141, v158, v97
	v_lshl_add_u64 v[156:157], s[30:31], 0, v[58:59]
	global_store_short v[156:157], v141, off
	v_cvt_pk_bf16_f32 v141, v145, v97
	v_lshl_add_u64 v[156:157], s[30:31], 0, v[154:155]
	global_store_short v[156:157], v141, off
	v_mul_f32_e32 v141, v149, v158
	v_lshl_add_u64 v[58:59], s[34:35], 0, v[58:59]
	v_cvt_pk_bf16_f32 v141, v141, v97
	global_store_short v[58:59], v141, off
	v_mul_f32_e32 v58, v151, v145
	v_cvt_pk_bf16_f32 v141, v58, v97
	v_lshl_add_u64 v[58:59], s[34:35], 0, v[154:155]
	global_store_short v[58:59], v141, off
	ds_read_u16 v59, v195 offset:40960
	ds_read_u16 v141, v195 offset:41024
	ds_read_u16 v143, v197 offset:40960
	ds_read_u16 v145, v197 offset:41024
	ds_read_u16 v147, v199 offset:40960
	ds_read_u16 v149, v199 offset:41024
	ds_read_u16 v151, v201 offset:40960
	ds_read_u16 v160, v201 offset:41024
	s_waitcnt lgkmcnt(6)
	v_lshlrev_b32_e32 v141, 16, v141
	v_lshlrev_b32_e32 v156, 16, v59
	v_mul_f32_e32 v154, v127, v141
	v_add_f32_e32 v59, v139, v60
	v_mul_f32_e32 v60, v125, v156
	v_mul_f32_e32 v155, v154, v154
	v_fmac_f32_e32 v155, v60, v60
	v_mul_f32_e32 v59, 0xbfb8aa3b, v59
	v_exp_f32_e32 v59, v59
	v_add_f32_dpp v155, v155, v155 quad_perm:[1,0,3,2] row_mask:0xf bank_mask:0xf bound_ctrl:1
	v_or_b32_e32 v58, s33, v194
	v_lshlrev_b32_e32 v58, 10, v58
	v_add_f32_dpp v155, v155, v155 quad_perm:[2,3,0,1] row_mask:0xf bank_mask:0xf bound_ctrl:1
	v_add_f32_e32 v59, 1.0, v59
	v_rcp_f32_e32 v161, v59
	v_add_f32_dpp v155, v155, v155 row_half_mirror row_mask:0xf bank_mask:0xf bound_ctrl:1
	v_mov_b32_e32 v59, v97
	v_mul_f32_e32 v47, 0xbfb8aa3b, v47
	v_add_f32_dpp v155, v155, v155 row_mirror row_mask:0xf bank_mask:0xf bound_ctrl:1
	ds_bpermute_b32 v157, v137, v155
	v_exp_f32_e32 v47, v47
	s_waitcnt lgkmcnt(0)
; __device__ __forceinline__ float bf1(bf16 h) { return __uint_as_float((unsigned)h << 16); }
; __device__ __forceinline__ bf16 f2bf(float f) { return (bf16)(pg8::cvt_pk_bf16(f, 0.f) & 0xffffu); }
; __device__ __forceinline__ float half32_sum(float v) { v = row16_sum(v); v += __shfl_xor(v, 16); return v; }
; __device__ __forceinline__ float sigmoid1(float x) { return __builtin_amdgcn_rcpf(1.0f + __expf(-x)); }
; __global__ void __launch_bounds__(NT, 2) mk_fwd(Args args) {
;     ...
;                     for (int hh = 0; hh < 2; ++hh) {
;                         const int colA = c0 + hh * 64 + (lane & 31), colB = colA + 32;
;                         const float a0A = a0p[colA], a0B = a0p[colB], kkA = kkw[colA], kkB = kkw[colB], kaA = kaw[colA], kaB = kaw[colB];
; #pragma unroll
;                         for (int r = 0; r < 16; ++r) { const int tl = (r & 3) + 8 * (r >> 2) + 4 * (lane >> 5); const int t = t0 + mt * 32 + tl;
;                             const float kA = bf1(Ks[tl * 1032 + colA]), kB = bf1(Ks[tl * 1032 + colB]);
;                             const float aA = sigmoid1(a0A + acc[hh * 2][r]), aB = sigmoid1(a0B + acc[hh * 2 + 1][r]);
;                             const float qA = kA * kkA, qB = kB * kkB;
;                             const float ss = half32_sum(qA * qA + qB * qB);
;                             const float inv = __builtin_amdgcn_rsqf(fmaxf(ss, 1e-24f));
;                             const float nA = qA * inv, nB = qB * inv;
;                             const size_t oA = (size_t)t * 1024 + colA, oB = oA + 32;
;                             KP[oA] = f2bf(kA * (1.0f + (aA - 1.0f) * kaA)); KP[oB] = f2bf(kB * (1.0f + (aB - 1.0f) * kaB));
;                             KKn[oA] = f2bf(nA); KKn[oB] = f2bf(nB); BB[oA] = f2bf(nA * aA); BB[oB] = f2bf(nB * aB);
;                             if ((r & 3) == 3) asm volatile("" ::: "memory"); }
;                     }
	v_add_f32_e32 v155, v155, v157
	v_max_f32_e32 v155, 0x179abe15, v155
	v_rsq_f32_e32 v155, v155
	v_add_f32_e32 v157, -1.0, v161
	v_fma_f32 v157, v121, v157, 1.0
	v_mul_f32_e32 v156, v157, v156
	v_mul_f32_e32 v60, v60, v155
	v_mul_f32_e32 v162, v154, v155
	v_lshl_add_u64 v[154:155], v[58:59], 0, v[64:65]
	v_lshlrev_b64 v[154:155], 1, v[154:155]
	v_cvt_pk_bf16_f32 v158, v156, v97
	v_lshl_add_u64 v[156:157], s[96:97], 0, v[154:155]
	global_store_short v[156:157], v158, off
	v_add_f32_e32 v156, -1.0, v44
	v_fma_f32 v156, v119, v156, 1.0
	v_mul_f32_e32 v141, v156, v141
	v_or_b32_e32 v156, 64, v154
	v_mov_b32_e32 v157, v155
	v_cvt_pk_bf16_f32 v141, v141, v97
	v_lshl_add_u64 v[158:159], s[96:97], 0, v[156:157]
	global_store_short v[158:159], v141, off
	v_cvt_pk_bf16_f32 v141, v60, v97
	v_lshl_add_u64 v[158:159], s[30:31], 0, v[154:155]
	global_store_short v[158:159], v141, off
	v_cvt_pk_bf16_f32 v141, v162, v97
	v_lshl_add_u64 v[158:159], s[30:31], 0, v[156:157]
	global_store_short v[158:159], v141, off
	v_mul_f32_e32 v60, v161, v60
	v_lshl_add_u64 v[154:155], s[34:35], 0, v[154:155]
	v_lshlrev_b32_e32 v141, 16, v143
	v_lshlrev_b32_e32 v143, 16, v145
	v_cvt_pk_bf16_f32 v60, v60, v97
	global_store_short v[154:155], v60, off
	v_mul_f32_e32 v44, v44, v162
	v_lshl_add_u64 v[154:155], s[34:35], 0, v[156:157]
	v_mul_f32_e32 v145, v127, v143
	v_cvt_pk_bf16_f32 v44, v44, v97
	global_store_short v[154:155], v44, off
	v_add_f32_e32 v60, v139, v61
	v_mul_f32_e32 v61, v125, v141
	v_mul_f32_e32 v154, v145, v145
	v_fmac_f32_e32 v154, v61, v61
	v_mul_f32_e32 v60, 0xbfb8aa3b, v60
	v_exp_f32_e32 v60, v60
	v_add_f32_dpp v154, v154, v154 quad_perm:[1,0,3,2] row_mask:0xf bank_mask:0xf bound_ctrl:1
	v_or_b32_e32 v44, s33, v196
	v_rcp_f32_e32 v159, v45
	v_add_f32_dpp v154, v154, v154 quad_perm:[2,3,0,1] row_mask:0xf bank_mask:0xf bound_ctrl:1
	v_add_f32_e32 v60, 1.0, v60
	v_rcp_f32_e32 v158, v60
	v_add_f32_dpp v154, v154, v154 row_half_mirror row_mask:0xf bank_mask:0xf bound_ctrl:1
	v_lshlrev_b32_e32 v44, 10, v44
	v_mov_b32_e32 v45, v97
	v_add_f32_dpp v154, v154, v154 row_mirror row_mask:0xf bank_mask:0xf bound_ctrl:1
	ds_bpermute_b32 v155, v137, v154
	v_add_f32_e32 v47, 1.0, v47
	s_waitcnt lgkmcnt(0)
	v_add_f32_e32 v154, v154, v155
	v_max_f32_e32 v154, 0x179abe15, v154
	v_rsq_f32_e32 v154, v154
	s_nop 0
	v_mul_f32_e32 v161, v61, v154
	v_mul_f32_e32 v145, v145, v154
	v_add_f32_e32 v154, -1.0, v158
	v_lshl_add_u64 v[60:61], v[44:45], 0, v[64:65]
	v_fma_f32 v154, v121, v154, 1.0
	v_mul_f32_e32 v141, v154, v141
	v_lshlrev_b64 v[60:61], 1, v[60:61]
	v_cvt_pk_bf16_f32 v141, v141, v97
	v_lshl_add_u64 v[154:155], s[96:97], 0, v[60:61]
	global_store_short v[154:155], v141, off
	v_add_f32_e32 v141, -1.0, v159
	v_fma_f32 v141, v119, v141, 1.0
	v_mul_f32_e32 v141, v141, v143
	v_or_b32_e32 v154, 64, v60
	v_mov_b32_e32 v155, v61
	v_cvt_pk_bf16_f32 v141, v141, v97
	v_lshl_add_u64 v[156:157], s[96:97], 0, v[154:155]
	global_store_short v[156:157], v141, off
	v_cvt_pk_bf16_f32 v141, v161, v97
	v_lshl_add_u64 v[156:157], s[30:31], 0, v[60:61]
	global_store_short v[156:157], v141, off
	v_cvt_pk_bf16_f32 v141, v145, v97
	v_lshl_add_u64 v[156:157], s[30:31], 0, v[154:155]
	global_store_short v[156:157], v141, off
	v_mul_f32_e32 v141, v158, v161
	v_lshl_add_u64 v[60:61], s[34:35], 0, v[60:61]
	v_cvt_pk_bf16_f32 v141, v141, v97
	global_store_short v[60:61], v141, off
	v_mul_f32_e32 v60, v159, v145
	v_cvt_pk_bf16_f32 v141, v60, v97
	v_lshl_add_u64 v[60:61], s[34:35], 0, v[154:155]
	v_lshlrev_b32_e32 v143, 16, v149
	global_store_short v[60:61], v141, off
	v_lshlrev_b32_e32 v141, 16, v147
	v_mul_f32_e32 v145, v127, v143
	v_add_f32_e32 v61, v139, v62
	v_mul_f32_e32 v62, v125, v141
	v_mul_f32_e32 v147, v145, v145
	v_fmac_f32_e32 v147, v62, v62
	v_mul_f32_e32 v61, 0xbfb8aa3b, v61
	v_exp_f32_e32 v61, v61
	v_add_f32_dpp v147, v147, v147 quad_perm:[1,0,3,2] row_mask:0xf bank_mask:0xf bound_ctrl:1
	v_or_b32_e32 v60, s33, v198
	v_lshlrev_b32_e32 v60, 10, v60
	v_add_f32_dpp v147, v147, v147 quad_perm:[2,3,0,1] row_mask:0xf bank_mask:0xf bound_ctrl:1
	v_add_f32_e32 v61, 1.0, v61
	s_nop 0
	v_add_f32_dpp v147, v147, v147 row_half_mirror row_mask:0xf bank_mask:0xf bound_ctrl:1
	s_nop 1
	v_add_f32_dpp v147, v147, v147 row_mirror row_mask:0xf bank_mask:0xf bound_ctrl:1
	ds_bpermute_b32 v149, v137, v147
	s_waitcnt lgkmcnt(0)
	v_add_f32_e32 v147, v147, v149
	v_max_f32_e32 v147, 0x179abe15, v147
	v_rsq_f32_e32 v147, v147
	v_rcp_f32_e32 v149, v61
	v_mov_b32_e32 v61, v97
	v_lshl_add_u64 v[154:155], v[60:61], 0, v[64:65]
	v_mul_f32_e32 v62, v62, v147
	v_mul_f32_e32 v145, v145, v147
	v_add_f32_e32 v147, -1.0, v149
	v_fma_f32 v147, v121, v147, 1.0
	v_mul_f32_e32 v141, v147, v141
	v_lshlrev_b64 v[154:155], 1, v[154:155]
	v_cvt_pk_bf16_f32 v141, v141, v97
	v_lshl_add_u64 v[156:157], s[96:97], 0, v[154:155]
	global_store_short v[156:157], v141, off
	v_add_f32_e32 v141, -1.0, v46
	v_fma_f32 v141, v119, v141, 1.0
	v_mul_f32_e32 v141, v141, v143
	v_or_b32_e32 v156, 64, v154
	v_mov_b32_e32 v157, v155
	v_cvt_pk_bf16_f32 v141, v141, v97
	v_lshl_add_u64 v[158:159], s[96:97], 0, v[156:157]
	global_store_short v[158:159], v141, off
	v_cvt_pk_bf16_f32 v141, v62, v97
	v_lshl_add_u64 v[158:159], s[30:31], 0, v[154:155]
	global_store_short v[158:159], v141, off
	v_cvt_pk_bf16_f32 v141, v145, v97
	v_lshl_add_u64 v[158:159], s[30:31], 0, v[156:157]
	v_mul_f32_e32 v62, v149, v62
	global_store_short v[158:159], v141, off
	v_cvt_pk_bf16_f32 v62, v62, v97
	v_lshl_add_u64 v[154:155], s[34:35], 0, v[154:155]
	v_lshlrev_b32_e32 v141, 16, v151
	v_lshlrev_b32_e32 v143, 16, v160
	global_store_short v[154:155], v62, off
	v_add_f32_e32 v62, v139, v63
	v_mul_f32_e32 v63, v125, v141
	v_mul_f32_e32 v125, v127, v143
	v_mul_f32_e32 v127, v125, v125
	v_fmac_f32_e32 v127, v63, v63
	v_mul_f32_e32 v62, 0xbfb8aa3b, v62
	v_exp_f32_e32 v62, v62
	v_add_f32_dpp v127, v127, v127 quad_perm:[1,0,3,2] row_mask:0xf bank_mask:0xf bound_ctrl:1
	v_mul_f32_e32 v46, v46, v145
	v_cvt_pk_bf16_f32 v46, v46, v97
	v_add_f32_e32 v62, 1.0, v62
	v_add_f32_dpp v127, v127, v127 quad_perm:[2,3,0,1] row_mask:0xf bank_mask:0xf bound_ctrl:1
	v_lshl_add_u64 v[154:155], s[34:35], 0, v[156:157]
	global_store_short v[154:155], v46, off
	v_add_f32_dpp v127, v127, v127 row_half_mirror row_mask:0xf bank_mask:0xf bound_ctrl:1
	v_or_b32_e32 v46, s33, v200
	v_lshlrev_b32_e32 v46, 10, v46
	v_add_f32_dpp v127, v127, v127 row_mirror row_mask:0xf bank_mask:0xf bound_ctrl:1
	ds_bpermute_b32 v139, v137, v127
	s_waitcnt lgkmcnt(0)
; __device__ __forceinline__ float bf1(bf16 h) { return __uint_as_float((unsigned)h << 16); }
; __device__ __forceinline__ bf16 f2bf(float f) { return (bf16)(pg8::cvt_pk_bf16(f, 0.f) & 0xffffu); }
; __device__ __forceinline__ float half32_sum(float v) { v = row16_sum(v); v += __shfl_xor(v, 16); return v; }
; __device__ __forceinline__ float sigmoid1(float x) { return __builtin_amdgcn_rcpf(1.0f + __expf(-x)); }
; __global__ void __launch_bounds__(NT, 2) mk_fwd(Args args) {
;     ...
;                     for (int hh = 0; hh < 2; ++hh) {
;                         const int colA = c0 + hh * 64 + (lane & 31), colB = colA + 32;
;                         const float a0A = a0p[colA], a0B = a0p[colB], kkA = kkw[colA], kkB = kkw[colB], kaA = kaw[colA], kaB = kaw[colB];
; #pragma unroll
;                         for (int r = 0; r < 16; ++r) { const int tl = (r & 3) + 8 * (r >> 2) + 4 * (lane >> 5); const int t = t0 + mt * 32 + tl;
;                             const float kA = bf1(Ks[tl * 1032 + colA]), kB = bf1(Ks[tl * 1032 + colB]);
;                             const float aA = sigmoid1(a0A + acc[hh * 2][r]), aB = sigmoid1(a0B + acc[hh * 2 + 1][r]);
;                             const float qA = kA * kkA, qB = kB * kkB;
;                             const float ss = half32_sum(qA * qA + qB * qB);
;                             const float inv = __builtin_amdgcn_rsqf(fmaxf(ss, 1e-24f));
;                             const float nA = qA * inv, nB = qB * inv;
;                             const size_t oA = (size_t)t * 1024 + colA, oB = oA + 32;
;                             KP[oA] = f2bf(kA * (1.0f + (aA - 1.0f) * kaA)); KP[oB] = f2bf(kB * (1.0f + (aB - 1.0f) * kaB));
;                             KKn[oA] = f2bf(nA); KKn[oB] = f2bf(nB); BB[oA] = f2bf(nA * aA); BB[oB] = f2bf(nB * aB);
;                             if ((r & 3) == 3) asm volatile("" ::: "memory"); }
;                     }
	v_add_f32_e32 v123, v127, v139
	v_max_f32_e32 v123, 0x179abe15, v123
	v_rsq_f32_e32 v123, v123
	v_rcp_f32_e32 v127, v62
	v_rcp_f32_e32 v139, v47
	v_mov_b32_e32 v47, v97
	v_mul_f32_e32 v145, v63, v123
	v_mul_f32_e32 v123, v125, v123
	v_add_f32_e32 v125, -1.0, v127
	v_lshl_add_u64 v[62:63], v[46:47], 0, v[64:65]
	v_fma_f32 v121, v121, v125, 1.0
	v_mul_f32_e32 v121, v121, v141
	v_lshlrev_b64 v[62:63], 1, v[62:63]
	v_cvt_pk_bf16_f32 v121, v121, v97
	v_lshl_add_u64 v[154:155], s[96:97], 0, v[62:63]
	global_store_short v[154:155], v121, off
	v_add_f32_e32 v121, -1.0, v139
	v_fma_f32 v119, v119, v121, 1.0
	v_mul_f32_e32 v119, v119, v143
	v_or_b32_e32 v154, 64, v62
	v_mov_b32_e32 v155, v63
	v_cvt_pk_bf16_f32 v119, v119, v97
	v_lshl_add_u64 v[156:157], s[96:97], 0, v[154:155]
	global_store_short v[156:157], v119, off
	v_cvt_pk_bf16_f32 v119, v145, v97
	v_lshl_add_u64 v[156:157], s[30:31], 0, v[62:63]
	global_store_short v[156:157], v119, off
	v_cvt_pk_bf16_f32 v119, v123, v97
	v_lshl_add_u64 v[156:157], s[30:31], 0, v[154:155]
	global_store_short v[156:157], v119, off
	v_mul_f32_e32 v119, v127, v145
	v_lshl_add_u64 v[62:63], s[34:35], 0, v[62:63]
	v_cvt_pk_bf16_f32 v119, v119, v97
	global_store_short v[62:63], v119, off
	v_mul_f32_e32 v62, v139, v123
	v_cvt_pk_bf16_f32 v119, v62, v97
	v_lshl_add_u64 v[62:63], s[34:35], 0, v[154:155]
	global_store_short v[62:63], v119, off
	v_mov_b32_e32 v125, v236
	v_mov_b32_e32 v121, v240
	v_mov_b32_e32 v123, v241
	v_mov_b32_e32 v119, v237
	v_mov_b32_e32 v63, v244
	v_mov_b32_e32 v62, v245
	ds_read_u16 v127, v171 offset:41088
	ds_read_u16 v139, v171 offset:41152
	ds_read_u16 v141, v173 offset:41088
	ds_read_u16 v143, v173 offset:41152
	ds_read_u16 v145, v175 offset:41088
	ds_read_u16 v147, v175 offset:41152
	ds_read_u16 v149, v177 offset:41088
	ds_read_u16 v151, v177 offset:41152
	s_waitcnt lgkmcnt(6)
	v_lshlrev_b32_e32 v139, 16, v139
	v_lshlrev_b32_e32 v127, 16, v127
	v_add_f32_e32 v16, v125, v16
	v_mul_f32_e32 v154, v121, v127
	v_mul_f32_e32 v155, v123, v139
	v_mul_f32_e32 v156, v155, v155
	v_fmac_f32_e32 v156, v154, v154
	v_mul_f32_e32 v16, 0xbfb8aa3b, v16
	v_exp_f32_e32 v16, v16
	v_add_f32_dpp v156, v156, v156 quad_perm:[1,0,3,2] row_mask:0xf bank_mask:0xf bound_ctrl:1
	v_add_f32_e32 v0, v119, v0
	v_mul_f32_e32 v0, 0xbfb8aa3b, v0
	v_add_f32_dpp v156, v156, v156 quad_perm:[2,3,0,1] row_mask:0xf bank_mask:0xf bound_ctrl:1
	v_add_f32_e32 v16, 1.0, v16
	v_exp_f32_e32 v0, v0
	v_add_f32_dpp v156, v156, v156 row_half_mirror row_mask:0xf bank_mask:0xf bound_ctrl:1
	v_rcp_f32_e32 v16, v16
	v_add_f32_e32 v1, v119, v1
	v_add_f32_dpp v156, v156, v156 row_mirror row_mask:0xf bank_mask:0xf bound_ctrl:1
	ds_bpermute_b32 v157, v137, v156
	v_add_f32_e32 v0, 1.0, v0
	v_rcp_f32_e32 v0, v0
	v_mul_f32_e32 v1, 0xbfb8aa3b, v1
	v_exp_f32_e32 v1, v1
	s_waitcnt lgkmcnt(0)
	v_add_f32_e32 v156, v156, v157
	v_max_f32_e32 v156, 0x179abe15, v156
	v_rsq_f32_e32 v156, v156
	v_add_f32_e32 v2, v119, v2
	v_mul_f32_e32 v2, 0xbfb8aa3b, v2
	v_exp_f32_e32 v2, v2
	v_mul_f32_e32 v158, v154, v156
	v_add_f32_e32 v154, -1.0, v16
	v_fma_f32 v154, v63, v154, 1.0
	v_mul_f32_e32 v127, v154, v127
	v_mul_f32_e32 v159, v155, v156
	v_cvt_pk_bf16_f32 v127, v127, v97
	v_lshl_add_u64 v[154:155], s[96:97], 0, v[152:153]
	global_store_short v[154:155], v127, off
	v_add_f32_e32 v127, -1.0, v0
	v_fma_f32 v127, v62, v127, 1.0
	v_mul_f32_e32 v127, v127, v139
	v_or_b32_e32 v154, 64, v152
	v_mov_b32_e32 v155, v153
	v_cvt_pk_bf16_f32 v127, v127, v97
	v_lshl_add_u64 v[156:157], s[96:97], 0, v[154:155]
	global_store_short v[156:157], v127, off
	v_cvt_pk_bf16_f32 v127, v158, v97
	v_lshl_add_u64 v[156:157], s[30:31], 0, v[152:153]
	global_store_short v[156:157], v127, off
	v_cvt_pk_bf16_f32 v127, v159, v97
	v_lshl_add_u64 v[156:157], s[30:31], 0, v[154:155]
	v_mul_f32_e32 v16, v16, v158
	global_store_short v[156:157], v127, off
	v_cvt_pk_bf16_f32 v16, v16, v97
	v_lshl_add_u64 v[152:153], s[34:35], 0, v[152:153]
	v_mul_f32_e32 v0, v0, v159
	v_lshlrev_b32_e32 v127, 16, v143
	global_store_short v[152:153], v16, off
	v_cvt_pk_bf16_f32 v0, v0, v97
	v_lshl_add_u64 v[152:153], s[34:35], 0, v[154:155]
	v_lshlrev_b32_e32 v16, 16, v141
	v_mul_f32_e32 v139, v123, v127
	global_store_short v[152:153], v0, off
	v_add_f32_e32 v0, v125, v17
	v_mul_f32_e32 v17, v121, v16
	v_mul_f32_e32 v141, v139, v139
	v_fmac_f32_e32 v141, v17, v17
	v_mul_f32_e32 v0, 0xbfb8aa3b, v0
	v_exp_f32_e32 v0, v0
	v_add_f32_dpp v141, v141, v141 quad_perm:[1,0,3,2] row_mask:0xf bank_mask:0xf bound_ctrl:1
	v_add_f32_e32 v3, v119, v3
	v_mul_f32_e32 v3, 0xbfb8aa3b, v3
	v_add_f32_dpp v141, v141, v141 quad_perm:[2,3,0,1] row_mask:0xf bank_mask:0xf bound_ctrl:1
	v_add_f32_e32 v0, 1.0, v0
	v_exp_f32_e32 v3, v3
	v_add_f32_dpp v141, v141, v141 row_half_mirror row_mask:0xf bank_mask:0xf bound_ctrl:1
	v_add_f32_e32 v4, v119, v4
	v_mul_f32_e32 v4, 0xbfb8aa3b, v4
	v_add_f32_dpp v141, v141, v141 row_mirror row_mask:0xf bank_mask:0xf bound_ctrl:1
	ds_bpermute_b32 v143, v137, v141
	v_exp_f32_e32 v4, v4
	v_add_f32_e32 v5, v119, v5
	v_mul_f32_e32 v5, 0xbfb8aa3b, v5
	v_exp_f32_e32 v5, v5
	s_waitcnt lgkmcnt(0)
; __device__ __forceinline__ float bf1(bf16 h) { return __uint_as_float((unsigned)h << 16); }
; __device__ __forceinline__ bf16 f2bf(float f) { return (bf16)(pg8::cvt_pk_bf16(f, 0.f) & 0xffffu); }
; __device__ __forceinline__ float half32_sum(float v) { v = row16_sum(v); v += __shfl_xor(v, 16); return v; }
; __device__ __forceinline__ float sigmoid1(float x) { return __builtin_amdgcn_rcpf(1.0f + __expf(-x)); }
; __global__ void __launch_bounds__(NT, 2) mk_fwd(Args args) {
;     ...
;                     for (int hh = 0; hh < 2; ++hh) {
;                         const int colA = c0 + hh * 64 + (lane & 31), colB = colA + 32;
;                         const float a0A = a0p[colA], a0B = a0p[colB], kkA = kkw[colA], kkB = kkw[colB], kaA = kaw[colA], kaB = kaw[colB];
; #pragma unroll
;                         for (int r = 0; r < 16; ++r) { const int tl = (r & 3) + 8 * (r >> 2) + 4 * (lane >> 5); const int t = t0 + mt * 32 + tl;
;                             const float kA = bf1(Ks[tl * 1032 + colA]), kB = bf1(Ks[tl * 1032 + colB]);
;                             const float aA = sigmoid1(a0A + acc[hh * 2][r]), aB = sigmoid1(a0B + acc[hh * 2 + 1][r]);
;                             const float qA = kA * kkA, qB = kB * kkB;
;                             const float ss = half32_sum(qA * qA + qB * qB);
;                             const float inv = __builtin_amdgcn_rsqf(fmaxf(ss, 1e-24f));
;                             const float nA = qA * inv, nB = qB * inv;
;                             const size_t oA = (size_t)t * 1024 + colA, oB = oA + 32;
;                             KP[oA] = f2bf(kA * (1.0f + (aA - 1.0f) * kaA)); KP[oB] = f2bf(kB * (1.0f + (aB - 1.0f) * kaB));
;                             KKn[oA] = f2bf(nA); KKn[oB] = f2bf(nB); BB[oA] = f2bf(nA * aA); BB[oB] = f2bf(nB * aB);
;                             if ((r & 3) == 3) asm volatile("" ::: "memory"); }
;                     }
	v_add_f32_e32 v141, v141, v143
	v_max_f32_e32 v141, 0x179abe15, v141
	v_rsq_f32_e32 v141, v141
	v_rcp_f32_e32 v143, v0
	v_add_f32_e32 v0, 1.0, v1
	v_rcp_f32_e32 v152, v0
	v_mul_f32_e32 v153, v17, v141
	v_add_f32_e32 v17, -1.0, v143
	v_lshl_add_u64 v[0:1], v[32:33], 0, v[70:71]
	v_fma_f32 v17, v63, v17, 1.0
	v_mul_f32_e32 v16, v17, v16
	v_lshlrev_b64 v[0:1], 1, v[0:1]
	v_cvt_pk_bf16_f32 v32, v16, v97
	v_lshl_add_u64 v[16:17], s[96:97], 0, v[0:1]
	global_store_short v[16:17], v32, off
	v_add_f32_e32 v16, -1.0, v152
	v_fma_f32 v16, v62, v16, 1.0
	v_mul_f32_e32 v16, v16, v127
	v_cvt_pk_bf16_f32 v127, v16, v97
	v_or_b32_e32 v16, 64, v0
	v_mov_b32_e32 v17, v1
	v_lshl_add_u64 v[32:33], s[96:97], 0, v[16:17]
	global_store_short v[32:33], v127, off
	v_lshl_add_u64 v[32:33], s[30:31], 0, v[0:1]
	v_cvt_pk_bf16_f32 v127, v153, v97
	global_store_short v[32:33], v127, off
	v_lshl_add_u64 v[32:33], s[30:31], 0, v[16:17]
	v_mul_f32_e32 v139, v139, v141
	v_cvt_pk_bf16_f32 v127, v139, v97
	global_store_short v[32:33], v127, off
	v_mul_f32_e32 v32, v143, v153
	v_lshl_add_u64 v[0:1], s[34:35], 0, v[0:1]
	v_cvt_pk_bf16_f32 v32, v32, v97
	global_store_short v[0:1], v32, off
	v_mul_f32_e32 v0, v152, v139
	v_cvt_pk_bf16_f32 v32, v0, v97
	v_lshl_add_u64 v[0:1], s[34:35], 0, v[16:17]
	global_store_short v[0:1], v32, off
	v_lshlrev_b32_e32 v32, 16, v147
	v_lshlrev_b32_e32 v16, 16, v145
	v_mul_f32_e32 v17, v123, v32
	v_add_f32_e32 v0, v125, v18
	v_mul_f32_e32 v1, v121, v16
	v_mul_f32_e32 v18, v17, v17
	v_fmac_f32_e32 v18, v1, v1
	v_mul_f32_e32 v0, 0xbfb8aa3b, v0
	v_exp_f32_e32 v0, v0
	v_add_f32_dpp v18, v18, v18 quad_perm:[1,0,3,2] row_mask:0xf bank_mask:0xf bound_ctrl:1
	v_add_f32_e32 v6, v119, v6
	v_mul_f32_e32 v6, 0xbfb8aa3b, v6
	v_add_f32_dpp v18, v18, v18 quad_perm:[2,3,0,1] row_mask:0xf bank_mask:0xf bound_ctrl:1
	v_add_f32_e32 v0, 1.0, v0
	v_rcp_f32_e32 v127, v0
	v_add_f32_dpp v18, v18, v18 row_half_mirror row_mask:0xf bank_mask:0xf bound_ctrl:1
	v_add_f32_e32 v0, 1.0, v2
	v_rcp_f32_e32 v2, v0
	v_add_f32_dpp v18, v18, v18 row_mirror row_mask:0xf bank_mask:0xf bound_ctrl:1
	ds_bpermute_b32 v33, v137, v18
	v_exp_f32_e32 v6, v6
	v_add_f32_e32 v7, v119, v7
	v_mul_f32_e32 v7, 0xbfb8aa3b, v7
	v_exp_f32_e32 v7, v7
	s_waitcnt lgkmcnt(0)
	v_add_f32_e32 v18, v18, v33
	v_max_f32_e32 v18, 0x179abe15, v18
	v_rsq_f32_e32 v18, v18
	v_add_f32_e32 v8, v119, v8
	v_mul_f32_e32 v8, 0xbfb8aa3b, v8
	v_exp_f32_e32 v8, v8
	v_mul_f32_e32 v139, v1, v18
	v_mul_f32_e32 v18, v17, v18
	v_add_f32_e32 v17, -1.0, v127
	v_lshl_add_u64 v[0:1], v[48:49], 0, v[70:71]
	v_fma_f32 v17, v63, v17, 1.0
	v_mul_f32_e32 v16, v17, v16
	v_lshlrev_b64 v[0:1], 1, v[0:1]
	v_cvt_pk_bf16_f32 v33, v16, v97
	v_lshl_add_u64 v[16:17], s[96:97], 0, v[0:1]
	global_store_short v[16:17], v33, off
	v_add_f32_e32 v16, -1.0, v2
	v_fma_f32 v16, v62, v16, 1.0
	v_mul_f32_e32 v16, v16, v32
	v_cvt_pk_bf16_f32 v48, v16, v97
	v_or_b32_e32 v16, 64, v0
	v_mov_b32_e32 v17, v1
	v_lshl_add_u64 v[32:33], s[96:97], 0, v[16:17]
	global_store_short v[32:33], v48, off
	v_lshl_add_u64 v[32:33], s[30:31], 0, v[0:1]
	v_cvt_pk_bf16_f32 v48, v139, v97
	global_store_short v[32:33], v48, off
	v_lshl_add_u64 v[32:33], s[30:31], 0, v[16:17]
	v_cvt_pk_bf16_f32 v48, v18, v97
	global_store_short v[32:33], v48, off
	v_mul_f32_e32 v32, v127, v139
	v_lshl_add_u64 v[0:1], s[34:35], 0, v[0:1]
	v_cvt_pk_bf16_f32 v32, v32, v97
	global_store_short v[0:1], v32, off
	v_mul_f32_e32 v0, v2, v18
	v_cvt_pk_bf16_f32 v2, v0, v97
	v_lshl_add_u64 v[0:1], s[34:35], 0, v[16:17]
	v_lshlrev_b32_e32 v16, 16, v151
	global_store_short v[0:1], v2, off
	v_lshlrev_b32_e32 v2, 16, v149
	v_mul_f32_e32 v17, v123, v16
	v_mul_f32_e32 v1, v121, v2
	v_mul_f32_e32 v18, v17, v17
	v_fmac_f32_e32 v18, v1, v1
	v_add_f32_e32 v0, v125, v19
	v_mul_f32_e32 v0, 0xbfb8aa3b, v0
	v_add_f32_dpp v18, v18, v18 quad_perm:[1,0,3,2] row_mask:0xf bank_mask:0xf bound_ctrl:1
	v_exp_f32_e32 v0, v0
	v_add_f32_e32 v12, v119, v12
	v_add_f32_dpp v18, v18, v18 quad_perm:[2,3,0,1] row_mask:0xf bank_mask:0xf bound_ctrl:1
	v_mul_f32_e32 v12, 0xbfb8aa3b, v12
	v_add_f32_e32 v0, 1.0, v0
	v_add_f32_dpp v18, v18, v18 row_half_mirror row_mask:0xf bank_mask:0xf bound_ctrl:1
	v_exp_f32_e32 v12, v12
	s_nop 0
	v_add_f32_dpp v18, v18, v18 row_mirror row_mask:0xf bank_mask:0xf bound_ctrl:1
	ds_bpermute_b32 v19, v137, v18
	s_waitcnt lgkmcnt(0)
	v_add_f32_e32 v18, v18, v19
	v_max_f32_e32 v18, 0x179abe15, v18
	v_rcp_f32_e32 v19, v0
	v_rsq_f32_e32 v18, v18
	v_add_f32_e32 v0, 1.0, v3
	v_rcp_f32_e32 v32, v0
	v_add_f32_e32 v3, -1.0, v19
	v_mul_f32_e32 v33, v1, v18
	v_lshl_add_u64 v[0:1], v[34:35], 0, v[70:71]
	v_fma_f32 v3, v63, v3, 1.0
	v_mul_f32_e32 v2, v3, v2
	v_lshlrev_b64 v[0:1], 1, v[0:1]
	v_mul_f32_e32 v18, v17, v18
	v_cvt_pk_bf16_f32 v17, v2, v97
	v_lshl_add_u64 v[2:3], s[96:97], 0, v[0:1]
	global_store_short v[2:3], v17, off
	v_add_f32_e32 v2, -1.0, v32
	v_fma_f32 v2, v62, v2, 1.0
	v_mul_f32_e32 v2, v2, v16
	v_cvt_pk_bf16_f32 v34, v2, v97
	v_or_b32_e32 v2, 64, v0
	v_mov_b32_e32 v3, v1
	v_lshl_add_u64 v[16:17], s[96:97], 0, v[2:3]
	global_store_short v[16:17], v34, off
	v_lshl_add_u64 v[16:17], s[30:31], 0, v[0:1]
	v_cvt_pk_bf16_f32 v34, v33, v97
	global_store_short v[16:17], v34, off
	v_lshl_add_u64 v[16:17], s[30:31], 0, v[2:3]
	v_cvt_pk_bf16_f32 v34, v18, v97
	global_store_short v[16:17], v34, off
	v_mul_f32_e32 v16, v19, v33
	v_lshl_add_u64 v[0:1], s[34:35], 0, v[0:1]
	v_cvt_pk_bf16_f32 v16, v16, v97
	global_store_short v[0:1], v16, off
	v_mul_f32_e32 v0, v32, v18
	v_cvt_pk_bf16_f32 v16, v0, v97
	v_lshl_add_u64 v[0:1], s[34:35], 0, v[2:3]
	global_store_short v[0:1], v16, off
	ds_read_u16 v0, v179 offset:41088
	ds_read_u16 v1, v179 offset:41152
	ds_read_u16 v18, v181 offset:41088
	ds_read_u16 v19, v181 offset:41152
	ds_read_u16 v32, v183 offset:41088
	ds_read_u16 v33, v183 offset:41152
	ds_read_u16 v34, v185 offset:41088
	ds_read_u16 v35, v185 offset:41152
	s_waitcnt lgkmcnt(6)
; __device__ __forceinline__ float bf1(bf16 h) { return __uint_as_float((unsigned)h << 16); }
; __device__ __forceinline__ bf16 f2bf(float f) { return (bf16)(pg8::cvt_pk_bf16(f, 0.f) & 0xffffu); }
; __device__ __forceinline__ float half32_sum(float v) { v = row16_sum(v); v += __shfl_xor(v, 16); return v; }
; __device__ __forceinline__ float sigmoid1(float x) { return __builtin_amdgcn_rcpf(1.0f + __expf(-x)); }
; __global__ void __launch_bounds__(NT, 2) mk_fwd(Args args) {
;     ...
;                     for (int hh = 0; hh < 2; ++hh) {
;                         const int colA = c0 + hh * 64 + (lane & 31), colB = colA + 32;
;                         const float a0A = a0p[colA], a0B = a0p[colB], kkA = kkw[colA], kkB = kkw[colB], kaA = kaw[colA], kaB = kaw[colB];
; #pragma unroll
;                         for (int r = 0; r < 16; ++r) { const int tl = (r & 3) + 8 * (r >> 2) + 4 * (lane >> 5); const int t = t0 + mt * 32 + tl;
;                             const float kA = bf1(Ks[tl * 1032 + colA]), kB = bf1(Ks[tl * 1032 + colB]);
;                             const float aA = sigmoid1(a0A + acc[hh * 2][r]), aB = sigmoid1(a0B + acc[hh * 2 + 1][r]);
;                             const float qA = kA * kkA, qB = kB * kkB;
;                             const float ss = half32_sum(qA * qA + qB * qB);
;                             const float inv = __builtin_amdgcn_rsqf(fmaxf(ss, 1e-24f));
;                             const float nA = qA * inv, nB = qB * inv;
;                             const size_t oA = (size_t)t * 1024 + colA, oB = oA + 32;
;                             KP[oA] = f2bf(kA * (1.0f + (aA - 1.0f) * kaA)); KP[oB] = f2bf(kB * (1.0f + (aB - 1.0f) * kaB));
;                             KKn[oA] = f2bf(nA); KKn[oB] = f2bf(nB); BB[oA] = f2bf(nA * aA); BB[oB] = f2bf(nB * aB);
;                             if ((r & 3) == 3) asm volatile("" ::: "memory"); }
;                     }
	v_lshlrev_b32_e32 v16, 16, v1
	v_lshlrev_b32_e32 v2, 16, v0
	v_mul_f32_e32 v3, v123, v16
	v_mul_f32_e32 v1, v121, v2
	v_mul_f32_e32 v17, v3, v3
	v_fmac_f32_e32 v17, v1, v1
	v_add_f32_e32 v0, v125, v20
	v_mul_f32_e32 v0, 0xbfb8aa3b, v0
	v_add_f32_dpp v17, v17, v17 quad_perm:[1,0,3,2] row_mask:0xf bank_mask:0xf bound_ctrl:1
	v_exp_f32_e32 v0, v0
	s_nop 0
	v_add_f32_dpp v17, v17, v17 quad_perm:[2,3,0,1] row_mask:0xf bank_mask:0xf bound_ctrl:1
	v_add_f32_e32 v0, 1.0, v0
	s_nop 0
	v_add_f32_dpp v17, v17, v17 row_half_mirror row_mask:0xf bank_mask:0xf bound_ctrl:1
	s_nop 1
	v_add_f32_dpp v17, v17, v17 row_mirror row_mask:0xf bank_mask:0xf bound_ctrl:1
	ds_bpermute_b32 v20, v137, v17
	s_waitcnt lgkmcnt(0)
	v_add_f32_e32 v17, v17, v20
	v_max_f32_e32 v17, 0x179abe15, v17
	v_rsq_f32_e32 v17, v17
	v_rcp_f32_e32 v20, v0
	v_add_f32_e32 v0, 1.0, v4
	v_rcp_f32_e32 v4, v0
	v_mul_f32_e32 v49, v3, v17
	v_add_f32_e32 v3, -1.0, v20
	v_mul_f32_e32 v48, v1, v17
	v_lshl_add_u64 v[0:1], v[50:51], 0, v[70:71]
	v_fma_f32 v3, v63, v3, 1.0
	v_mul_f32_e32 v2, v3, v2
	v_lshlrev_b64 v[0:1], 1, v[0:1]
	v_cvt_pk_bf16_f32 v17, v2, v97
	v_lshl_add_u64 v[2:3], s[96:97], 0, v[0:1]
	global_store_short v[2:3], v17, off
	v_add_f32_e32 v2, -1.0, v4
	v_fma_f32 v2, v62, v2, 1.0
	v_mul_f32_e32 v2, v2, v16
	v_cvt_pk_bf16_f32 v50, v2, v97
	v_or_b32_e32 v2, 64, v0
	v_mov_b32_e32 v3, v1
	v_lshl_add_u64 v[16:17], s[96:97], 0, v[2:3]
	global_store_short v[16:17], v50, off
	v_lshl_add_u64 v[16:17], s[30:31], 0, v[0:1]
	v_cvt_pk_bf16_f32 v50, v48, v97
	global_store_short v[16:17], v50, off
	v_lshl_add_u64 v[16:17], s[30:31], 0, v[2:3]
	v_cvt_pk_bf16_f32 v50, v49, v97
	global_store_short v[16:17], v50, off
	v_mul_f32_e32 v16, v20, v48
	v_lshl_add_u64 v[0:1], s[34:35], 0, v[0:1]
	v_cvt_pk_bf16_f32 v16, v16, v97
	global_store_short v[0:1], v16, off
	v_mul_f32_e32 v0, v4, v49
	v_cvt_pk_bf16_f32 v4, v0, v97
	v_lshl_add_u64 v[0:1], s[34:35], 0, v[2:3]
	global_store_short v[0:1], v4, off
	v_lshlrev_b32_e32 v4, 16, v19
	v_lshlrev_b32_e32 v2, 16, v18
	v_mul_f32_e32 v3, v123, v4
	v_mul_f32_e32 v1, v121, v2
	v_mul_f32_e32 v16, v3, v3
	v_fmac_f32_e32 v16, v1, v1
	v_add_f32_e32 v0, v125, v21
	v_mul_f32_e32 v0, 0xbfb8aa3b, v0
	v_add_f32_dpp v16, v16, v16 quad_perm:[1,0,3,2] row_mask:0xf bank_mask:0xf bound_ctrl:1
	v_exp_f32_e32 v0, v0
	v_mov_b32_e32 v48, 0
	v_add_f32_dpp v16, v16, v16 quad_perm:[2,3,0,1] row_mask:0xf bank_mask:0xf bound_ctrl:1
	v_mov_b32_e32 v49, v48
	v_add_f32_e32 v0, 1.0, v0
	v_add_f32_dpp v16, v16, v16 row_half_mirror row_mask:0xf bank_mask:0xf bound_ctrl:1
	v_mov_b32_e32 v50, v48
	v_mov_b32_e32 v51, v48
	v_add_f32_dpp v16, v16, v16 row_mirror row_mask:0xf bank_mask:0xf bound_ctrl:1
	ds_bpermute_b32 v17, v137, v16
	s_waitcnt lgkmcnt(0)
	v_add_f32_e32 v16, v16, v17
	v_max_f32_e32 v16, 0x179abe15, v16
	v_rsq_f32_e32 v16, v16
	v_rcp_f32_e32 v17, v0
	v_add_f32_e32 v0, 1.0, v5
	v_rcp_f32_e32 v18, v0
	v_mul_f32_e32 v19, v1, v16
	v_mul_f32_e32 v16, v3, v16
	v_add_f32_e32 v3, -1.0, v17
	v_lshl_add_u64 v[0:1], v[36:37], 0, v[70:71]
	v_fma_f32 v3, v63, v3, 1.0
	v_mul_f32_e32 v2, v3, v2
	v_lshlrev_b64 v[0:1], 1, v[0:1]
	v_cvt_pk_bf16_f32 v5, v2, v97
	v_lshl_add_u64 v[2:3], s[96:97], 0, v[0:1]
	global_store_short v[2:3], v5, off
	v_add_f32_e32 v2, -1.0, v18
	v_fma_f32 v2, v62, v2, 1.0
	v_mul_f32_e32 v2, v2, v4
	v_cvt_pk_bf16_f32 v20, v2, v97
	v_or_b32_e32 v2, 64, v0
	v_mov_b32_e32 v3, v1
	v_lshl_add_u64 v[4:5], s[96:97], 0, v[2:3]
	global_store_short v[4:5], v20, off
	v_lshl_add_u64 v[4:5], s[30:31], 0, v[0:1]
	v_cvt_pk_bf16_f32 v20, v19, v97
	global_store_short v[4:5], v20, off
	v_lshl_add_u64 v[4:5], s[30:31], 0, v[2:3]
	v_cvt_pk_bf16_f32 v20, v16, v97
	global_store_short v[4:5], v20, off
	v_mul_f32_e32 v4, v17, v19
	v_lshl_add_u64 v[0:1], s[34:35], 0, v[0:1]
	v_cvt_pk_bf16_f32 v4, v4, v97
	global_store_short v[0:1], v4, off
	v_mul_f32_e32 v0, v18, v16
	v_cvt_pk_bf16_f32 v4, v0, v97
	v_lshl_add_u64 v[0:1], s[34:35], 0, v[2:3]
	global_store_short v[0:1], v4, off
	v_lshlrev_b32_e32 v4, 16, v33
	v_lshlrev_b32_e32 v2, 16, v32
	v_mul_f32_e32 v3, v123, v4
	v_mul_f32_e32 v1, v121, v2
	v_mul_f32_e32 v5, v3, v3
	v_fmac_f32_e32 v5, v1, v1
	v_add_f32_e32 v0, v125, v22
	v_mul_f32_e32 v0, 0xbfb8aa3b, v0
	v_add_f32_dpp v5, v5, v5 quad_perm:[1,0,3,2] row_mask:0xf bank_mask:0xf bound_ctrl:1
	v_exp_f32_e32 v0, v0
	v_mov_b32_e32 v32, v48
	v_add_f32_dpp v5, v5, v5 quad_perm:[2,3,0,1] row_mask:0xf bank_mask:0xf bound_ctrl:1
	v_mov_b32_e32 v33, v48
	v_add_f32_e32 v0, 1.0, v0
	v_add_f32_dpp v5, v5, v5 row_half_mirror row_mask:0xf bank_mask:0xf bound_ctrl:1
	v_mov_b32_e32 v36, v48
	v_mov_b32_e32 v37, v48
	v_add_f32_dpp v5, v5, v5 row_mirror row_mask:0xf bank_mask:0xf bound_ctrl:1
	ds_bpermute_b32 v16, v137, v5
	s_waitcnt lgkmcnt(0)
; __device__ __forceinline__ float bf1(bf16 h) { return __uint_as_float((unsigned)h << 16); }
; __device__ __forceinline__ bf16 f2bf(float f) { return (bf16)(pg8::cvt_pk_bf16(f, 0.f) & 0xffffu); }
; __device__ __forceinline__ float half32_sum(float v) { v = row16_sum(v); v += __shfl_xor(v, 16); return v; }
; __device__ __forceinline__ float sigmoid1(float x) { return __builtin_amdgcn_rcpf(1.0f + __expf(-x)); }
; __global__ void __launch_bounds__(NT, 2) mk_fwd(Args args) {
;     ...
;                     for (int hh = 0; hh < 2; ++hh) {
;                         const int colA = c0 + hh * 64 + (lane & 31), colB = colA + 32;
;                         const float a0A = a0p[colA], a0B = a0p[colB], kkA = kkw[colA], kkB = kkw[colB], kaA = kaw[colA], kaB = kaw[colB];
; #pragma unroll
;                         for (int r = 0; r < 16; ++r) { const int tl = (r & 3) + 8 * (r >> 2) + 4 * (lane >> 5); const int t = t0 + mt * 32 + tl;
;                             const float kA = bf1(Ks[tl * 1032 + colA]), kB = bf1(Ks[tl * 1032 + colB]);
;                             const float aA = sigmoid1(a0A + acc[hh * 2][r]), aB = sigmoid1(a0B + acc[hh * 2 + 1][r]);
;                             const float qA = kA * kkA, qB = kB * kkB;
;                             const float ss = half32_sum(qA * qA + qB * qB);
;                             const float inv = __builtin_amdgcn_rsqf(fmaxf(ss, 1e-24f));
;                             const float nA = qA * inv, nB = qB * inv;
;                             const size_t oA = (size_t)t * 1024 + colA, oB = oA + 32;
;                             KP[oA] = f2bf(kA * (1.0f + (aA - 1.0f) * kaA)); KP[oB] = f2bf(kB * (1.0f + (aB - 1.0f) * kaB));
;                             KKn[oA] = f2bf(nA); KKn[oB] = f2bf(nB); BB[oA] = f2bf(nA * aA); BB[oB] = f2bf(nB * aB);
;                             if ((r & 3) == 3) asm volatile("" ::: "memory"); }
;                     }
	v_add_f32_e32 v5, v5, v16
	v_max_f32_e32 v5, 0x179abe15, v5
	v_rsq_f32_e32 v5, v5
	v_rcp_f32_e32 v16, v0
	v_add_f32_e32 v0, 1.0, v6
	v_rcp_f32_e32 v6, v0
	v_mul_f32_e32 v18, v3, v5
	v_add_f32_e32 v3, -1.0, v16
	v_mul_f32_e32 v17, v1, v5
	v_lshl_add_u64 v[0:1], v[52:53], 0, v[70:71]
	v_fma_f32 v3, v63, v3, 1.0
	v_mul_f32_e32 v2, v3, v2
	v_lshlrev_b64 v[0:1], 1, v[0:1]
	v_cvt_pk_bf16_f32 v5, v2, v97
	v_lshl_add_u64 v[2:3], s[96:97], 0, v[0:1]
	global_store_short v[2:3], v5, off
	v_add_f32_e32 v2, -1.0, v6
	v_fma_f32 v2, v62, v2, 1.0
	v_mul_f32_e32 v2, v2, v4
	v_cvt_pk_bf16_f32 v19, v2, v97
	v_or_b32_e32 v2, 64, v0
	v_mov_b32_e32 v3, v1
	v_lshl_add_u64 v[4:5], s[96:97], 0, v[2:3]
	global_store_short v[4:5], v19, off
	v_lshl_add_u64 v[4:5], s[30:31], 0, v[0:1]
	v_cvt_pk_bf16_f32 v19, v17, v97
	global_store_short v[4:5], v19, off
	v_lshl_add_u64 v[4:5], s[30:31], 0, v[2:3]
	v_cvt_pk_bf16_f32 v19, v18, v97
	global_store_short v[4:5], v19, off
	v_mul_f32_e32 v4, v16, v17
	v_lshl_add_u64 v[0:1], s[34:35], 0, v[0:1]
	v_cvt_pk_bf16_f32 v4, v4, v97
	global_store_short v[0:1], v4, off
	v_mul_f32_e32 v0, v6, v18
	v_cvt_pk_bf16_f32 v4, v0, v97
	v_lshl_add_u64 v[0:1], s[34:35], 0, v[2:3]
	global_store_short v[0:1], v4, off
	v_lshlrev_b32_e32 v4, 16, v35
	v_lshlrev_b32_e32 v2, 16, v34
	v_mul_f32_e32 v3, v123, v4
	v_mul_f32_e32 v1, v121, v2
	v_mul_f32_e32 v5, v3, v3
	v_fmac_f32_e32 v5, v1, v1
	v_add_f32_e32 v0, v125, v23
	v_mul_f32_e32 v0, 0xbfb8aa3b, v0
	v_add_f32_dpp v5, v5, v5 quad_perm:[1,0,3,2] row_mask:0xf bank_mask:0xf bound_ctrl:1
	v_exp_f32_e32 v0, v0
	v_mov_b32_e32 v52, v48
	v_add_f32_dpp v5, v5, v5 quad_perm:[2,3,0,1] row_mask:0xf bank_mask:0xf bound_ctrl:1
	v_mov_b32_e32 v53, v48
	v_add_f32_e32 v0, 1.0, v0
	v_add_f32_dpp v5, v5, v5 row_half_mirror row_mask:0xf bank_mask:0xf bound_ctrl:1
	v_mov_b32_e32 v34, v48
	v_mov_b32_e32 v35, v48
	v_add_f32_dpp v5, v5, v5 row_mirror row_mask:0xf bank_mask:0xf bound_ctrl:1
	ds_bpermute_b32 v6, v137, v5
	s_waitcnt lgkmcnt(0)
	v_add_f32_e32 v5, v5, v6
	v_max_f32_e32 v5, 0x179abe15, v5
	v_rsq_f32_e32 v5, v5
	v_rcp_f32_e32 v6, v0
	v_add_f32_e32 v0, 1.0, v7
	v_rcp_f32_e32 v7, v0
	v_mul_f32_e32 v17, v3, v5
	v_add_f32_e32 v3, -1.0, v6
	v_mul_f32_e32 v16, v1, v5
	v_lshl_add_u64 v[0:1], v[38:39], 0, v[70:71]
	v_fma_f32 v3, v63, v3, 1.0
	v_mul_f32_e32 v2, v3, v2
	v_lshlrev_b64 v[0:1], 1, v[0:1]
	v_cvt_pk_bf16_f32 v5, v2, v97
	v_lshl_add_u64 v[2:3], s[96:97], 0, v[0:1]
	global_store_short v[2:3], v5, off
	v_add_f32_e32 v2, -1.0, v7
	v_fma_f32 v2, v62, v2, 1.0
	v_mul_f32_e32 v2, v2, v4
	v_cvt_pk_bf16_f32 v18, v2, v97
	v_or_b32_e32 v2, 64, v0
	v_mov_b32_e32 v3, v1
	v_lshl_add_u64 v[4:5], s[96:97], 0, v[2:3]
	global_store_short v[4:5], v18, off
	v_lshl_add_u64 v[4:5], s[30:31], 0, v[0:1]
	v_cvt_pk_bf16_f32 v18, v16, v97
	global_store_short v[4:5], v18, off
	v_lshl_add_u64 v[4:5], s[30:31], 0, v[2:3]
	v_cvt_pk_bf16_f32 v18, v17, v97
	global_store_short v[4:5], v18, off
	v_mul_f32_e32 v4, v6, v16
	v_lshl_add_u64 v[0:1], s[34:35], 0, v[0:1]
	v_cvt_pk_bf16_f32 v4, v4, v97
	global_store_short v[0:1], v4, off
	v_mul_f32_e32 v0, v7, v17
	v_cvt_pk_bf16_f32 v4, v0, v97
	v_lshl_add_u64 v[0:1], s[34:35], 0, v[2:3]
	global_store_short v[0:1], v4, off
	ds_read_u16 v0, v187 offset:41088
	ds_read_u16 v1, v187 offset:41152
	ds_read_u16 v6, v189 offset:41088
	ds_read_u16 v7, v189 offset:41152
	ds_read_u16 v16, v191 offset:41088
	ds_read_u16 v17, v191 offset:41152
	ds_read_u16 v18, v193 offset:41088
	ds_read_u16 v19, v193 offset:41152
	s_waitcnt lgkmcnt(6)
	v_lshlrev_b32_e32 v4, 16, v1
	v_lshlrev_b32_e32 v2, 16, v0
	v_mul_f32_e32 v3, v123, v4
	v_mul_f32_e32 v1, v121, v2
	v_mul_f32_e32 v5, v3, v3
	v_fmac_f32_e32 v5, v1, v1
	v_add_f32_e32 v0, v125, v24
	v_mul_f32_e32 v0, 0xbfb8aa3b, v0
	v_add_f32_dpp v5, v5, v5 quad_perm:[1,0,3,2] row_mask:0xf bank_mask:0xf bound_ctrl:1
	v_exp_f32_e32 v0, v0
	v_mov_b32_e32 v38, v48
	v_add_f32_dpp v5, v5, v5 quad_perm:[2,3,0,1] row_mask:0xf bank_mask:0xf bound_ctrl:1
	v_mov_b32_e32 v39, v48
	v_add_f32_e32 v0, 1.0, v0
	v_add_f32_dpp v5, v5, v5 row_half_mirror row_mask:0xf bank_mask:0xf bound_ctrl:1
	v_mov_b32_e32 v24, v48
	s_nop 0
	v_add_f32_dpp v5, v5, v5 row_mirror row_mask:0xf bank_mask:0xf bound_ctrl:1
	ds_bpermute_b32 v20, v137, v5
	s_waitcnt lgkmcnt(0)
	v_add_f32_e32 v5, v5, v20
	v_max_f32_e32 v5, 0x179abe15, v5
	v_rsq_f32_e32 v5, v5
	v_rcp_f32_e32 v20, v0
	v_add_f32_e32 v0, 1.0, v8
	v_rcp_f32_e32 v8, v0
	v_mul_f32_e32 v22, v3, v5
	v_add_f32_e32 v3, -1.0, v20
	v_mul_f32_e32 v21, v1, v5
	v_lshl_add_u64 v[0:1], v[54:55], 0, v[70:71]
	v_fma_f32 v3, v63, v3, 1.0
	v_mul_f32_e32 v2, v3, v2
	v_lshlrev_b64 v[0:1], 1, v[0:1]
	v_cvt_pk_bf16_f32 v5, v2, v97
	v_lshl_add_u64 v[2:3], s[96:97], 0, v[0:1]
	global_store_short v[2:3], v5, off
	v_add_f32_e32 v2, -1.0, v8
	v_fma_f32 v2, v62, v2, 1.0
	v_mul_f32_e32 v2, v2, v4
	v_cvt_pk_bf16_f32 v23, v2, v97
	v_or_b32_e32 v2, 64, v0
	v_mov_b32_e32 v3, v1
	v_lshl_add_u64 v[4:5], s[96:97], 0, v[2:3]
	global_store_short v[4:5], v23, off
	v_lshl_add_u64 v[4:5], s[30:31], 0, v[0:1]
	v_cvt_pk_bf16_f32 v23, v21, v97
	global_store_short v[4:5], v23, off
	v_lshl_add_u64 v[4:5], s[30:31], 0, v[2:3]
	v_cvt_pk_bf16_f32 v23, v22, v97
	global_store_short v[4:5], v23, off
	v_mul_f32_e32 v4, v20, v21
	v_lshl_add_u64 v[0:1], s[34:35], 0, v[0:1]
	v_cvt_pk_bf16_f32 v4, v4, v97
	global_store_short v[0:1], v4, off
	v_mul_f32_e32 v0, v8, v22
	v_cvt_pk_bf16_f32 v4, v0, v97
	v_lshl_add_u64 v[0:1], s[34:35], 0, v[2:3]
	global_store_short v[0:1], v4, off
	v_lshlrev_b32_e32 v4, 16, v7
	v_lshlrev_b32_e32 v2, 16, v6
	v_mul_f32_e32 v3, v123, v4
	v_mul_f32_e32 v1, v121, v2
	v_mul_f32_e32 v5, v3, v3
	v_fmac_f32_e32 v5, v1, v1
	v_add_f32_e32 v0, v125, v25
	v_mul_f32_e32 v0, 0xbfb8aa3b, v0
	v_add_f32_dpp v5, v5, v5 quad_perm:[1,0,3,2] row_mask:0xf bank_mask:0xf bound_ctrl:1
	v_exp_f32_e32 v0, v0
	v_add_f32_e32 v7, v119, v9
	v_add_f32_dpp v5, v5, v5 quad_perm:[2,3,0,1] row_mask:0xf bank_mask:0xf bound_ctrl:1
	v_mul_f32_e32 v7, 0xbfb8aa3b, v7
	v_add_f32_e32 v0, 1.0, v0
	v_add_f32_dpp v5, v5, v5 row_half_mirror row_mask:0xf bank_mask:0xf bound_ctrl:1
	v_exp_f32_e32 v7, v7
	v_mov_b32_e32 v54, v48
	v_add_f32_dpp v5, v5, v5 row_mirror row_mask:0xf bank_mask:0xf bound_ctrl:1
	ds_bpermute_b32 v6, v137, v5
	v_mov_b32_e32 v55, v48
	v_mov_b32_e32 v21, v48
	v_mov_b32_e32 v22, v48
	v_mov_b32_e32 v23, v48
	s_waitcnt lgkmcnt(0)
; __device__ __forceinline__ float bf1(bf16 h) { return __uint_as_float((unsigned)h << 16); }
; __device__ __forceinline__ bf16 f2bf(float f) { return (bf16)(pg8::cvt_pk_bf16(f, 0.f) & 0xffffu); }
; __device__ __forceinline__ float half32_sum(float v) { v = row16_sum(v); v += __shfl_xor(v, 16); return v; }
; __device__ __forceinline__ float sigmoid1(float x) { return __builtin_amdgcn_rcpf(1.0f + __expf(-x)); }
; __global__ void __launch_bounds__(NT, 2) mk_fwd(Args args) {
;     ...
;                     for (int hh = 0; hh < 2; ++hh) {
;                         const int colA = c0 + hh * 64 + (lane & 31), colB = colA + 32;
;                         const float a0A = a0p[colA], a0B = a0p[colB], kkA = kkw[colA], kkB = kkw[colB], kaA = kaw[colA], kaB = kaw[colB];
; #pragma unroll
;                         for (int r = 0; r < 16; ++r) { const int tl = (r & 3) + 8 * (r >> 2) + 4 * (lane >> 5); const int t = t0 + mt * 32 + tl;
;                             const float kA = bf1(Ks[tl * 1032 + colA]), kB = bf1(Ks[tl * 1032 + colB]);
;                             const float aA = sigmoid1(a0A + acc[hh * 2][r]), aB = sigmoid1(a0B + acc[hh * 2 + 1][r]);
;                             const float qA = kA * kkA, qB = kB * kkB;
;                             const float ss = half32_sum(qA * qA + qB * qB);
;                             const float inv = __builtin_amdgcn_rsqf(fmaxf(ss, 1e-24f));
;                             const float nA = qA * inv, nB = qB * inv;
;                             const size_t oA = (size_t)t * 1024 + colA, oB = oA + 32;
;                             KP[oA] = f2bf(kA * (1.0f + (aA - 1.0f) * kaA)); KP[oB] = f2bf(kB * (1.0f + (aB - 1.0f) * kaB));
;                             KKn[oA] = f2bf(nA); KKn[oB] = f2bf(nB); BB[oA] = f2bf(nA * aA); BB[oB] = f2bf(nB * aB);
;                             if ((r & 3) == 3) asm volatile("" ::: "memory"); }
;                     }
	v_add_f32_e32 v5, v5, v6
	v_max_f32_e32 v5, 0x179abe15, v5
	v_rsq_f32_e32 v5, v5
	v_rcp_f32_e32 v6, v0
	v_add_f32_e32 v0, 1.0, v7
	v_rcp_f32_e32 v7, v0
	v_mul_f32_e32 v9, v3, v5
	v_add_f32_e32 v3, -1.0, v6
	v_mul_f32_e32 v8, v1, v5
	v_lshl_add_u64 v[0:1], v[40:41], 0, v[70:71]
	v_fma_f32 v3, v63, v3, 1.0
	v_mul_f32_e32 v2, v3, v2
	v_lshlrev_b64 v[0:1], 1, v[0:1]
	v_cvt_pk_bf16_f32 v5, v2, v97
	v_lshl_add_u64 v[2:3], s[96:97], 0, v[0:1]
	global_store_short v[2:3], v5, off
	v_add_f32_e32 v2, -1.0, v7
	v_fma_f32 v2, v62, v2, 1.0
	v_mul_f32_e32 v2, v2, v4
	v_cvt_pk_bf16_f32 v20, v2, v97
	v_or_b32_e32 v2, 64, v0
	v_mov_b32_e32 v3, v1
	v_lshl_add_u64 v[4:5], s[96:97], 0, v[2:3]
	global_store_short v[4:5], v20, off
	v_lshl_add_u64 v[4:5], s[30:31], 0, v[0:1]
	v_cvt_pk_bf16_f32 v20, v8, v97
	global_store_short v[4:5], v20, off
	v_lshl_add_u64 v[4:5], s[30:31], 0, v[2:3]
	v_cvt_pk_bf16_f32 v20, v9, v97
	global_store_short v[4:5], v20, off
	v_mul_f32_e32 v4, v6, v8
	v_lshl_add_u64 v[0:1], s[34:35], 0, v[0:1]
	v_cvt_pk_bf16_f32 v4, v4, v97
	global_store_short v[0:1], v4, off
	v_mul_f32_e32 v0, v7, v9
	v_cvt_pk_bf16_f32 v4, v0, v97
	v_lshl_add_u64 v[0:1], s[34:35], 0, v[2:3]
	global_store_short v[0:1], v4, off
	v_lshlrev_b32_e32 v4, 16, v17
	v_lshlrev_b32_e32 v2, 16, v16
	v_mul_f32_e32 v3, v123, v4
	v_mul_f32_e32 v1, v121, v2
	v_mul_f32_e32 v5, v3, v3
	v_fmac_f32_e32 v5, v1, v1
	v_add_f32_e32 v0, v125, v26
	v_mul_f32_e32 v0, 0xbfb8aa3b, v0
	v_add_f32_dpp v5, v5, v5 quad_perm:[1,0,3,2] row_mask:0xf bank_mask:0xf bound_ctrl:1
	v_exp_f32_e32 v0, v0
	v_add_f32_e32 v7, v119, v10
	v_add_f32_dpp v5, v5, v5 quad_perm:[2,3,0,1] row_mask:0xf bank_mask:0xf bound_ctrl:1
	v_mul_f32_e32 v7, 0xbfb8aa3b, v7
	v_add_f32_e32 v0, 1.0, v0
	v_add_f32_dpp v5, v5, v5 row_half_mirror row_mask:0xf bank_mask:0xf bound_ctrl:1
	v_exp_f32_e32 v7, v7
	v_mov_b32_e32 v40, v48
	v_add_f32_dpp v5, v5, v5 row_mirror row_mask:0xf bank_mask:0xf bound_ctrl:1
	ds_bpermute_b32 v6, v137, v5
	v_mov_b32_e32 v41, v48
	v_mov_b32_e32 v20, v48
	v_mov_b32_e32 v25, v48
	v_mov_b32_e32 v26, v48
	s_waitcnt lgkmcnt(0)
	v_add_f32_e32 v5, v5, v6
	v_max_f32_e32 v5, 0x179abe15, v5
	v_rsq_f32_e32 v5, v5
	v_rcp_f32_e32 v6, v0
	v_add_f32_e32 v0, 1.0, v7
	v_rcp_f32_e32 v7, v0
	v_mul_f32_e32 v9, v3, v5
	v_add_f32_e32 v3, -1.0, v6
	v_mul_f32_e32 v8, v1, v5
	v_lshl_add_u64 v[0:1], v[56:57], 0, v[70:71]
	v_fma_f32 v3, v63, v3, 1.0
	v_mul_f32_e32 v2, v3, v2
	v_lshlrev_b64 v[0:1], 1, v[0:1]
	v_cvt_pk_bf16_f32 v5, v2, v97
	v_lshl_add_u64 v[2:3], s[96:97], 0, v[0:1]
	global_store_short v[2:3], v5, off
	v_add_f32_e32 v2, -1.0, v7
	v_fma_f32 v2, v62, v2, 1.0
	v_mul_f32_e32 v2, v2, v4
	v_cvt_pk_bf16_f32 v10, v2, v97
	v_or_b32_e32 v2, 64, v0
	v_mov_b32_e32 v3, v1
	v_lshl_add_u64 v[4:5], s[96:97], 0, v[2:3]
	global_store_short v[4:5], v10, off
	v_lshl_add_u64 v[4:5], s[30:31], 0, v[0:1]
	v_cvt_pk_bf16_f32 v10, v8, v97
	global_store_short v[4:5], v10, off
	v_lshl_add_u64 v[4:5], s[30:31], 0, v[2:3]
	v_cvt_pk_bf16_f32 v10, v9, v97
	global_store_short v[4:5], v10, off
	v_mul_f32_e32 v4, v6, v8
	v_lshl_add_u64 v[0:1], s[34:35], 0, v[0:1]
	v_cvt_pk_bf16_f32 v4, v4, v97
	global_store_short v[0:1], v4, off
	v_mul_f32_e32 v0, v7, v9
	v_cvt_pk_bf16_f32 v4, v0, v97
	v_lshl_add_u64 v[0:1], s[34:35], 0, v[2:3]
	global_store_short v[0:1], v4, off
	v_lshlrev_b32_e32 v4, 16, v19
	v_lshlrev_b32_e32 v2, 16, v18
	v_mul_f32_e32 v3, v123, v4
	v_mul_f32_e32 v1, v121, v2
	v_mul_f32_e32 v5, v3, v3
	v_fmac_f32_e32 v5, v1, v1
	v_add_f32_e32 v0, v125, v27
	v_mul_f32_e32 v0, 0xbfb8aa3b, v0
	v_add_f32_dpp v5, v5, v5 quad_perm:[1,0,3,2] row_mask:0xf bank_mask:0xf bound_ctrl:1
	v_exp_f32_e32 v0, v0
	v_add_f32_e32 v7, v119, v11
	v_add_f32_dpp v5, v5, v5 quad_perm:[2,3,0,1] row_mask:0xf bank_mask:0xf bound_ctrl:1
	v_mul_f32_e32 v7, 0xbfb8aa3b, v7
	v_add_f32_e32 v0, 1.0, v0
	v_add_f32_dpp v5, v5, v5 row_half_mirror row_mask:0xf bank_mask:0xf bound_ctrl:1
	v_exp_f32_e32 v7, v7
	v_mov_b32_e32 v56, v48
	v_add_f32_dpp v5, v5, v5 row_mirror row_mask:0xf bank_mask:0xf bound_ctrl:1
	ds_bpermute_b32 v6, v137, v5
	v_mov_b32_e32 v57, v48
	v_mov_b32_e32 v27, v48
	s_waitcnt lgkmcnt(0)
	v_add_f32_e32 v5, v5, v6
	v_max_f32_e32 v5, 0x179abe15, v5
	v_rsq_f32_e32 v5, v5
	v_rcp_f32_e32 v6, v0
	v_add_f32_e32 v0, 1.0, v7
	v_rcp_f32_e32 v7, v0
	v_mul_f32_e32 v9, v3, v5
	v_add_f32_e32 v3, -1.0, v6
	v_mul_f32_e32 v8, v1, v5
	v_lshl_add_u64 v[0:1], v[42:43], 0, v[70:71]
	v_fma_f32 v3, v63, v3, 1.0
	v_mul_f32_e32 v2, v3, v2
	v_lshlrev_b64 v[0:1], 1, v[0:1]
	v_cvt_pk_bf16_f32 v5, v2, v97
	v_lshl_add_u64 v[2:3], s[96:97], 0, v[0:1]
	global_store_short v[2:3], v5, off
	v_add_f32_e32 v2, -1.0, v7
	v_fma_f32 v2, v62, v2, 1.0
	v_mul_f32_e32 v2, v2, v4
	v_cvt_pk_bf16_f32 v10, v2, v97
	v_or_b32_e32 v2, 64, v0
	v_mov_b32_e32 v3, v1
	v_lshl_add_u64 v[4:5], s[96:97], 0, v[2:3]
	global_store_short v[4:5], v10, off
	v_lshl_add_u64 v[4:5], s[30:31], 0, v[0:1]
	v_cvt_pk_bf16_f32 v10, v8, v97
	global_store_short v[4:5], v10, off
	v_lshl_add_u64 v[4:5], s[30:31], 0, v[2:3]
	v_cvt_pk_bf16_f32 v10, v9, v97
	global_store_short v[4:5], v10, off
	v_mul_f32_e32 v4, v6, v8
	v_lshl_add_u64 v[0:1], s[34:35], 0, v[0:1]
	v_cvt_pk_bf16_f32 v4, v4, v97
	global_store_short v[0:1], v4, off
	v_mul_f32_e32 v0, v7, v9
	v_cvt_pk_bf16_f32 v4, v0, v97
	v_lshl_add_u64 v[0:1], s[34:35], 0, v[2:3]
	global_store_short v[0:1], v4, off
	ds_read_u16 v0, v195 offset:41088
	ds_read_u16 v1, v195 offset:41152
	ds_read_u16 v6, v197 offset:41088
	ds_read_u16 v7, v197 offset:41152
	ds_read_u16 v8, v199 offset:41088
	ds_read_u16 v9, v199 offset:41152
	ds_read_u16 v10, v201 offset:41088
	ds_read_u16 v11, v201 offset:41152
	s_waitcnt lgkmcnt(6)
; __device__ __forceinline__ float bf1(bf16 h) { return __uint_as_float((unsigned)h << 16); }
; __device__ __forceinline__ bf16 f2bf(float f) { return (bf16)(pg8::cvt_pk_bf16(f, 0.f) & 0xffffu); }
; __device__ __forceinline__ float half32_sum(float v) { v = row16_sum(v); v += __shfl_xor(v, 16); return v; }
; __device__ __forceinline__ float sigmoid1(float x) { return __builtin_amdgcn_rcpf(1.0f + __expf(-x)); }
; __global__ void __launch_bounds__(NT, 2) mk_fwd(Args args) {
;     ...
;                     for (int hh = 0; hh < 2; ++hh) {
;                         const int colA = c0 + hh * 64 + (lane & 31), colB = colA + 32;
;                         const float a0A = a0p[colA], a0B = a0p[colB], kkA = kkw[colA], kkB = kkw[colB], kaA = kaw[colA], kaB = kaw[colB];
; #pragma unroll
;                         for (int r = 0; r < 16; ++r) { const int tl = (r & 3) + 8 * (r >> 2) + 4 * (lane >> 5); const int t = t0 + mt * 32 + tl;
;                             const float kA = bf1(Ks[tl * 1032 + colA]), kB = bf1(Ks[tl * 1032 + colB]);
;                             const float aA = sigmoid1(a0A + acc[hh * 2][r]), aB = sigmoid1(a0B + acc[hh * 2 + 1][r]);
;                             const float qA = kA * kkA, qB = kB * kkB;
;                             const float ss = half32_sum(qA * qA + qB * qB);
;                             const float inv = __builtin_amdgcn_rsqf(fmaxf(ss, 1e-24f));
;                             const float nA = qA * inv, nB = qB * inv;
;                             const size_t oA = (size_t)t * 1024 + colA, oB = oA + 32;
;                             KP[oA] = f2bf(kA * (1.0f + (aA - 1.0f) * kaA)); KP[oB] = f2bf(kB * (1.0f + (aB - 1.0f) * kaB));
;                             KKn[oA] = f2bf(nA); KKn[oB] = f2bf(nB); BB[oA] = f2bf(nA * aA); BB[oB] = f2bf(nB * aB);
;                             if ((r & 3) == 3) asm volatile("" ::: "memory"); }
;                     }
	v_lshlrev_b32_e32 v4, 16, v1
	v_lshlrev_b32_e32 v2, 16, v0
	v_mul_f32_e32 v3, v123, v4
	v_mul_f32_e32 v1, v121, v2
	v_mul_f32_e32 v5, v3, v3
	v_fmac_f32_e32 v5, v1, v1
	v_add_f32_e32 v0, v125, v28
	v_mul_f32_e32 v0, 0xbfb8aa3b, v0
	v_add_f32_dpp v5, v5, v5 quad_perm:[1,0,3,2] row_mask:0xf bank_mask:0xf bound_ctrl:1
	v_exp_f32_e32 v0, v0
	v_mov_b32_e32 v42, v48
	v_add_f32_dpp v5, v5, v5 quad_perm:[2,3,0,1] row_mask:0xf bank_mask:0xf bound_ctrl:1
	v_mov_b32_e32 v43, v48
	v_add_f32_e32 v0, 1.0, v0
	v_add_f32_dpp v5, v5, v5 row_half_mirror row_mask:0xf bank_mask:0xf bound_ctrl:1
	v_mov_b32_e32 v28, v48
	s_nop 0
	v_add_f32_dpp v5, v5, v5 row_mirror row_mask:0xf bank_mask:0xf bound_ctrl:1
	ds_bpermute_b32 v16, v137, v5
	s_waitcnt lgkmcnt(0)
	v_add_f32_e32 v5, v5, v16
	v_max_f32_e32 v5, 0x179abe15, v5
	v_rsq_f32_e32 v5, v5
	v_rcp_f32_e32 v16, v0
	v_add_f32_e32 v0, 1.0, v12
	v_rcp_f32_e32 v12, v0
	v_mul_f32_e32 v18, v3, v5
	v_add_f32_e32 v3, -1.0, v16
	v_mul_f32_e32 v17, v1, v5
	v_lshl_add_u64 v[0:1], v[58:59], 0, v[70:71]
	v_fma_f32 v3, v63, v3, 1.0
	v_mul_f32_e32 v2, v3, v2
	v_lshlrev_b64 v[0:1], 1, v[0:1]
	v_cvt_pk_bf16_f32 v5, v2, v97
	v_lshl_add_u64 v[2:3], s[96:97], 0, v[0:1]
	global_store_short v[2:3], v5, off
	v_add_f32_e32 v2, -1.0, v12
	v_fma_f32 v2, v62, v2, 1.0
	v_mul_f32_e32 v2, v2, v4
	v_cvt_pk_bf16_f32 v19, v2, v97
	v_or_b32_e32 v2, 64, v0
	v_mov_b32_e32 v3, v1
	v_lshl_add_u64 v[4:5], s[96:97], 0, v[2:3]
	global_store_short v[4:5], v19, off
	v_lshl_add_u64 v[4:5], s[30:31], 0, v[0:1]
	v_cvt_pk_bf16_f32 v19, v17, v97
	global_store_short v[4:5], v19, off
	v_lshl_add_u64 v[4:5], s[30:31], 0, v[2:3]
	v_cvt_pk_bf16_f32 v19, v18, v97
	global_store_short v[4:5], v19, off
	v_mul_f32_e32 v4, v16, v17
	v_lshl_add_u64 v[0:1], s[34:35], 0, v[0:1]
	v_cvt_pk_bf16_f32 v4, v4, v97
	global_store_short v[0:1], v4, off
	v_mul_f32_e32 v0, v12, v18
	v_cvt_pk_bf16_f32 v4, v0, v97
	v_lshl_add_u64 v[0:1], s[34:35], 0, v[2:3]
	global_store_short v[0:1], v4, off
	v_lshlrev_b32_e32 v4, 16, v7
	v_lshlrev_b32_e32 v2, 16, v6
	v_mul_f32_e32 v3, v123, v4
	v_mul_f32_e32 v1, v121, v2
	v_mul_f32_e32 v5, v3, v3
	v_fmac_f32_e32 v5, v1, v1
	v_add_f32_e32 v0, v125, v29
	v_mul_f32_e32 v0, 0xbfb8aa3b, v0
	v_add_f32_dpp v5, v5, v5 quad_perm:[1,0,3,2] row_mask:0xf bank_mask:0xf bound_ctrl:1
	v_exp_f32_e32 v0, v0
	v_add_f32_e32 v7, v119, v13
	v_add_f32_dpp v5, v5, v5 quad_perm:[2,3,0,1] row_mask:0xf bank_mask:0xf bound_ctrl:1
	v_mul_f32_e32 v7, 0xbfb8aa3b, v7
	v_add_f32_e32 v0, 1.0, v0
	v_add_f32_dpp v5, v5, v5 row_half_mirror row_mask:0xf bank_mask:0xf bound_ctrl:1
	v_exp_f32_e32 v7, v7
	v_mov_b32_e32 v58, v48
	v_add_f32_dpp v5, v5, v5 row_mirror row_mask:0xf bank_mask:0xf bound_ctrl:1
	ds_bpermute_b32 v6, v137, v5
	v_mov_b32_e32 v59, v48
	v_mov_b32_e32 v17, v48
	v_mov_b32_e32 v18, v48
	v_mov_b32_e32 v19, v48
	s_waitcnt lgkmcnt(0)
	v_add_f32_e32 v5, v5, v6
	v_max_f32_e32 v5, 0x179abe15, v5
	v_rsq_f32_e32 v5, v5
	v_rcp_f32_e32 v6, v0
	v_add_f32_e32 v0, 1.0, v7
	v_rcp_f32_e32 v7, v0
	v_mul_f32_e32 v13, v3, v5
	v_add_f32_e32 v3, -1.0, v6
	v_mul_f32_e32 v12, v1, v5
	v_lshl_add_u64 v[0:1], v[44:45], 0, v[70:71]
	v_fma_f32 v3, v63, v3, 1.0
	v_mul_f32_e32 v2, v3, v2
	v_lshlrev_b64 v[0:1], 1, v[0:1]
	v_cvt_pk_bf16_f32 v5, v2, v97
	v_lshl_add_u64 v[2:3], s[96:97], 0, v[0:1]
	global_store_short v[2:3], v5, off
	v_add_f32_e32 v2, -1.0, v7
	v_fma_f32 v2, v62, v2, 1.0
	v_mul_f32_e32 v2, v2, v4
	v_cvt_pk_bf16_f32 v16, v2, v97
	v_or_b32_e32 v2, 64, v0
	v_mov_b32_e32 v3, v1
	v_lshl_add_u64 v[4:5], s[96:97], 0, v[2:3]
	global_store_short v[4:5], v16, off
	v_lshl_add_u64 v[4:5], s[30:31], 0, v[0:1]
	v_cvt_pk_bf16_f32 v16, v12, v97
	global_store_short v[4:5], v16, off
	v_lshl_add_u64 v[4:5], s[30:31], 0, v[2:3]
	v_cvt_pk_bf16_f32 v16, v13, v97
	global_store_short v[4:5], v16, off
	v_mul_f32_e32 v4, v6, v12
	v_lshl_add_u64 v[0:1], s[34:35], 0, v[0:1]
	v_cvt_pk_bf16_f32 v4, v4, v97
	global_store_short v[0:1], v4, off
	v_mul_f32_e32 v0, v7, v13
	v_cvt_pk_bf16_f32 v4, v0, v97
	v_lshl_add_u64 v[0:1], s[34:35], 0, v[2:3]
	global_store_short v[0:1], v4, off
	v_lshlrev_b32_e32 v4, 16, v9
	v_lshlrev_b32_e32 v2, 16, v8
	v_mul_f32_e32 v3, v123, v4
	v_mul_f32_e32 v1, v121, v2
	v_mul_f32_e32 v5, v3, v3
	v_fmac_f32_e32 v5, v1, v1
	v_add_f32_e32 v0, v125, v30
	v_mul_f32_e32 v0, 0xbfb8aa3b, v0
	v_add_f32_dpp v5, v5, v5 quad_perm:[1,0,3,2] row_mask:0xf bank_mask:0xf bound_ctrl:1
	v_exp_f32_e32 v0, v0
	v_add_f32_e32 v7, v119, v14
	v_add_f32_dpp v5, v5, v5 quad_perm:[2,3,0,1] row_mask:0xf bank_mask:0xf bound_ctrl:1
	v_mul_f32_e32 v7, 0xbfb8aa3b, v7
	v_add_f32_e32 v0, 1.0, v0
	v_add_f32_dpp v5, v5, v5 row_half_mirror row_mask:0xf bank_mask:0xf bound_ctrl:1
	v_exp_f32_e32 v7, v7
	v_mov_b32_e32 v44, v48
	v_add_f32_dpp v5, v5, v5 row_mirror row_mask:0xf bank_mask:0xf bound_ctrl:1
	ds_bpermute_b32 v6, v137, v5
	v_mov_b32_e32 v45, v48
	v_mov_b32_e32 v16, v48
	v_mov_b32_e32 v29, v48
	v_mov_b32_e32 v30, v48
	s_waitcnt lgkmcnt(0)
; __device__ __forceinline__ float bf1(bf16 h) { return __uint_as_float((unsigned)h << 16); }
; __device__ __forceinline__ bf16 f2bf(float f) { return (bf16)(pg8::cvt_pk_bf16(f, 0.f) & 0xffffu); }
; __device__ __forceinline__ float half32_sum(float v) { v = row16_sum(v); v += __shfl_xor(v, 16); return v; }
; __device__ __forceinline__ float sigmoid1(float x) { return __builtin_amdgcn_rcpf(1.0f + __expf(-x)); }
; __global__ void __launch_bounds__(NT, 2) mk_fwd(Args args) {
;     ...
;                     for (int hh = 0; hh < 2; ++hh) {
;                         const int colA = c0 + hh * 64 + (lane & 31), colB = colA + 32;
;                         const float a0A = a0p[colA], a0B = a0p[colB], kkA = kkw[colA], kkB = kkw[colB], kaA = kaw[colA], kaB = kaw[colB];
; #pragma unroll
;                         for (int r = 0; r < 16; ++r) { const int tl = (r & 3) + 8 * (r >> 2) + 4 * (lane >> 5); const int t = t0 + mt * 32 + tl;
;                             const float kA = bf1(Ks[tl * 1032 + colA]), kB = bf1(Ks[tl * 1032 + colB]);
;                             const float aA = sigmoid1(a0A + acc[hh * 2][r]), aB = sigmoid1(a0B + acc[hh * 2 + 1][r]);
;                             const float qA = kA * kkA, qB = kB * kkB;
;                             const float ss = half32_sum(qA * qA + qB * qB);
;                             const float inv = __builtin_amdgcn_rsqf(fmaxf(ss, 1e-24f));
;                             const float nA = qA * inv, nB = qB * inv;
;                             const size_t oA = (size_t)t * 1024 + colA, oB = oA + 32;
;                             KP[oA] = f2bf(kA * (1.0f + (aA - 1.0f) * kaA)); KP[oB] = f2bf(kB * (1.0f + (aB - 1.0f) * kaB));
;                             KKn[oA] = f2bf(nA); KKn[oB] = f2bf(nB); BB[oA] = f2bf(nA * aA); BB[oB] = f2bf(nB * aB);
;                             if ((r & 3) == 3) asm volatile("" ::: "memory"); }
;                     }
	v_add_f32_e32 v5, v5, v6
	v_max_f32_e32 v5, 0x179abe15, v5
	v_rsq_f32_e32 v5, v5
	v_rcp_f32_e32 v6, v0
	v_add_f32_e32 v0, 1.0, v7
	v_rcp_f32_e32 v7, v0
	v_mul_f32_e32 v9, v3, v5
	v_add_f32_e32 v3, -1.0, v6
	v_mul_f32_e32 v8, v1, v5
	v_lshl_add_u64 v[0:1], v[60:61], 0, v[70:71]
	v_fma_f32 v3, v63, v3, 1.0
	v_mul_f32_e32 v2, v3, v2
	v_lshlrev_b64 v[0:1], 1, v[0:1]
	v_cvt_pk_bf16_f32 v5, v2, v97
	v_lshl_add_u64 v[2:3], s[96:97], 0, v[0:1]
	global_store_short v[2:3], v5, off
	v_add_f32_e32 v2, -1.0, v7
	v_fma_f32 v2, v62, v2, 1.0
	v_mul_f32_e32 v2, v2, v4
	v_cvt_pk_bf16_f32 v12, v2, v97
	v_or_b32_e32 v2, 64, v0
	v_mov_b32_e32 v3, v1
	v_lshl_add_u64 v[4:5], s[96:97], 0, v[2:3]
	global_store_short v[4:5], v12, off
	v_lshl_add_u64 v[4:5], s[30:31], 0, v[0:1]
	v_cvt_pk_bf16_f32 v12, v8, v97
	global_store_short v[4:5], v12, off
	v_lshl_add_u64 v[4:5], s[30:31], 0, v[2:3]
	v_cvt_pk_bf16_f32 v12, v9, v97
	global_store_short v[4:5], v12, off
	v_mul_f32_e32 v4, v6, v8
	v_lshl_add_u64 v[0:1], s[34:35], 0, v[0:1]
	v_cvt_pk_bf16_f32 v4, v4, v97
	global_store_short v[0:1], v4, off
	v_mul_f32_e32 v0, v7, v9
	v_cvt_pk_bf16_f32 v4, v0, v97
	v_lshl_add_u64 v[0:1], s[34:35], 0, v[2:3]
	global_store_short v[0:1], v4, off
	v_lshlrev_b32_e32 v4, 16, v11
	v_lshlrev_b32_e32 v2, 16, v10
	v_mul_f32_e32 v3, v123, v4
	v_mul_f32_e32 v1, v121, v2
	v_mul_f32_e32 v5, v3, v3
	v_fmac_f32_e32 v5, v1, v1
	v_add_f32_e32 v0, v125, v31
	v_mul_f32_e32 v0, 0xbfb8aa3b, v0
	v_add_f32_dpp v5, v5, v5 quad_perm:[1,0,3,2] row_mask:0xf bank_mask:0xf bound_ctrl:1
	v_exp_f32_e32 v0, v0
	v_add_f32_e32 v7, v119, v15
	v_add_f32_dpp v5, v5, v5 quad_perm:[2,3,0,1] row_mask:0xf bank_mask:0xf bound_ctrl:1
	v_mul_f32_e32 v7, 0xbfb8aa3b, v7
	v_add_f32_e32 v0, 1.0, v0
	v_add_f32_dpp v5, v5, v5 row_half_mirror row_mask:0xf bank_mask:0xf bound_ctrl:1
	v_exp_f32_e32 v7, v7
	v_add_u32_e32 v119, v207, v210
	v_add_f32_dpp v5, v5, v5 row_mirror row_mask:0xf bank_mask:0xf bound_ctrl:1
	ds_bpermute_b32 v6, v137, v5
	v_mov_b32_e32 v60, v48
	v_mov_b32_e32 v61, v48
	v_mov_b32_e32 v31, v48
	v_mov_b32_e32 v11, v48
	s_waitcnt lgkmcnt(0)
	v_add_f32_e32 v5, v5, v6
	v_max_f32_e32 v5, 0x179abe15, v5
	v_rsq_f32_e32 v5, v5
	v_rcp_f32_e32 v6, v0
	v_add_f32_e32 v0, 1.0, v7
	v_rcp_f32_e32 v7, v0
	v_mul_f32_e32 v9, v3, v5
	v_add_f32_e32 v3, -1.0, v6
	v_mul_f32_e32 v8, v1, v5
	v_lshl_add_u64 v[0:1], v[46:47], 0, v[70:71]
	v_fma_f32 v3, v63, v3, 1.0
	v_mul_f32_e32 v2, v3, v2
	v_lshlrev_b64 v[0:1], 1, v[0:1]
	v_cvt_pk_bf16_f32 v5, v2, v97
	v_lshl_add_u64 v[2:3], s[96:97], 0, v[0:1]
	global_store_short v[2:3], v5, off
	v_add_f32_e32 v2, -1.0, v7
	v_fma_f32 v2, v62, v2, 1.0
	v_mul_f32_e32 v2, v2, v4
	v_cvt_pk_bf16_f32 v10, v2, v97
	v_or_b32_e32 v2, 64, v0
	v_mov_b32_e32 v3, v1
	v_lshl_add_u64 v[4:5], s[96:97], 0, v[2:3]
	global_store_short v[4:5], v10, off
	v_lshl_add_u64 v[4:5], s[30:31], 0, v[0:1]
	v_cvt_pk_bf16_f32 v10, v8, v97
	global_store_short v[4:5], v10, off
	v_lshl_add_u64 v[4:5], s[30:31], 0, v[2:3]
	v_cvt_pk_bf16_f32 v10, v9, v97
	global_store_short v[4:5], v10, off
	v_mul_f32_e32 v4, v6, v8
	v_lshl_add_u64 v[0:1], s[34:35], 0, v[0:1]
	v_cvt_pk_bf16_f32 v4, v4, v97
	global_store_short v[0:1], v4, off
	v_mul_f32_e32 v0, v7, v9
	v_cvt_pk_bf16_f32 v4, v0, v97
	v_lshl_add_u64 v[0:1], s[34:35], 0, v[2:3]
	global_store_short v[0:1], v4, off
	v_mov_b32_e32 v62, v48
	v_mov_b32_e32 v63, v48
	v_mov_b32_e32 v46, v48
	v_mov_b32_e32 v47, v48
	v_mov_b32_e32 v0, v48
	v_mov_b32_e32 v1, v48
	v_mov_b32_e32 v2, v48
	v_mov_b32_e32 v3, v48
	v_mov_b32_e32 v4, v48
	v_mov_b32_e32 v5, v48
	v_mov_b32_e32 v6, v48
	v_mov_b32_e32 v7, v48
	v_mov_b32_e32 v8, v48
	v_mov_b32_e32 v9, v48
	v_mov_b32_e32 v10, v48
	v_mov_b32_e32 v12, v48
	v_mov_b32_e32 v13, v48
	v_mov_b32_e32 v14, v48
	v_mov_b32_e32 v15, v48

; #define SC_LOAD(tc) do { const size_t o_ = base + (size_t)(tc) * 1024 + q * 4; ld_dec = *(const f32x4*)(DEC + o_); ld_kk = *(const u32x2*)(KKn + o_); ld_bb = *(const u32x2*)(BB + o_); \
;             ld_kp = *(const u32x2*)(KP + o_); ld_rr = *(const u32x2*)(RR + o_); ld_vv = *(const unsigned*)(VV + base + (size_t)(tc) * 1024 + half * 32 + q * 2); } while (0)
; __global__ void __launch_bounds__(NT, 2) mk_fwd(Args args) {
;     ...
;         for (int task_ = bx; task_ < 256 * RMUL(4); task_ += G) {
;             const int tb_ = task_ & 255; const int task = ((tb_ >> 4) << 4) | ((tb_ & 7) << 1) | ((tb_ >> 3) & 1); const int bh = task >> 1, half = task & 1, b = bh >> 4, h = bh & 15;
;             const int stp = tid >> 4, q = tid & 15;
;             const size_t base = ((size_t)b * SEQ + stp) * 1024 + h * 64;
;             f32x4 ld_dec; u32x2 ld_kk, ld_bb, ld_kp, ld_rr; unsigned ld_vv;
;     ...
;             __syncthreads();
;             SC_LOAD(0); SC_STORE();
;             __syncthreads();
;             f32x4 S = (f32x4){0.f, 0.f, 0.f, 0.f};
;             const int row = wave * 4 + (lane >> 4), kl = lane & 15;
.Lp4_task:
	s_and_b32 s3, s48, 0xf0
	s_and_b32 s6, s48, 7
	s_lshl_b32 s6, s6, 1
	s_or_b32 s3, s3, s6
	s_bfe_u32 s6, s48, 0x10003
	s_or_b32 s3, s3, s6
	s_and_b32 s33, s3, 1
	s_lshr_b32 s6, s3, 1
	s_and_b32 s7, s6, 15
	s_lshr_b32 s6, s6, 4
	s_lshl_b32 s6, s6, 21
	s_lshl_b32 s7, s7, 6
	s_or_b32 s6, s6, s7
	s_lshl_b32 s7, s6, 1
	s_lshl_b32 s8, s6, 2
	s_add_u32 s38, s90, s8
	s_addc_u32 s39, s91, 0
	s_add_u32 s40, s30, s7
	s_addc_u32 s41, s31, 0
	s_add_u32 s42, s34, s7
	s_addc_u32 s43, s35, 0
	s_add_u32 s44, s96, s7
	s_addc_u32 s45, s97, 0
	s_add_u32 s46, s28, s7
	s_addc_u32 s47, s29, 0
	s_lshl_b32 s9, s33, 6
	s_add_u32 s9, s9, s7
	s_add_u32 s52, s24, s9
	s_addc_u32 s53, s25, 0
	s_lshl_b32 s9, s33, 7
	s_add_u32 s9, s9, s8
	s_add_u32 s54, s20, s9
	s_addc_u32 s55, s21, 0
	s_waitcnt vmcnt(0) lgkmcnt(0)
	s_barrier
	s_cmp_gt_u32 s85, 3
	s_cbranch_scc1 .Lp4_helper
	v_and_b32_e32 v54, 15, v128
	v_lshrrev_b32_e32 v55, 4, v128
	v_lshl_or_b32 v55, s85, 2, v55
	v_lshlrev_b32_e32 v80, 4, v54
	v_lshlrev_b32_e32 v81, 3, v55
	v_add_u32_e32 v81, 0x5000, v81
	v_mul_u32_u24_e32 v82, 0x90, v55
	v_lshl_add_u32 v82, v54, 3, v82
	v_add_u32_e32 v82, 0xb000, v82
	v_mov_b32_e32 v72, 0
	v_mov_b32_e32 v73, 0
	v_mov_b32_e32 v74, 0
	v_mov_b32_e32 v75, 0
	v_mov_b32_e32 v76, 0
	v_mov_b32_e32 v77, 0
	v_mov_b32_e32 v78, 0
	v_mov_b32_e32 v79, 0
	s_movk_i32 s10, 0x80
	s_barrier
	s_nop 0
